# attention: K/V ds_write of next tile moved from tile tail into PV MFMA groups; GEMM SP1 load segment mid-wait relaxed lgkmcnt(0)->(7)
# speedup vs baseline: 1.0150x; 1.0150x over previous
; #define PG8_STAGE(bufoff, gbase, voff) do { _Pragma("unroll") for (int _i = 0; _i < 2; ++_i) \
;         __builtin_amdgcn_global_load_lds((const unsigned*)((const char*)(gbase) + (voff)[_i]), (PG8_LAS unsigned*)(lds + (bufoff) + ldsw + _i * 8192), 16, 0, 0); } while (0)
; #define PG8_LDA(dst, b, h) do { _Pragma("unroll") for (int m = 0; m < 4; ++m) _Pragma("unroll") for (int k = 0; k < 2; ++k) dst[m][k] = *(const PG8_LAS bf16x8*)(lds + PG8_SA(b, h) + aoff + m * 2048 + k * 1024); } while (0)
; #define PG8_LDB(dst, b, h) do { _Pragma("unroll") for (int n = 0; n < 2; ++n) _Pragma("unroll") for (int k = 0; k < 2; ++k) dst[n][k] = *(const PG8_LAS bf16x8*)(lds + PG8_SB(b, h) + boff + n * 2048 + k * 1024); } while (0)
; #define PG8_MMA(ai, bj, At, Bt) do { __builtin_amdgcn_s_setprio(1); _Pragma("unroll") for (int m = 0; m < 4; ++m) _Pragma("unroll") for (int n = 0; n < 2; ++n) _Pragma("unroll") for (int k = 0; k < 2; ++k) \
;         acc[ai][bj][m][n] = __builtin_amdgcn_mfma_f32_16x16x32_bf16(Bt[n][k], At[m][k], acc[ai][bj][m][n], 0, 0, 0); __builtin_amdgcn_s_setprio(0); } while (0)
; #define PG8_BAR __builtin_amdgcn_s_barrier()
; template <class Epi, class Sched, bool ALIGN_EPI = false, bool SP2 = false>
; __device__ __forceinline__ void gemm_phase(PG8_LAS unsigned char* lds, const Gemm g, const Sched& S, const Epi& E) {
;     ...
;             PG8_LDB(B0, 0, 0); PG8_LDB(B1, 0, 1); PG8_SCHED; PG8_LDA(At, 0, 0); PG8_STAGE(PG8_SA(1, 1), a1 + hstep, voffA);
;             PG8_WAIT_V(8); PG8_WAIT_L(0); PG8_BAR; PG8_MMA(0, 0, At, B0); PG8_MMA(0, 1, At, B1); PG8_BAR; PG8_SCHED;
;             PG8_LDA(At, 0, 1); PG8_STAGE(PG8_SB(0, 0), b2, voffB); PG8_STAGE(PG8_SB(0, 1), b2 + hstep, voffB); PG8_STAGE(PG8_SA(0, 0), a2, voffA);
;             PG8_WAIT_V(8); PG8_WAIT_L(0); PG8_BAR; if (full) { PG8_MMA(1, 0, At, B0); PG8_MMA(1, 1, At, B1); } PG8_BAR; PG8_SCHED;
;             PG8_LDB(B0, 1, 0); PG8_LDB(B1, 1, 1); PG8_SCHED; PG8_LDA(At, 1, 0); PG8_STAGE(PG8_SA(0, 1), a2 + hstep, voffA);
;             PG8_WAIT_V(8); PG8_WAIT_L(0); PG8_BAR; PG8_MMA(0, 0, At, B0); PG8_MMA(0, 1, At, B1); PG8_BAR; PG8_SCHED;
;             PG8_LDA(At, 1, 1); PG8_STAGE(PG8_SB(1, 0), b3, voffB); PG8_STAGE(PG8_SB(1, 1), b3 + hstep, voffB); PG8_STAGE(PG8_SA(1, 0), a3, voffA);
;             PG8_WAIT_V(8); PG8_WAIT_L(0); PG8_BAR; if (full) { PG8_MMA(1, 0, At, B0); PG8_MMA(1, 1, At, B1); } PG8_BAR; PG8_SCHED;
.LBB0_166:
	s_add_u32 s2, s48, 0xfffc0080
	s_addc_u32 s3, s49, -1
	s_add_i32 s4, 0, 0x10000
	s_cmp_eq_u32 s12, 12
	s_cselect_b32 s35, s81, s3
	s_cselect_b32 s34, s94, s2
	v_add_u32_e32 v128, s4, v228
	s_cselect_b32 s29, s79, s51
	s_cselect_b32 s28, s95, s50
	s_add_i32 s5, 0, 0x14000
	ds_read_b128 v[146:149], v128
	ds_read_b128 v[150:153], v128 offset:1024
	ds_read_b128 v[154:157], v128 offset:2048
	ds_read_b128 v[158:161], v128 offset:3072
	v_add_u32_e32 v128, s5, v228
	ds_read_b128 v[130:133], v128
	ds_read_b128 v[134:137], v128 offset:1024
	ds_read_b128 v[138:141], v128 offset:2048
	ds_read_b128 v[142:145], v128 offset:3072
	v_lshl_add_u64 v[196:197], s[48:49], 0, v[216:217]
	s_add_i32 m0, s70, 0xc000
	s_waitcnt lgkmcnt(7)
	ds_read_b128 v[162:165], v248
	ds_read_b128 v[166:169], v248 offset:1024
	ds_read_b128 v[170:173], v248 offset:2048
	ds_read_b128 v[174:177], v248 offset:3072
	ds_read_b128 v[178:181], v248 offset:4096
	ds_read_b128 v[182:185], v248 offset:5120
	ds_read_b128 v[186:189], v248 offset:6144
	ds_read_b128 v[190:193], v248 offset:7168
	global_load_lds_dwordx4 v[196:197], off
	v_lshl_add_u64 v[196:197], s[48:49], 0, v[218:219]
	s_add_i32 m0, s70, 0xe000
	s_nop 0
	global_load_lds_dwordx4 v[196:197], off
	s_waitcnt vmcnt(8)
	s_waitcnt lgkmcnt(0)
	s_barrier
	s_setprio 1
	s_waitcnt lgkmcnt(0)
	v_mfma_f32_16x16x32_bf16 v[124:127], v[146:149], v[162:165], v[124:127]
	v_mfma_f32_16x16x32_bf16 v[120:123], v[154:157], v[162:165], v[120:123]
	v_mfma_f32_16x16x32_bf16 v[108:111], v[146:149], v[170:173], v[108:111]
	v_mfma_f32_16x16x32_bf16 v[104:107], v[154:157], v[170:173], v[104:107]
	v_mfma_f32_16x16x32_bf16 v[92:95], v[146:149], v[178:181], v[92:95]
	v_mfma_f32_16x16x32_bf16 v[88:91], v[154:157], v[178:181], v[88:91]
	v_mfma_f32_16x16x32_bf16 v[76:79], v[146:149], v[186:189], v[76:79]
	v_mfma_f32_16x16x32_bf16 v[72:75], v[154:157], v[186:189], v[72:75]
	v_mfma_f32_16x16x32_bf16 v[124:127], v[150:153], v[166:169], v[124:127]
	v_mfma_f32_16x16x32_bf16 v[120:123], v[158:161], v[166:169], v[120:123]
	v_mfma_f32_16x16x32_bf16 v[108:111], v[150:153], v[174:177], v[108:111]
	v_mfma_f32_16x16x32_bf16 v[104:107], v[158:161], v[174:177], v[104:107]
	v_mfma_f32_16x16x32_bf16 v[92:95], v[150:153], v[182:185], v[92:95]
	v_mfma_f32_16x16x32_bf16 v[88:91], v[158:161], v[182:185], v[88:91]
	v_mfma_f32_16x16x32_bf16 v[76:79], v[150:153], v[190:193], v[76:79]
	v_mfma_f32_16x16x32_bf16 v[72:75], v[158:161], v[190:193], v[72:75]
	s_setprio 0
	s_setprio 1
	v_mfma_f32_16x16x32_bf16 v[116:119], v[130:133], v[162:165], v[116:119]
	v_mfma_f32_16x16x32_bf16 v[112:115], v[138:141], v[162:165], v[112:115]
	v_mfma_f32_16x16x32_bf16 v[100:103], v[130:133], v[170:173], v[100:103]
	v_mfma_f32_16x16x32_bf16 v[96:99], v[138:141], v[170:173], v[96:99]
	v_mfma_f32_16x16x32_bf16 v[84:87], v[130:133], v[178:181], v[84:87]
	v_mfma_f32_16x16x32_bf16 v[80:83], v[138:141], v[178:181], v[80:83]
	v_mfma_f32_16x16x32_bf16 v[68:71], v[130:133], v[186:189], v[68:71]
	v_mfma_f32_16x16x32_bf16 v[64:67], v[138:141], v[186:189], v[64:67]
	v_mfma_f32_16x16x32_bf16 v[116:119], v[134:137], v[166:169], v[116:119]
	v_mfma_f32_16x16x32_bf16 v[112:115], v[142:145], v[166:169], v[112:115]
	v_mfma_f32_16x16x32_bf16 v[100:103], v[134:137], v[174:177], v[100:103]
	v_mfma_f32_16x16x32_bf16 v[96:99], v[142:145], v[174:177], v[96:99]
	v_mfma_f32_16x16x32_bf16 v[84:87], v[134:137], v[182:185], v[84:87]
	v_mfma_f32_16x16x32_bf16 v[80:83], v[142:145], v[182:185], v[80:83]
	v_mfma_f32_16x16x32_bf16 v[68:71], v[134:137], v[190:193], v[68:71]
	v_mfma_f32_16x16x32_bf16 v[64:67], v[142:145], v[190:193], v[64:67]
	s_setprio 0
	s_barrier
	s_add_i32 s2, s4, s65
	v_lshl_add_u64 v[220:221], s[28:29], 0, v[208:209]
	s_mov_b32 m0, s2
	ds_read_b128 v[186:189], v248 offset:16384
	ds_read_b128 v[190:193], v248 offset:17408
	ds_read_b128 v[178:181], v248 offset:18432
	ds_read_b128 v[182:185], v248 offset:19456
	ds_read_b128 v[170:173], v248 offset:20480
	ds_read_b128 v[174:177], v248 offset:21504
	ds_read_b128 v[162:165], v248 offset:22528
	ds_read_b128 v[166:169], v248 offset:23552
	global_load_lds_dwordx4 v[220:221], off
	s_add_i32 m0, s2, 0x2000
	s_add_u32 s2, s28, 0x40000
	v_lshl_add_u64 v[222:223], s[28:29], 0, v[212:213]
	s_addc_u32 s3, s29, 0
	s_add_i32 s4, s5, s65
	global_load_lds_dwordx4 v[222:223], off
	v_lshl_add_u64 v[196:197], s[2:3], 0, v[208:209]
	s_mov_b32 m0, s4
	v_lshl_add_u64 v[224:225], s[34:35], 0, v[206:207]
	global_load_lds_dwordx4 v[196:197], off
	v_lshl_add_u64 v[196:197], s[2:3], 0, v[212:213]
	s_add_i32 m0, s4, 0x2000
	v_lshl_add_u64 v[226:227], s[34:35], 0, v[210:211]
	global_load_lds_dwordx4 v[196:197], off
	s_mov_b32 m0, s70
	v_cndmask_b32_e64 v128, 0, 1, s[30:31]
	global_load_lds_dwordx4 v[224:225], off
	s_mov_b32 m0, s71
	v_cmp_ne_u32_e64 s[42:43], 1, v128
	global_load_lds_dwordx4 v[226:227], off
	s_waitcnt vmcnt(8)
	s_waitcnt lgkmcnt(0)
	s_andn2_b64 vcc, exec, s[30:31]
	s_barrier
	s_cbranch_vccnz .LBB0_168
; #define PG8_STAGE(bufoff, gbase, voff) do { _Pragma("unroll") for (int _i = 0; _i < 2; ++_i) \
;         __builtin_amdgcn_global_load_lds((const unsigned*)((const char*)(gbase) + (voff)[_i]), (PG8_LAS unsigned*)(lds + (bufoff) + ldsw + _i * 8192), 16, 0, 0); } while (0)
; #define PG8_LDA(dst, b, h) do { _Pragma("unroll") for (int m = 0; m < 4; ++m) _Pragma("unroll") for (int k = 0; k < 2; ++k) dst[m][k] = *(const PG8_LAS bf16x8*)(lds + PG8_SA(b, h) + aoff + m * 2048 + k * 1024); } while (0)
; #define PG8_LDB(dst, b, h) do { _Pragma("unroll") for (int n = 0; n < 2; ++n) _Pragma("unroll") for (int k = 0; k < 2; ++k) dst[n][k] = *(const PG8_LAS bf16x8*)(lds + PG8_SB(b, h) + boff + n * 2048 + k * 1024); } while (0)
; #define PG8_MMA(ai, bj, At, Bt) do { __builtin_amdgcn_s_setprio(1); _Pragma("unroll") for (int m = 0; m < 4; ++m) _Pragma("unroll") for (int n = 0; n < 2; ++n) _Pragma("unroll") for (int k = 0; k < 2; ++k) \
;         acc[ai][bj][m][n] = __builtin_amdgcn_mfma_f32_16x16x32_bf16(Bt[n][k], At[m][k], acc[ai][bj][m][n], 0, 0, 0); __builtin_amdgcn_s_setprio(0); } while (0)
; #define PG8_BAR __builtin_amdgcn_s_barrier()
; template <class Epi, class Sched, bool ALIGN_EPI = false, bool SP2 = false>
; __device__ __forceinline__ void gemm_phase(PG8_LAS unsigned char* lds, const Gemm g, const Sched& S, const Epi& E) {
;     ...
;             PG8_LDB(B0, 0, 0); PG8_LDB(B1, 0, 1); PG8_SCHED; PG8_LDA(At, 0, 0); PG8_STAGE(PG8_SA(1, 1), a1 + hstep, voffA);
;             PG8_WAIT_V(8); PG8_WAIT_L(0); PG8_BAR; PG8_MMA(0, 0, At, B0); PG8_MMA(0, 1, At, B1); PG8_BAR; PG8_SCHED;
;             PG8_LDA(At, 0, 1); PG8_STAGE(PG8_SB(0, 0), b2, voffB); PG8_STAGE(PG8_SB(0, 1), b2 + hstep, voffB); PG8_STAGE(PG8_SA(0, 0), a2, voffA);
;             PG8_WAIT_V(8); PG8_WAIT_L(0); PG8_BAR; if (full) { PG8_MMA(1, 0, At, B0); PG8_MMA(1, 1, At, B1); } PG8_BAR; PG8_SCHED;
;             PG8_LDB(B0, 1, 0); PG8_LDB(B1, 1, 1); PG8_SCHED; PG8_LDA(At, 1, 0); PG8_STAGE(PG8_SA(0, 1), a2 + hstep, voffA);
;             PG8_WAIT_V(8); PG8_WAIT_L(0); PG8_BAR; PG8_MMA(0, 0, At, B0); PG8_MMA(0, 1, At, B1); PG8_BAR; PG8_SCHED;
;             PG8_LDA(At, 1, 1); PG8_STAGE(PG8_SB(1, 0), b3, voffB); PG8_STAGE(PG8_SB(1, 1), b3 + hstep, voffB); PG8_STAGE(PG8_SA(1, 0), a3, voffA);
;             PG8_WAIT_V(8); PG8_WAIT_L(0); PG8_BAR; if (full) { PG8_MMA(1, 0, At, B0); PG8_MMA(1, 1, At, B1); } PG8_BAR; PG8_SCHED;
	s_setprio 1
	s_waitcnt lgkmcnt(0)
	v_mfma_f32_16x16x32_bf16 v[60:63], v[146:149], v[186:189], v[60:63]
	v_mfma_f32_16x16x32_bf16 v[56:59], v[154:157], v[186:189], v[56:59]
	v_mfma_f32_16x16x32_bf16 v[44:47], v[146:149], v[178:181], v[44:47]
	v_mfma_f32_16x16x32_bf16 v[40:43], v[154:157], v[178:181], v[40:43]
	v_mfma_f32_16x16x32_bf16 v[28:31], v[146:149], v[170:173], v[28:31]
	v_mfma_f32_16x16x32_bf16 v[24:27], v[154:157], v[170:173], v[24:27]
	v_mfma_f32_16x16x32_bf16 v[12:15], v[146:149], v[162:165], v[12:15]
	v_mfma_f32_16x16x32_bf16 v[8:11], v[154:157], v[162:165], v[8:11]
	v_mfma_f32_16x16x32_bf16 v[60:63], v[150:153], v[190:193], v[60:63]
	v_mfma_f32_16x16x32_bf16 v[56:59], v[158:161], v[190:193], v[56:59]
	v_mfma_f32_16x16x32_bf16 v[44:47], v[150:153], v[182:185], v[44:47]
	v_mfma_f32_16x16x32_bf16 v[40:43], v[158:161], v[182:185], v[40:43]
	v_mfma_f32_16x16x32_bf16 v[28:31], v[150:153], v[174:177], v[28:31]
	v_mfma_f32_16x16x32_bf16 v[24:27], v[158:161], v[174:177], v[24:27]
	v_mfma_f32_16x16x32_bf16 v[12:15], v[150:153], v[166:169], v[12:15]
	v_mfma_f32_16x16x32_bf16 v[8:11], v[158:161], v[166:169], v[8:11]
	s_setprio 0
	s_setprio 1
	v_mfma_f32_16x16x32_bf16 v[52:55], v[130:133], v[186:189], v[52:55]
	v_mfma_f32_16x16x32_bf16 v[48:51], v[138:141], v[186:189], v[48:51]
	v_mfma_f32_16x16x32_bf16 v[36:39], v[130:133], v[178:181], v[36:39]
	v_mfma_f32_16x16x32_bf16 v[32:35], v[138:141], v[178:181], v[32:35]
	v_mfma_f32_16x16x32_bf16 v[20:23], v[130:133], v[170:173], v[20:23]
	v_mfma_f32_16x16x32_bf16 v[16:19], v[138:141], v[170:173], v[16:19]
	v_mfma_f32_16x16x32_bf16 v[4:7], v[130:133], v[162:165], v[4:7]
	v_mfma_f32_16x16x32_bf16 v[0:3], v[138:141], v[162:165], v[0:3]
	v_mfma_f32_16x16x32_bf16 v[52:55], v[134:137], v[190:193], v[52:55]
	v_mfma_f32_16x16x32_bf16 v[48:51], v[142:145], v[190:193], v[48:51]
	v_mfma_f32_16x16x32_bf16 v[36:39], v[134:137], v[182:185], v[36:39]
	v_mfma_f32_16x16x32_bf16 v[32:35], v[142:145], v[182:185], v[32:35]
	v_mfma_f32_16x16x32_bf16 v[20:23], v[134:137], v[174:177], v[20:23]
	v_mfma_f32_16x16x32_bf16 v[16:19], v[142:145], v[174:177], v[16:19]
	v_mfma_f32_16x16x32_bf16 v[4:7], v[134:137], v[166:169], v[4:7]
	v_mfma_f32_16x16x32_bf16 v[0:3], v[142:145], v[166:169], v[0:3]
	s_setprio 0
.LBB0_168:
	s_barrier
	s_add_i32 s4, 0, 0x18000
	v_add_u32_e32 v128, s4, v228
	s_add_i32 s5, 0, 0x1c000
	ds_read_b128 v[146:149], v128
	ds_read_b128 v[150:153], v128 offset:1024
	ds_read_b128 v[154:157], v128 offset:2048
	ds_read_b128 v[158:161], v128 offset:3072
	v_add_u32_e32 v128, s5, v228
	ds_read_b128 v[130:133], v128
	ds_read_b128 v[134:137], v128 offset:1024
	ds_read_b128 v[138:141], v128 offset:2048
	ds_read_b128 v[142:145], v128 offset:3072
	s_add_u32 s2, s34, 0x40000
	s_addc_u32 s3, s35, 0
	s_mov_b32 m0, s73
	v_lshl_add_u64 v[196:197], s[2:3], 0, v[206:207]
	s_waitcnt lgkmcnt(7)
	ds_read_b128 v[162:165], v248 offset:32768
	ds_read_b128 v[166:169], v248 offset:33792
	ds_read_b128 v[170:173], v248 offset:34816
	ds_read_b128 v[174:177], v248 offset:35840
	ds_read_b128 v[178:181], v248 offset:36864
	ds_read_b128 v[182:185], v248 offset:37888
	ds_read_b128 v[186:189], v248 offset:38912
	ds_read_b128 v[190:193], v248 offset:39936
	global_load_lds_dwordx4 v[196:197], off
	v_lshl_add_u64 v[196:197], s[2:3], 0, v[210:211]
	s_mov_b32 m0, s87
	s_nop 0
	global_load_lds_dwordx4 v[196:197], off
	s_waitcnt vmcnt(8)
	s_waitcnt lgkmcnt(0)
	s_barrier
	s_setprio 1
	s_waitcnt lgkmcnt(0)
	v_mfma_f32_16x16x32_bf16 v[124:127], v[146:149], v[162:165], v[124:127]
	v_mfma_f32_16x16x32_bf16 v[120:123], v[154:157], v[162:165], v[120:123]
	v_mfma_f32_16x16x32_bf16 v[108:111], v[146:149], v[170:173], v[108:111]
	v_mfma_f32_16x16x32_bf16 v[104:107], v[154:157], v[170:173], v[104:107]
	v_mfma_f32_16x16x32_bf16 v[92:95], v[146:149], v[178:181], v[92:95]
	v_mfma_f32_16x16x32_bf16 v[88:91], v[154:157], v[178:181], v[88:91]
	v_mfma_f32_16x16x32_bf16 v[76:79], v[146:149], v[186:189], v[76:79]
	v_mfma_f32_16x16x32_bf16 v[72:75], v[154:157], v[186:189], v[72:75]
	v_mfma_f32_16x16x32_bf16 v[124:127], v[150:153], v[166:169], v[124:127]
	v_mfma_f32_16x16x32_bf16 v[120:123], v[158:161], v[166:169], v[120:123]
	v_mfma_f32_16x16x32_bf16 v[108:111], v[150:153], v[174:177], v[108:111]
	v_mfma_f32_16x16x32_bf16 v[104:107], v[158:161], v[174:177], v[104:107]
	v_mfma_f32_16x16x32_bf16 v[92:95], v[150:153], v[182:185], v[92:95]
	v_mfma_f32_16x16x32_bf16 v[88:91], v[158:161], v[182:185], v[88:91]
	v_mfma_f32_16x16x32_bf16 v[76:79], v[150:153], v[190:193], v[76:79]
	v_mfma_f32_16x16x32_bf16 v[72:75], v[158:161], v[190:193], v[72:75]
	s_setprio 0
	s_setprio 1
	v_mfma_f32_16x16x32_bf16 v[116:119], v[130:133], v[162:165], v[116:119]
	v_mfma_f32_16x16x32_bf16 v[112:115], v[138:141], v[162:165], v[112:115]
	v_mfma_f32_16x16x32_bf16 v[100:103], v[130:133], v[170:173], v[100:103]
	v_mfma_f32_16x16x32_bf16 v[96:99], v[138:141], v[170:173], v[96:99]
	v_mfma_f32_16x16x32_bf16 v[84:87], v[130:133], v[178:181], v[84:87]
	v_mfma_f32_16x16x32_bf16 v[80:83], v[138:141], v[178:181], v[80:83]
	v_mfma_f32_16x16x32_bf16 v[68:71], v[130:133], v[186:189], v[68:71]
	v_mfma_f32_16x16x32_bf16 v[64:67], v[138:141], v[186:189], v[64:67]
	v_mfma_f32_16x16x32_bf16 v[116:119], v[134:137], v[166:169], v[116:119]
	v_mfma_f32_16x16x32_bf16 v[112:115], v[142:145], v[166:169], v[112:115]
	v_mfma_f32_16x16x32_bf16 v[100:103], v[134:137], v[174:177], v[100:103]
	v_mfma_f32_16x16x32_bf16 v[96:99], v[142:145], v[174:177], v[96:99]
	v_mfma_f32_16x16x32_bf16 v[84:87], v[134:137], v[182:185], v[84:87]
	v_mfma_f32_16x16x32_bf16 v[80:83], v[142:145], v[182:185], v[80:83]
	v_mfma_f32_16x16x32_bf16 v[68:71], v[134:137], v[190:193], v[68:71]
	v_mfma_f32_16x16x32_bf16 v[64:67], v[142:145], v[190:193], v[64:67]
	s_setprio 0
	s_barrier
; #define PG8_STAGE(bufoff, gbase, voff) do { _Pragma("unroll") for (int _i = 0; _i < 2; ++_i) \
;         __builtin_amdgcn_global_load_lds((const unsigned*)((const char*)(gbase) + (voff)[_i]), (PG8_LAS unsigned*)(lds + (bufoff) + ldsw + _i * 8192), 16, 0, 0); } while (0)
; #define PG8_LDA(dst, b, h) do { _Pragma("unroll") for (int m = 0; m < 4; ++m) _Pragma("unroll") for (int k = 0; k < 2; ++k) dst[m][k] = *(const PG8_LAS bf16x8*)(lds + PG8_SA(b, h) + aoff + m * 2048 + k * 1024); } while (0)
; #define PG8_LDB(dst, b, h) do { _Pragma("unroll") for (int n = 0; n < 2; ++n) _Pragma("unroll") for (int k = 0; k < 2; ++k) dst[n][k] = *(const PG8_LAS bf16x8*)(lds + PG8_SB(b, h) + boff + n * 2048 + k * 1024); } while (0)
; #define PG8_MMA(ai, bj, At, Bt) do { __builtin_amdgcn_s_setprio(1); _Pragma("unroll") for (int m = 0; m < 4; ++m) _Pragma("unroll") for (int n = 0; n < 2; ++n) _Pragma("unroll") for (int k = 0; k < 2; ++k) \
;         acc[ai][bj][m][n] = __builtin_amdgcn_mfma_f32_16x16x32_bf16(Bt[n][k], At[m][k], acc[ai][bj][m][n], 0, 0, 0); __builtin_amdgcn_s_setprio(0); } while (0)
; #define PG8_BAR __builtin_amdgcn_s_barrier()
; template <class Epi, class Sched, bool ALIGN_EPI = false, bool SP2 = false>
; __device__ __forceinline__ void gemm_phase(PG8_LAS unsigned char* lds, const Gemm g, const Sched& S, const Epi& E) {
;     ...
;             PG8_LDB(B0, 0, 0); PG8_LDB(B1, 0, 1); PG8_SCHED; PG8_LDA(At, 0, 0); PG8_STAGE(PG8_SA(1, 1), a1 + hstep, voffA);
;             PG8_WAIT_V(8); PG8_WAIT_L(0); PG8_BAR; PG8_MMA(0, 0, At, B0); PG8_MMA(0, 1, At, B1); PG8_BAR; PG8_SCHED;
;             PG8_LDA(At, 0, 1); PG8_STAGE(PG8_SB(0, 0), b2, voffB); PG8_STAGE(PG8_SB(0, 1), b2 + hstep, voffB); PG8_STAGE(PG8_SA(0, 0), a2, voffA);
;             PG8_WAIT_V(8); PG8_WAIT_L(0); PG8_BAR; if (full) { PG8_MMA(1, 0, At, B0); PG8_MMA(1, 1, At, B1); } PG8_BAR; PG8_SCHED;
;             PG8_LDB(B0, 1, 0); PG8_LDB(B1, 1, 1); PG8_SCHED; PG8_LDA(At, 1, 0); PG8_STAGE(PG8_SA(0, 1), a2 + hstep, voffA);
;             PG8_WAIT_V(8); PG8_WAIT_L(0); PG8_BAR; PG8_MMA(0, 0, At, B0); PG8_MMA(0, 1, At, B1); PG8_BAR; PG8_SCHED;
;             PG8_LDA(At, 1, 1); PG8_STAGE(PG8_SB(1, 0), b3, voffB); PG8_STAGE(PG8_SB(1, 1), b3 + hstep, voffB); PG8_STAGE(PG8_SA(1, 0), a3, voffA);
;             PG8_WAIT_V(8); PG8_WAIT_L(0); PG8_BAR; if (full) { PG8_MMA(1, 0, At, B0); PG8_MMA(1, 1, At, B1); } PG8_BAR; PG8_SCHED;
	s_add_i32 s2, s4, s65
	v_lshl_add_u64 v[196:197], v[220:221], 0, s[26:27]
	s_mov_b32 m0, s2
	ds_read_b128 v[186:189], v248 offset:49152
	ds_read_b128 v[190:193], v248 offset:50176
	ds_read_b128 v[178:181], v248 offset:51200
	ds_read_b128 v[182:185], v248 offset:52224
	ds_read_b128 v[170:173], v248 offset:53248
	ds_read_b128 v[174:177], v248 offset:54272
	ds_read_b128 v[162:165], v248 offset:55296
	ds_read_b128 v[166:169], v248 offset:56320
	global_load_lds_dwordx4 v[196:197], off
	s_add_i32 m0, s2, 0x2000
	s_add_u32 s2, s28, 0x40080
	v_lshl_add_u64 v[196:197], v[222:223], 0, s[26:27]
	s_addc_u32 s3, s29, 0
	s_add_i32 s4, s5, s65
	global_load_lds_dwordx4 v[196:197], off
	v_lshl_add_u64 v[196:197], s[2:3], 0, v[208:209]
	s_mov_b32 m0, s4
	s_and_b64 vcc, exec, s[42:43]
	global_load_lds_dwordx4 v[196:197], off
	v_lshl_add_u64 v[196:197], s[2:3], 0, v[212:213]
	s_add_i32 m0, s4, 0x2000
	s_nop 0
	global_load_lds_dwordx4 v[196:197], off
	v_lshl_add_u64 v[196:197], v[224:225], 0, s[26:27]
	s_mov_b32 m0, s88
	s_nop 0
	global_load_lds_dwordx4 v[196:197], off
	v_lshl_add_u64 v[196:197], v[226:227], 0, s[26:27]
	s_mov_b32 m0, s89
	s_nop 0
	global_load_lds_dwordx4 v[196:197], off
	s_waitcnt vmcnt(8)
	s_waitcnt lgkmcnt(0)
	s_barrier
	s_cbranch_vccnz .LBB0_165
	s_setprio 1
	s_waitcnt lgkmcnt(0)
	v_mfma_f32_16x16x32_bf16 v[60:63], v[146:149], v[186:189], v[60:63]
	v_mfma_f32_16x16x32_bf16 v[56:59], v[154:157], v[186:189], v[56:59]
	v_mfma_f32_16x16x32_bf16 v[44:47], v[146:149], v[178:181], v[44:47]
	v_mfma_f32_16x16x32_bf16 v[40:43], v[154:157], v[178:181], v[40:43]
	v_mfma_f32_16x16x32_bf16 v[28:31], v[146:149], v[170:173], v[28:31]
	v_mfma_f32_16x16x32_bf16 v[24:27], v[154:157], v[170:173], v[24:27]
	v_mfma_f32_16x16x32_bf16 v[12:15], v[146:149], v[162:165], v[12:15]
	v_mfma_f32_16x16x32_bf16 v[8:11], v[154:157], v[162:165], v[8:11]
	v_mfma_f32_16x16x32_bf16 v[60:63], v[150:153], v[190:193], v[60:63]
	v_mfma_f32_16x16x32_bf16 v[56:59], v[158:161], v[190:193], v[56:59]
	v_mfma_f32_16x16x32_bf16 v[44:47], v[150:153], v[182:185], v[44:47]
	v_mfma_f32_16x16x32_bf16 v[40:43], v[158:161], v[182:185], v[40:43]
	v_mfma_f32_16x16x32_bf16 v[28:31], v[150:153], v[174:177], v[28:31]
	v_mfma_f32_16x16x32_bf16 v[24:27], v[158:161], v[174:177], v[24:27]
	v_mfma_f32_16x16x32_bf16 v[12:15], v[150:153], v[166:169], v[12:15]
	v_mfma_f32_16x16x32_bf16 v[8:11], v[158:161], v[166:169], v[8:11]
	s_setprio 0
	s_setprio 1
	v_mfma_f32_16x16x32_bf16 v[52:55], v[130:133], v[186:189], v[52:55]
	v_mfma_f32_16x16x32_bf16 v[48:51], v[138:141], v[186:189], v[48:51]
	v_mfma_f32_16x16x32_bf16 v[36:39], v[130:133], v[178:181], v[36:39]
	v_mfma_f32_16x16x32_bf16 v[32:35], v[138:141], v[178:181], v[32:35]
	v_mfma_f32_16x16x32_bf16 v[20:23], v[130:133], v[170:173], v[20:23]
	v_mfma_f32_16x16x32_bf16 v[16:19], v[138:141], v[170:173], v[16:19]
	v_mfma_f32_16x16x32_bf16 v[4:7], v[130:133], v[162:165], v[4:7]
	v_mfma_f32_16x16x32_bf16 v[0:3], v[138:141], v[162:165], v[0:3]
	v_mfma_f32_16x16x32_bf16 v[52:55], v[134:137], v[190:193], v[52:55]
	v_mfma_f32_16x16x32_bf16 v[48:51], v[142:145], v[190:193], v[48:51]
	v_mfma_f32_16x16x32_bf16 v[36:39], v[134:137], v[182:185], v[36:39]
	v_mfma_f32_16x16x32_bf16 v[32:35], v[142:145], v[182:185], v[32:35]
	v_mfma_f32_16x16x32_bf16 v[20:23], v[134:137], v[174:177], v[20:23]
	v_mfma_f32_16x16x32_bf16 v[16:19], v[142:145], v[174:177], v[16:19]
	v_mfma_f32_16x16x32_bf16 v[4:7], v[134:137], v[166:169], v[4:7]
	v_mfma_f32_16x16x32_bf16 v[0:3], v[142:145], v[166:169], v[0:3]
	s_setprio 0
	s_branch .LBB0_165

; __device__ __forceinline__ void finishSM(f32x16& p0, f32x16& p1, float alpha, float& l_reg, bf16x8& pa0, bf16x8& pa1, bf16x8& pa2, bf16x8& pa3) {
;   for (int r = 0; r < 16; ++r) p1[r] = __builtin_amdgcn_exp2f(p1[r]);
;   float ps = 0; for (int r = 0; r < 16; ++r) ps += p0[r]; for (int r = 0; r < 16; ++r) ps += p1[r];
;   { auto rr = __builtin_amdgcn_permlane32_swap(__float_as_uint(ps), __float_as_uint(ps), false, false);
;     ps = __uint_as_float(rr[0]) + __uint_as_float(rr[1]); }
;   l_reg = l_reg * alpha + ps;
;     ...
;   PK4(p0, 0, pa0); PK4(p0, 8, pa1); PK4(p1, 0, pa2); PK4(p1, 8, pa3);
;     ...
; }
; template <int BOFF> __device__ __forceinline__ void qkt_i(f32x16& p0, f32x16& p1, const int (&kb)[4], const bf16x8* qr) {
;   p0 = f32x16{}; p1 = f32x16{};
; #pragma unroll
;   for (int d0 = 0; d0 < 8; ++d0) { const int off = BOFF + (d0 >> 2) * 128;
;     const bf16x8 b0 = LDSV(kb[d0 & 3] + off), b1 = LDSV(kb[d0 & 3] + off + 8192);
;     p0 = __builtin_amdgcn_mfma_f32_32x32x16_bf16(b0, qr[d0], p0, 0, 0, 0);
;     p1 = __builtin_amdgcn_mfma_f32_32x32x16_bf16(b1, qr[d0], p1, 0, 0, 0); }
; }
.LBB0_352:
	s_waitcnt lgkmcnt(0)
	s_barrier
	ds_read_b128 v[80:83], v207 offset:16384
	ds_read_b128 v[84:87], v207 offset:24576
	ds_read_b128 v[162:165], v208 offset:16384
	ds_read_b128 v[166:169], v208 offset:24576
	v_exp_f32_e32 v170, v72
	v_exp_f32_e32 v171, v73
	v_exp_f32_e32 v172, v74
	v_exp_f32_e32 v173, v75
	v_exp_f32_e32 v174, v76
	v_exp_f32_e32 v175, v77
	v_exp_f32_e32 v176, v78
	v_exp_f32_e32 v79, v79
	s_waitcnt lgkmcnt(3)
	v_mfma_f32_32x32x16_bf16 v[96:111], v[80:83], v[142:145], 0
	v_exp_f32_e32 v236, v64
	v_add_f32_e32 v64, 0, v229
	v_add_f32_e32 v64, v243, v64
	v_add_f32_e32 v64, v244, v64
	s_waitcnt lgkmcnt(2)
	v_mfma_f32_32x32x16_bf16 v[80:95], v[84:87], v[142:145], 0
	v_add_f32_e32 v64, v246, v64
	v_add_f32_e32 v64, v242, v64
	v_add_f32_e32 v64, v245, v64
	s_waitcnt lgkmcnt(1)
	v_mfma_f32_32x32x16_bf16 v[96:111], v[162:165], v[138:141], v[96:111]
	v_add_f32_e32 v64, v227, v64
	v_add_f32_e32 v64, v228, v64
	v_add_f32_e32 v64, v223, v64
	s_waitcnt lgkmcnt(0)
	v_mfma_f32_32x32x16_bf16 v[80:95], v[166:169], v[138:141], v[80:95]
	ds_read_b128 v[162:165], v209 offset:16384
	ds_read_b128 v[166:169], v209 offset:24576
	v_add_f32_e32 v64, v226, v64
	v_add_f32_e32 v64, v224, v64
	v_add_f32_e32 v64, v225, v64
	v_add_f32_e32 v64, v220, v64
	v_exp_f32_e32 v237, v65
	s_waitcnt lgkmcnt(1)
	v_mfma_f32_32x32x16_bf16 v[96:111], v[162:165], v[112:115], v[96:111]
	v_add_f32_e32 v64, v222, v64
	v_exp_f32_e32 v238, v66
	v_add_f32_e32 v64, v219, v64
	v_exp_f32_e32 v239, v67
	s_waitcnt lgkmcnt(0)
	v_mfma_f32_32x32x16_bf16 v[80:95], v[166:169], v[112:115], v[80:95]
	ds_read_b128 v[162:165], v210 offset:16384
	ds_read_b128 v[166:169], v210 offset:24576
	v_add_f32_e32 v64, v221, v64
	v_exp_f32_e32 v247, v68
	v_add_f32_e32 v64, v236, v64
	v_exp_f32_e32 v248, v69
	s_waitcnt lgkmcnt(1)
	v_mfma_f32_32x32x16_bf16 v[96:111], v[162:165], v[116:119], v[96:111]
	v_add_f32_e32 v64, v237, v64
	v_exp_f32_e32 v249, v70
	v_add_f32_e32 v64, v238, v64
	v_exp_f32_e32 v252, v71
	s_waitcnt lgkmcnt(0)
	v_mfma_f32_32x32x16_bf16 v[80:95], v[166:169], v[116:119], v[80:95]
	ds_read_b128 v[162:165], v190 offset:16384
	ds_read_b128 v[166:169], v190 offset:24576
	v_add_f32_e32 v64, v239, v64
	v_add_f32_e32 v64, v247, v64
	v_add_f32_e32 v64, v248, v64
	v_add_f32_e32 v64, v249, v64
	v_add_f32_e32 v64, v252, v64
	v_add_f32_e32 v64, v170, v64
	s_waitcnt lgkmcnt(1)
	v_mfma_f32_32x32x16_bf16 v[96:111], v[162:165], v[120:123], v[96:111]
	v_add_f32_e32 v64, v171, v64
	v_add_f32_e32 v64, v172, v64
	v_add_f32_e32 v64, v173, v64
	v_add_f32_e32 v64, v174, v64
	v_add_f32_e32 v64, v175, v64
	s_waitcnt lgkmcnt(0)
	v_mfma_f32_32x32x16_bf16 v[80:95], v[166:169], v[120:123], v[80:95]
	ds_read_b128 v[162:165], v191 offset:16384
	ds_read_b128 v[166:169], v191 offset:24576
	v_add_f32_e32 v64, v176, v64
	v_add_f32_e32 v64, v79, v64
	v_mov_b32_e32 v65, v64
	s_nop 1
	v_permlane32_swap_b32_e32 v64, v65
	v_add_f32_e32 v64, v64, v65
	s_waitcnt lgkmcnt(1)
	v_mfma_f32_32x32x16_bf16 v[96:111], v[162:165], v[124:127], v[96:111]
	v_add_f32_e32 v128, v215, v64
	v_cvt_pk_bf16_f32 v64, v229, v243
	v_cvt_pk_bf16_f32 v65, v244, v246
	v_cvt_pk_bf16_f32 v66, v242, v245
	v_cvt_pk_bf16_f32 v67, v227, v228
	s_waitcnt lgkmcnt(0)
	v_mfma_f32_32x32x16_bf16 v[80:95], v[166:169], v[124:127], v[80:95]
	ds_read_b128 v[162:165], v192 offset:16384
	ds_read_b128 v[166:169], v192 offset:24576
	v_cvt_pk_bf16_f32 v68, v223, v226
	v_cvt_pk_bf16_f32 v69, v224, v225
	v_cvt_pk_bf16_f32 v70, v220, v222
	v_cvt_pk_bf16_f32 v71, v219, v221
	v_cvt_pk_bf16_f32 v72, v236, v237
	v_cvt_pk_bf16_f32 v73, v238, v239
	s_waitcnt lgkmcnt(1)
	v_mfma_f32_32x32x16_bf16 v[96:111], v[162:165], v[130:133], v[96:111]
	v_cvt_pk_bf16_f32 v74, v247, v248
	v_cvt_pk_bf16_f32 v75, v249, v252
	v_cvt_pk_bf16_f32 v76, v170, v171
	v_cvt_pk_bf16_f32 v77, v172, v173
	v_cvt_pk_bf16_f32 v78, v174, v175
	s_waitcnt lgkmcnt(0)
	v_mfma_f32_32x32x16_bf16 v[80:95], v[166:169], v[130:133], v[80:95]
	ds_read_b128 v[162:165], v193 offset:16384
	ds_read_b128 v[166:169], v193 offset:24576
	v_cvt_pk_bf16_f32 v79, v176, v79
	s_nop 0
	v_permlane32_swap_b32_e32 v64, v66
	v_permlane32_swap_b32_e32 v65, v67
	v_permlane32_swap_b32_e32 v68, v70
	v_permlane32_swap_b32_e32 v69, v71
	s_waitcnt lgkmcnt(1)
	v_mfma_f32_32x32x16_bf16 v[96:111], v[162:165], v[134:137], v[96:111]
	v_permlane32_swap_b32_e32 v72, v74
	v_permlane32_swap_b32_e32 v73, v75
	v_permlane32_swap_b32_e32 v76, v78
	v_permlane32_swap_b32_e32 v77, v79
	s_waitcnt lgkmcnt(0)
	v_mfma_f32_32x32x16_bf16 v[80:95], v[166:169], v[134:137], v[80:95]
	v_add_co_u32_e32 v166, vcc, s19, v178
	s_nop 1
	v_addc_co_u32_e32 v167, vcc, -1, v179, vcc
	v_add_co_u32_e32 v170, vcc, s20, v178
	s_nop 1
	v_addc_co_u32_e32 v171, vcc, -1, v179, vcc
	global_load_dwordx4 v[162:165], v[166:167], off
	s_nop 0
	global_load_dwordx4 v[166:169], v[166:167], off offset:-512
	s_nop 0
	global_load_dwordx4 v[174:177], v[170:171], off
	s_nop 0
	global_load_dwordx4 v[170:173], v[170:171], off offset:-512
	ds_read_b64_tr_b16 v[180:181], v206 offset:0
	ds_read_b64_tr_b16 v[182:183], v206 offset:0x800
	ds_read_b64_tr_b16 v[184:185], v206 offset:0x1000
	ds_read_b64_tr_b16 v[186:187], v206 offset:0x1800
	ds_read_b64_tr_b16 v[216:217], v206 offset:0x2000
	ds_read_b64_tr_b16 v[218:219], v206 offset:0x2800
	ds_read_b64_tr_b16 v[220:221], v206 offset:0x3000
	ds_read_b64_tr_b16 v[222:223], v206 offset:0x3800
	s_waitcnt lgkmcnt(0)
	s_waitcnt vmcnt(4)
; #define SBAR() __builtin_amdgcn_sched_barrier(0)
; template <int D0, int BOFF> __device__ __forceinline__ void pv_one_i(f32x16& od, int vb, bf16x8 pa0, bf16x8 pa1, bf16x8 pa2, bf16x8 pa3) {
;   const s16x4 l0 = tr_read<BOFF + v_rd_off(D0, 0, 0)>(vb), h0 = tr_read<BOFF + v_rd_off(D0, 0, 1)>(vb), l1 = tr_read<BOFF + v_rd_off(D0, 1, 0)>(vb), h1 = tr_read<BOFF + v_rd_off(D0, 1, 1)>(vb);
;   const s16x4 l2 = tr_read<BOFF + v_rd_off(D0, 2, 0)>(vb), h2 = tr_read<BOFF + v_rd_off(D0, 2, 1)>(vb), l3 = tr_read<BOFF + v_rd_off(D0, 3, 0)>(vb), h3 = tr_read<BOFF + v_rd_off(D0, 3, 1)>(vb);
;   asm volatile("s_waitcnt lgkmcnt(0)" ::: "memory"); SBAR();
;     ...
;   od = __builtin_amdgcn_mfma_f32_32x32x16_bf16(pa0, PK(l0, h0), od, 0, 0, 0);
;   od = __builtin_amdgcn_mfma_f32_32x32x16_bf16(pa1, PK(l1, h1), od, 0, 0, 0);
;   od = __builtin_amdgcn_mfma_f32_32x32x16_bf16(pa2, PK(l2, h2), od, 0, 0, 0);
;   od = __builtin_amdgcn_mfma_f32_32x32x16_bf16(pa3, PK(l3, h3), od, 0, 0, 0);
;     ...
; }
; template <int BOFF> __device__ __forceinline__ void pv_i(f32x16* o, int vb, bf16x8 pa0, bf16x8 pa1, bf16x8 pa2, bf16x8 pa3) {
;   pv_one_i<0, BOFF>(o[0], vb, pa0, pa1, pa2, pa3); pv_one_i<1, BOFF>(o[1], vb, pa0, pa1, pa2, pa3); pv_one_i<2, BOFF>(o[2], vb, pa0, pa1, pa2, pa3); pv_one_i<3, BOFF>(o[3], vb, pa0, pa1, pa2, pa3);
	ds_write_b128 v211, v[146:149] offset:32768
	s_nop 0
	v_mfma_f32_32x32x16_bf16 v[0:15], v[64:67], v[180:183], v[0:15]
	ds_read_b64_tr_b16 v[180:181], v206 offset:0x200
	ds_read_b64_tr_b16 v[182:183], v206 offset:0xa00
	v_mfma_f32_32x32x16_bf16 v[0:15], v[68:71], v[184:187], v[0:15]
	ds_read_b64_tr_b16 v[184:185], v206 offset:0x1200
	ds_read_b64_tr_b16 v[186:187], v206 offset:0x1a00
	v_mfma_f32_32x32x16_bf16 v[0:15], v[72:75], v[216:219], v[0:15]
	ds_read_b64_tr_b16 v[216:217], v206 offset:0x2200
	ds_read_b64_tr_b16 v[218:219], v206 offset:0x2a00
	v_mfma_f32_32x32x16_bf16 v[0:15], v[76:79], v[220:223], v[0:15]
	ds_read_b64_tr_b16 v[220:221], v206 offset:0x3200
	ds_read_b64_tr_b16 v[222:223], v206 offset:0x3a00
	s_waitcnt lgkmcnt(0)
	ds_write_b128 v212, v[150:153] offset:32768
	v_mfma_f32_32x32x16_bf16 v[16:31], v[64:67], v[180:183], v[16:31]
	ds_read_b64_tr_b16 v[180:181], v206 offset:0x400
	ds_read_b64_tr_b16 v[182:183], v206 offset:0xc00
	v_mfma_f32_32x32x16_bf16 v[16:31], v[68:71], v[184:187], v[16:31]
	ds_read_b64_tr_b16 v[184:185], v206 offset:0x1400
	ds_read_b64_tr_b16 v[186:187], v206 offset:0x1c00
	v_mfma_f32_32x32x16_bf16 v[16:31], v[72:75], v[216:219], v[16:31]
	ds_read_b64_tr_b16 v[216:217], v206 offset:0x2400
	ds_read_b64_tr_b16 v[218:219], v206 offset:0x2c00
	v_mfma_f32_32x32x16_bf16 v[16:31], v[76:79], v[220:223], v[16:31]
	ds_read_b64_tr_b16 v[220:221], v206 offset:0x3400
	ds_read_b64_tr_b16 v[222:223], v206 offset:0x3c00
	s_waitcnt lgkmcnt(0)
	ds_write_b128 v213, v[154:157] offset:32768
	v_mfma_f32_32x32x16_bf16 v[32:47], v[64:67], v[180:183], v[32:47]
	ds_read_b64_tr_b16 v[180:181], v206 offset:0x600
	ds_read_b64_tr_b16 v[182:183], v206 offset:0xe00
	v_mfma_f32_32x32x16_bf16 v[32:47], v[68:71], v[184:187], v[32:47]
	ds_read_b64_tr_b16 v[184:185], v206 offset:0x1600
	ds_read_b64_tr_b16 v[186:187], v206 offset:0x1e00
	v_mfma_f32_32x32x16_bf16 v[32:47], v[72:75], v[216:219], v[32:47]
	ds_read_b64_tr_b16 v[216:217], v206 offset:0x2600
	ds_read_b64_tr_b16 v[218:219], v206 offset:0x2e00
	v_mfma_f32_32x32x16_bf16 v[32:47], v[76:79], v[220:223], v[32:47]
	ds_read_b64_tr_b16 v[220:221], v206 offset:0x3600
	ds_read_b64_tr_b16 v[222:223], v206 offset:0x3e00
	s_waitcnt lgkmcnt(0)
	ds_write_b128 v214, v[158:161] offset:32768
	v_mfma_f32_32x32x16_bf16 v[48:63], v[64:67], v[180:183], v[48:63]
	v_exp_f32_e32 v215, v108
	s_waitcnt vmcnt(4)
	v_exp_f32_e32 v181, v96
	v_exp_f32_e32 v183, v97
	v_exp_f32_e32 v188, v102
	v_exp_f32_e32 v189, v103
	v_exp_f32_e32 v196, v104
	v_mfma_f32_32x32x16_bf16 v[48:63], v[68:71], v[184:187], v[48:63]
	v_exp_f32_e32 v184, v98
	v_exp_f32_e32 v185, v99
	v_exp_f32_e32 v186, v100
	v_exp_f32_e32 v187, v101
	v_exp_f32_e32 v197, v105
	v_exp_f32_e32 v198, v106
	v_exp_f32_e32 v199, v107
	v_mfma_f32_32x32x16_bf16 v[48:63], v[72:75], v[216:219], v[48:63]
	v_exp_f32_e32 v216, v109
	v_exp_f32_e32 v217, v110
	v_exp_f32_e32 v218, v111
	s_waitcnt lgkmcnt(0)
	s_barrier
	v_mfma_f32_32x32x16_bf16 v[48:63], v[76:79], v[220:223], v[48:63]
	ds_read_b128 v[64:67], v207 offset:32768
	ds_read_b128 v[96:99], v207 offset:40960
	ds_read_b128 v[146:149], v208 offset:32768
	ds_read_b128 v[150:153], v208 offset:40960
	v_exp_f32_e32 v154, v88
	v_exp_f32_e32 v155, v89
	v_exp_f32_e32 v156, v90
	v_exp_f32_e32 v157, v91
	v_exp_f32_e32 v158, v92
	v_exp_f32_e32 v159, v93
	v_exp_f32_e32 v160, v94
	v_exp_f32_e32 v95, v95
	s_waitcnt lgkmcnt(3)
	v_mfma_f32_32x32x16_bf16 v[64:79], v[64:67], v[142:145], 0
	v_exp_f32_e32 v236, v80
	v_add_f32_e32 v80, 0, v181
	v_add_f32_e32 v80, v183, v80
	v_add_f32_e32 v80, v184, v80
	s_waitcnt lgkmcnt(2)
	v_mfma_f32_32x32x16_bf16 v[96:111], v[96:99], v[142:145], 0
	v_add_f32_e32 v80, v185, v80
	v_add_f32_e32 v80, v186, v80
	v_add_f32_e32 v80, v187, v80
	s_waitcnt lgkmcnt(1)
	v_mfma_f32_32x32x16_bf16 v[64:79], v[146:149], v[138:141], v[64:79]
	v_add_f32_e32 v80, v188, v80
	v_add_f32_e32 v80, v189, v80
	v_add_f32_e32 v80, v196, v80
	s_waitcnt lgkmcnt(0)
	v_mfma_f32_32x32x16_bf16 v[96:111], v[150:153], v[138:141], v[96:111]
	ds_read_b128 v[146:149], v209 offset:32768
	ds_read_b128 v[150:153], v209 offset:40960
	v_add_f32_e32 v80, v197, v80
	v_add_f32_e32 v80, v198, v80
	v_add_f32_e32 v80, v199, v80
	v_add_f32_e32 v80, v215, v80
	v_exp_f32_e32 v237, v81
	s_waitcnt lgkmcnt(1)
	v_mfma_f32_32x32x16_bf16 v[64:79], v[146:149], v[112:115], v[64:79]
	v_add_f32_e32 v80, v216, v80
	v_exp_f32_e32 v238, v82
	v_add_f32_e32 v80, v217, v80
	v_exp_f32_e32 v239, v83
	s_waitcnt lgkmcnt(0)
	v_mfma_f32_32x32x16_bf16 v[96:111], v[150:153], v[112:115], v[96:111]
	ds_read_b128 v[146:149], v210 offset:32768
	ds_read_b128 v[150:153], v210 offset:40960
	v_add_f32_e32 v80, v218, v80
	v_exp_f32_e32 v247, v84
	v_add_f32_e32 v80, v236, v80
	v_exp_f32_e32 v248, v85
	s_waitcnt lgkmcnt(1)
	v_mfma_f32_32x32x16_bf16 v[64:79], v[146:149], v[116:119], v[64:79]
	v_add_f32_e32 v80, v237, v80
	v_exp_f32_e32 v249, v86
	v_add_f32_e32 v80, v238, v80
	v_exp_f32_e32 v252, v87
	s_waitcnt lgkmcnt(0)
	v_mfma_f32_32x32x16_bf16 v[96:111], v[150:153], v[116:119], v[96:111]
	ds_read_b128 v[146:149], v190 offset:32768
	ds_read_b128 v[150:153], v190 offset:40960
	v_add_f32_e32 v80, v239, v80
	v_add_f32_e32 v80, v247, v80
	v_add_f32_e32 v80, v248, v80
	v_add_f32_e32 v80, v249, v80
	v_add_f32_e32 v80, v252, v80
	v_add_f32_e32 v80, v154, v80
	s_waitcnt lgkmcnt(1)
	v_mfma_f32_32x32x16_bf16 v[64:79], v[146:149], v[120:123], v[64:79]
	v_add_f32_e32 v80, v155, v80
	v_add_f32_e32 v80, v156, v80
	v_add_f32_e32 v80, v157, v80
	v_add_f32_e32 v80, v158, v80
	v_add_f32_e32 v80, v159, v80
	s_waitcnt lgkmcnt(0)
; #define SBAR() __builtin_amdgcn_sched_barrier(0)
; template <int D0, int BOFF> __device__ __forceinline__ void pv_one_i(f32x16& od, int vb, bf16x8 pa0, bf16x8 pa1, bf16x8 pa2, bf16x8 pa3) {
;   const s16x4 l0 = tr_read<BOFF + v_rd_off(D0, 0, 0)>(vb), h0 = tr_read<BOFF + v_rd_off(D0, 0, 1)>(vb), l1 = tr_read<BOFF + v_rd_off(D0, 1, 0)>(vb), h1 = tr_read<BOFF + v_rd_off(D0, 1, 1)>(vb);
;   const s16x4 l2 = tr_read<BOFF + v_rd_off(D0, 2, 0)>(vb), h2 = tr_read<BOFF + v_rd_off(D0, 2, 1)>(vb), l3 = tr_read<BOFF + v_rd_off(D0, 3, 0)>(vb), h3 = tr_read<BOFF + v_rd_off(D0, 3, 1)>(vb);
;   asm volatile("s_waitcnt lgkmcnt(0)" ::: "memory"); SBAR();
;     ...
;   od = __builtin_amdgcn_mfma_f32_32x32x16_bf16(pa0, PK(l0, h0), od, 0, 0, 0);
;   od = __builtin_amdgcn_mfma_f32_32x32x16_bf16(pa1, PK(l1, h1), od, 0, 0, 0);
;   od = __builtin_amdgcn_mfma_f32_32x32x16_bf16(pa2, PK(l2, h2), od, 0, 0, 0);
;   od = __builtin_amdgcn_mfma_f32_32x32x16_bf16(pa3, PK(l3, h3), od, 0, 0, 0);
;     ...
; }
; template <int BOFF> __device__ __forceinline__ void pv_i(f32x16* o, int vb, bf16x8 pa0, bf16x8 pa1, bf16x8 pa2, bf16x8 pa3) {
;   pv_one_i<0, BOFF>(o[0], vb, pa0, pa1, pa2, pa3); pv_one_i<1, BOFF>(o[1], vb, pa0, pa1, pa2, pa3); pv_one_i<2, BOFF>(o[2], vb, pa0, pa1, pa2, pa3); pv_one_i<3, BOFF>(o[3], vb, pa0, pa1, pa2, pa3);
	v_mfma_f32_32x32x16_bf16 v[96:111], v[150:153], v[120:123], v[96:111]
	ds_read_b128 v[146:149], v191 offset:32768
	ds_read_b128 v[150:153], v191 offset:40960
	v_add_f32_e32 v80, v160, v80
	v_add_f32_e32 v180, v95, v80
	v_mov_b32_e32 v182, v180
	v_cvt_pk_bf16_f32 v80, v181, v183
	v_cvt_pk_bf16_f32 v81, v184, v185
	v_cvt_pk_bf16_f32 v82, v186, v187
	s_waitcnt lgkmcnt(1)
	v_mfma_f32_32x32x16_bf16 v[64:79], v[146:149], v[124:127], v[64:79]
	v_cvt_pk_bf16_f32 v83, v188, v189
	v_cvt_pk_bf16_f32 v84, v196, v197
	v_cvt_pk_bf16_f32 v85, v198, v199
	v_cvt_pk_bf16_f32 v86, v215, v216
	v_cvt_pk_bf16_f32 v87, v217, v218
	s_waitcnt lgkmcnt(0)
	v_mfma_f32_32x32x16_bf16 v[96:111], v[150:153], v[124:127], v[96:111]
	ds_read_b128 v[146:149], v192 offset:32768
	ds_read_b128 v[150:153], v192 offset:40960
	v_cvt_pk_bf16_f32 v88, v236, v237
	v_cvt_pk_bf16_f32 v89, v238, v239
	v_cvt_pk_bf16_f32 v90, v247, v248
	v_cvt_pk_bf16_f32 v91, v249, v252
	v_cvt_pk_bf16_f32 v92, v154, v155
	v_cvt_pk_bf16_f32 v93, v156, v157
	s_waitcnt lgkmcnt(1)
	v_mfma_f32_32x32x16_bf16 v[64:79], v[146:149], v[130:133], v[64:79]
	v_cvt_pk_bf16_f32 v94, v158, v159
	v_cvt_pk_bf16_f32 v95, v160, v95
	s_nop 1
	v_permlane32_swap_b32_e32 v180, v182
	v_permlane32_swap_b32_e32 v80, v82
	s_waitcnt lgkmcnt(0)
	v_mfma_f32_32x32x16_bf16 v[96:111], v[150:153], v[130:133], v[96:111]
	ds_read_b128 v[146:149], v193 offset:32768
	ds_read_b128 v[150:153], v193 offset:40960
	v_permlane32_swap_b32_e32 v81, v83
	v_permlane32_swap_b32_e32 v84, v86
	v_permlane32_swap_b32_e32 v85, v87
	v_permlane32_swap_b32_e32 v88, v90
	v_permlane32_swap_b32_e32 v89, v91
	v_permlane32_swap_b32_e32 v92, v94
	s_waitcnt lgkmcnt(1)
	v_mfma_f32_32x32x16_bf16 v[64:79], v[146:149], v[134:137], v[64:79]
	v_permlane32_swap_b32_e32 v93, v95
	s_waitcnt lgkmcnt(0)
	v_mfma_f32_32x32x16_bf16 v[96:111], v[150:153], v[134:137], v[96:111]
	v_add_co_u32_e32 v150, vcc, s21, v178
	s_nop 1
	v_addc_co_u32_e32 v151, vcc, -1, v179, vcc
	v_add_co_u32_e32 v154, vcc, s22, v178
	s_nop 1
	v_addc_co_u32_e32 v155, vcc, -1, v179, vcc
	global_load_dwordx4 v[146:149], v[150:151], off
	s_nop 0
	global_load_dwordx4 v[150:153], v[150:151], off offset:-512
	s_nop 0
	global_load_dwordx4 v[158:161], v[154:155], off
	s_nop 0
	global_load_dwordx4 v[154:157], v[154:155], off offset:-512
	ds_read_b64_tr_b16 v[184:185], v206 offset:0x4000
	ds_read_b64_tr_b16 v[186:187], v206 offset:0x4800
	ds_read_b64_tr_b16 v[216:217], v206 offset:0x5000
	ds_read_b64_tr_b16 v[218:219], v206 offset:0x5800
	ds_read_b64_tr_b16 v[220:221], v206 offset:0x6000
	ds_read_b64_tr_b16 v[222:223], v206 offset:0x6800
	ds_read_b64_tr_b16 v[224:225], v206 offset:0x7000
	ds_read_b64_tr_b16 v[226:227], v206 offset:0x7800
	s_waitcnt lgkmcnt(0)
	s_waitcnt vmcnt(4)
	ds_write_b128 v211, v[162:165]
	s_nop 0
	v_mfma_f32_32x32x16_bf16 v[0:15], v[80:83], v[184:187], v[0:15]
	ds_read_b64_tr_b16 v[184:185], v206 offset:0x4200
	ds_read_b64_tr_b16 v[186:187], v206 offset:0x4a00
	v_mfma_f32_32x32x16_bf16 v[0:15], v[84:87], v[216:219], v[0:15]
	ds_read_b64_tr_b16 v[216:217], v206 offset:0x5200
	ds_read_b64_tr_b16 v[218:219], v206 offset:0x5a00
	v_mfma_f32_32x32x16_bf16 v[0:15], v[88:91], v[220:223], v[0:15]
	ds_read_b64_tr_b16 v[220:221], v206 offset:0x6200
	ds_read_b64_tr_b16 v[222:223], v206 offset:0x6a00
	v_mfma_f32_32x32x16_bf16 v[0:15], v[92:95], v[224:227], v[0:15]
	ds_read_b64_tr_b16 v[224:225], v206 offset:0x7200
	ds_read_b64_tr_b16 v[226:227], v206 offset:0x7a00
	s_waitcnt lgkmcnt(0)
	ds_write_b128 v212, v[174:177]
	v_mfma_f32_32x32x16_bf16 v[16:31], v[80:83], v[184:187], v[16:31]
	ds_read_b64_tr_b16 v[184:185], v206 offset:0x4400
	ds_read_b64_tr_b16 v[186:187], v206 offset:0x4c00
	v_mfma_f32_32x32x16_bf16 v[16:31], v[84:87], v[216:219], v[16:31]
	ds_read_b64_tr_b16 v[216:217], v206 offset:0x5400
	ds_read_b64_tr_b16 v[218:219], v206 offset:0x5c00
	v_mfma_f32_32x32x16_bf16 v[16:31], v[88:91], v[220:223], v[16:31]
	ds_read_b64_tr_b16 v[220:221], v206 offset:0x6400
	ds_read_b64_tr_b16 v[222:223], v206 offset:0x6c00
	v_mfma_f32_32x32x16_bf16 v[16:31], v[92:95], v[224:227], v[16:31]
	ds_read_b64_tr_b16 v[224:225], v206 offset:0x7400
	ds_read_b64_tr_b16 v[226:227], v206 offset:0x7c00
	s_waitcnt lgkmcnt(0)
	ds_write_b128 v213, v[166:169]
	v_mfma_f32_32x32x16_bf16 v[32:47], v[80:83], v[184:187], v[32:47]
	ds_read_b64_tr_b16 v[184:185], v206 offset:0x4600
	ds_read_b64_tr_b16 v[186:187], v206 offset:0x4e00
	v_mfma_f32_32x32x16_bf16 v[32:47], v[84:87], v[216:219], v[32:47]
	ds_read_b64_tr_b16 v[216:217], v206 offset:0x5600
	ds_read_b64_tr_b16 v[218:219], v206 offset:0x5e00
	v_mfma_f32_32x32x16_bf16 v[32:47], v[88:91], v[220:223], v[32:47]
	ds_read_b64_tr_b16 v[220:221], v206 offset:0x6600
	ds_read_b64_tr_b16 v[222:223], v206 offset:0x6e00
	v_mfma_f32_32x32x16_bf16 v[32:47], v[92:95], v[224:227], v[32:47]
	ds_read_b64_tr_b16 v[224:225], v206 offset:0x7600
	ds_read_b64_tr_b16 v[226:227], v206 offset:0x7e00
	s_waitcnt lgkmcnt(0)
	ds_write_b128 v214, v[170:173]
	v_mfma_f32_32x32x16_bf16 v[48:63], v[80:83], v[184:187], v[48:63]
	v_exp_f32_e32 v215, v74
	s_waitcnt vmcnt(4)
	v_exp_f32_e32 v184, v64
	v_exp_f32_e32 v185, v65
	v_exp_f32_e32 v186, v66
	v_exp_f32_e32 v187, v67
	v_exp_f32_e32 v188, v68
	v_mfma_f32_32x32x16_bf16 v[48:63], v[84:87], v[216:219], v[48:63]
	v_exp_f32_e32 v219, v78
	v_exp_f32_e32 v189, v69
	v_exp_f32_e32 v196, v70
	v_exp_f32_e32 v197, v71
	v_exp_f32_e32 v198, v72
	v_exp_f32_e32 v199, v73
	v_exp_f32_e32 v216, v75
	v_mfma_f32_32x32x16_bf16 v[48:63], v[88:91], v[220:223], v[48:63]
	v_exp_f32_e32 v220, v79
	v_exp_f32_e32 v217, v76
	v_exp_f32_e32 v218, v77
	s_waitcnt lgkmcnt(0)
	s_barrier
; __device__ __forceinline__ void finishSM(f32x16& p0, f32x16& p1, float alpha, float& l_reg, bf16x8& pa0, bf16x8& pa1, bf16x8& pa2, bf16x8& pa3) {
;   for (int r = 0; r < 16; ++r) p1[r] = __builtin_amdgcn_exp2f(p1[r]);
;   float ps = 0; for (int r = 0; r < 16; ++r) ps += p0[r]; for (int r = 0; r < 16; ++r) ps += p1[r];
;   { auto rr = __builtin_amdgcn_permlane32_swap(__float_as_uint(ps), __float_as_uint(ps), false, false);
;     ps = __uint_as_float(rr[0]) + __uint_as_float(rr[1]); }
;   l_reg = l_reg * alpha + ps;
;     ...
;   PK4(p0, 0, pa0); PK4(p0, 8, pa1); PK4(p1, 0, pa2); PK4(p1, 8, pa3);
;     ...
; }
; template <int BOFF> __device__ __forceinline__ void qkt_i(f32x16& p0, f32x16& p1, const int (&kb)[4], const bf16x8* qr) {
;   p0 = f32x16{}; p1 = f32x16{};
; #pragma unroll
;   for (int d0 = 0; d0 < 8; ++d0) { const int off = BOFF + (d0 >> 2) * 128;
;     const bf16x8 b0 = LDSV(kb[d0 & 3] + off), b1 = LDSV(kb[d0 & 3] + off + 8192);
;     p0 = __builtin_amdgcn_mfma_f32_32x32x16_bf16(b0, qr[d0], p0, 0, 0, 0);
;     p1 = __builtin_amdgcn_mfma_f32_32x32x16_bf16(b1, qr[d0], p1, 0, 0, 0); }
; }
	v_mfma_f32_32x32x16_bf16 v[48:63], v[92:95], v[224:227], v[48:63]
	ds_read_b128 v[64:67], v207
	ds_read_b128 v[68:71], v207 offset:8192
	ds_read_b128 v[162:165], v208
	ds_read_b128 v[166:169], v208 offset:8192
	v_exp_f32_e32 v170, v104
	v_exp_f32_e32 v171, v105
	v_exp_f32_e32 v172, v106
	v_exp_f32_e32 v173, v107
	v_exp_f32_e32 v174, v108
	v_exp_f32_e32 v175, v109
	v_exp_f32_e32 v176, v110
	v_exp_f32_e32 v111, v111
	s_waitcnt lgkmcnt(3)
	v_mfma_f32_32x32x16_bf16 v[80:95], v[64:67], v[142:145], 0
	v_exp_f32_e32 v236, v96
	v_add_f32_e32 v96, 0, v184
	v_add_f32_e32 v96, v185, v96
	v_add_f32_e32 v96, v186, v96
	s_waitcnt lgkmcnt(2)
	v_mfma_f32_32x32x16_bf16 v[64:79], v[68:71], v[142:145], 0
	v_add_f32_e32 v96, v187, v96
	v_add_f32_e32 v96, v188, v96
	v_add_f32_e32 v96, v189, v96
	s_waitcnt lgkmcnt(1)
	v_mfma_f32_32x32x16_bf16 v[80:95], v[162:165], v[138:141], v[80:95]
	v_add_f32_e32 v96, v196, v96
	v_add_f32_e32 v96, v197, v96
	v_add_f32_e32 v96, v198, v96
	s_waitcnt lgkmcnt(0)
	v_mfma_f32_32x32x16_bf16 v[64:79], v[166:169], v[138:141], v[64:79]
	ds_read_b128 v[162:165], v209
	ds_read_b128 v[166:169], v209 offset:8192
	v_add_f32_e32 v96, v199, v96
	v_add_f32_e32 v96, v215, v96
	v_add_f32_e32 v96, v216, v96
	v_add_f32_e32 v96, v217, v96
	v_exp_f32_e32 v237, v97
	s_waitcnt lgkmcnt(1)
	v_mfma_f32_32x32x16_bf16 v[80:95], v[162:165], v[112:115], v[80:95]
	v_add_f32_e32 v96, v218, v96
	v_exp_f32_e32 v238, v98
	v_add_f32_e32 v96, v219, v96
	v_exp_f32_e32 v239, v99
	s_waitcnt lgkmcnt(0)
	v_mfma_f32_32x32x16_bf16 v[64:79], v[166:169], v[112:115], v[64:79]
	ds_read_b128 v[162:165], v210
	ds_read_b128 v[166:169], v210 offset:8192
	v_add_f32_e32 v96, v220, v96
	v_exp_f32_e32 v247, v100
	v_add_f32_e32 v96, v236, v96
	v_exp_f32_e32 v248, v101
	s_waitcnt lgkmcnt(1)
	v_mfma_f32_32x32x16_bf16 v[80:95], v[162:165], v[116:119], v[80:95]
	v_add_f32_e32 v96, v237, v96
	v_exp_f32_e32 v249, v102
	v_add_f32_e32 v96, v238, v96
	v_exp_f32_e32 v252, v103
	s_waitcnt lgkmcnt(0)
	v_mfma_f32_32x32x16_bf16 v[64:79], v[166:169], v[116:119], v[64:79]
	ds_read_b128 v[162:165], v190 offset:0
	ds_read_b128 v[166:169], v190 offset:8192
	v_add_f32_e32 v96, v239, v96
	v_add_f32_e32 v96, v247, v96
	v_add_f32_e32 v96, v248, v96
	v_add_f32_e32 v96, v249, v96
	v_add_f32_e32 v96, v252, v96
	v_add_f32_e32 v96, v170, v96
	s_waitcnt lgkmcnt(1)
	v_mfma_f32_32x32x16_bf16 v[80:95], v[162:165], v[120:123], v[80:95]
	v_add_f32_e32 v96, v171, v96
	v_add_f32_e32 v96, v172, v96
	v_add_f32_e32 v96, v173, v96
	v_add_f32_e32 v96, v174, v96
	v_add_f32_e32 v96, v175, v96
	s_waitcnt lgkmcnt(0)
	v_mfma_f32_32x32x16_bf16 v[64:79], v[166:169], v[120:123], v[64:79]
	ds_read_b128 v[162:165], v191 offset:0
	ds_read_b128 v[166:169], v191 offset:8192
	v_add_f32_e32 v96, v176, v96
	v_add_f32_e32 v181, v111, v96
	v_mov_b32_e32 v183, v181
	s_nop 1
	v_permlane32_swap_b32_e32 v181, v183
	v_pk_add_f32 v[96:97], v[180:181], v[182:183]
	s_waitcnt lgkmcnt(1)
	v_mfma_f32_32x32x16_bf16 v[80:95], v[162:165], v[124:127], v[80:95]
	s_nop 0
	v_add_f32_e32 v96, v128, v96
	v_add_f32_e32 v128, v96, v97
	v_cvt_pk_bf16_f32 v96, v184, v185
	v_cvt_pk_bf16_f32 v97, v186, v187
	s_waitcnt lgkmcnt(0)
	v_mfma_f32_32x32x16_bf16 v[64:79], v[166:169], v[124:127], v[64:79]
	ds_read_b128 v[162:165], v192 offset:0
	ds_read_b128 v[166:169], v192 offset:8192
	v_cvt_pk_bf16_f32 v98, v188, v189
	v_cvt_pk_bf16_f32 v99, v196, v197
	v_cvt_pk_bf16_f32 v100, v198, v199
	v_cvt_pk_bf16_f32 v101, v215, v216
	v_cvt_pk_bf16_f32 v102, v217, v218
	v_cvt_pk_bf16_f32 v103, v219, v220
	s_waitcnt lgkmcnt(1)
	v_mfma_f32_32x32x16_bf16 v[80:95], v[162:165], v[130:133], v[80:95]
	v_cvt_pk_bf16_f32 v104, v236, v237
	v_cvt_pk_bf16_f32 v105, v238, v239
	v_cvt_pk_bf16_f32 v106, v247, v248
	v_cvt_pk_bf16_f32 v107, v249, v252
	v_cvt_pk_bf16_f32 v108, v170, v171
	s_waitcnt lgkmcnt(0)
	v_mfma_f32_32x32x16_bf16 v[64:79], v[166:169], v[130:133], v[64:79]
	ds_read_b128 v[162:165], v193 offset:0
	ds_read_b128 v[166:169], v193 offset:8192
	v_cvt_pk_bf16_f32 v109, v172, v173
	v_cvt_pk_bf16_f32 v110, v174, v175
	v_cvt_pk_bf16_f32 v111, v176, v111
	s_nop 0
	v_permlane32_swap_b32_e32 v96, v98
	v_permlane32_swap_b32_e32 v97, v99
	s_waitcnt lgkmcnt(1)
	v_mfma_f32_32x32x16_bf16 v[80:95], v[162:165], v[134:137], v[80:95]
	v_permlane32_swap_b32_e32 v100, v102
	v_permlane32_swap_b32_e32 v101, v103
	v_permlane32_swap_b32_e32 v104, v106
	v_permlane32_swap_b32_e32 v105, v107
	v_permlane32_swap_b32_e32 v108, v110
	s_waitcnt lgkmcnt(0)
	v_mfma_f32_32x32x16_bf16 v[64:79], v[166:169], v[134:137], v[64:79]
	v_permlane32_swap_b32_e32 v109, v111
	v_add_co_u32_e32 v166, vcc, s23, v178
	s_nop 1
	v_addc_co_u32_e32 v167, vcc, -1, v179, vcc
	v_add_co_u32_e32 v170, vcc, s24, v178
	s_nop 1
	v_addc_co_u32_e32 v171, vcc, -1, v179, vcc
	global_load_dwordx4 v[162:165], v[166:167], off
	s_nop 0
	global_load_dwordx4 v[166:169], v[166:167], off offset:-512
	s_nop 0
	global_load_dwordx4 v[174:177], v[170:171], off
	s_nop 0
	global_load_dwordx4 v[170:173], v[170:171], off offset:-512
	ds_read_b64_tr_b16 v[180:181], v206 offset:0x8000
	ds_read_b64_tr_b16 v[182:183], v206 offset:0x8800
	ds_read_b64_tr_b16 v[184:185], v206 offset:0x9000
	ds_read_b64_tr_b16 v[186:187], v206 offset:0x9800
	ds_read_b64_tr_b16 v[216:217], v206 offset:0xa000
	ds_read_b64_tr_b16 v[218:219], v206 offset:0xa800
	ds_read_b64_tr_b16 v[220:221], v206 offset:0xb000
	ds_read_b64_tr_b16 v[222:223], v206 offset:0xb800
	s_waitcnt lgkmcnt(0)
	s_waitcnt vmcnt(4)
; __device__ __forceinline__ void partialSM(f32x16& p0, f32x16& p1, float& m_reg, float& mn, float& alpha) {
;     ...
;   for (int r = 0; r < 16; ++r) p0[r] = __builtin_amdgcn_exp2f(p0[r]);
; }
; __device__ __forceinline__ void partialSM_fixed(f32x16& p0) {
;   for (int r = 0; r < 16; ++r) p0[r] = __builtin_amdgcn_exp2f(p0[r]);
; }
; __device__ __forceinline__ void finishSM(f32x16& p0, f32x16& p1, float alpha, float& l_reg, bf16x8& pa0, bf16x8& pa1, bf16x8& pa2, bf16x8& pa3) {
;   for (int r = 0; r < 16; ++r) p1[r] = __builtin_amdgcn_exp2f(p1[r]);
;   float ps = 0; for (int r = 0; r < 16; ++r) ps += p0[r]; for (int r = 0; r < 16; ++r) ps += p1[r];
; template <int BOFF> __device__ __forceinline__ void qkt_i(f32x16& p0, f32x16& p1, const int (&kb)[4], const bf16x8* qr) {
;   p0 = f32x16{}; p1 = f32x16{};
; #pragma unroll
;   for (int d0 = 0; d0 < 8; ++d0) { const int off = BOFF + (d0 >> 2) * 128;
;     const bf16x8 b0 = LDSV(kb[d0 & 3] + off), b1 = LDSV(kb[d0 & 3] + off + 8192);
;     p0 = __builtin_amdgcn_mfma_f32_32x32x16_bf16(b0, qr[d0], p0, 0, 0, 0);
;     p1 = __builtin_amdgcn_mfma_f32_32x32x16_bf16(b1, qr[d0], p1, 0, 0, 0); }
; }
; template <int D0, int BOFF> __device__ __forceinline__ void pv_one_i(f32x16& od, int vb, bf16x8 pa0, bf16x8 pa1, bf16x8 pa2, bf16x8 pa3) {
;   const s16x4 l0 = tr_read<BOFF + v_rd_off(D0, 0, 0)>(vb), h0 = tr_read<BOFF + v_rd_off(D0, 0, 1)>(vb), l1 = tr_read<BOFF + v_rd_off(D0, 1, 0)>(vb), h1 = tr_read<BOFF + v_rd_off(D0, 1, 1)>(vb);
;   const s16x4 l2 = tr_read<BOFF + v_rd_off(D0, 2, 0)>(vb), h2 = tr_read<BOFF + v_rd_off(D0, 2, 1)>(vb), l3 = tr_read<BOFF + v_rd_off(D0, 3, 0)>(vb), h3 = tr_read<BOFF + v_rd_off(D0, 3, 1)>(vb);
;   asm volatile("s_waitcnt lgkmcnt(0)" ::: "memory"); SBAR();
;     ...
;   od = __builtin_amdgcn_mfma_f32_32x32x16_bf16(pa0, PK(l0, h0), od, 0, 0, 0);
;   od = __builtin_amdgcn_mfma_f32_32x32x16_bf16(pa1, PK(l1, h1), od, 0, 0, 0);
;   od = __builtin_amdgcn_mfma_f32_32x32x16_bf16(pa2, PK(l2, h2), od, 0, 0, 0);
;   od = __builtin_amdgcn_mfma_f32_32x32x16_bf16(pa3, PK(l3, h3), od, 0, 0, 0);
;     ...
; }
; template <int BOFF> __device__ __forceinline__ void pv_i(f32x16* o, int vb, bf16x8 pa0, bf16x8 pa1, bf16x8 pa2, bf16x8 pa3) {
;   pv_one_i<0, BOFF>(o[0], vb, pa0, pa1, pa2, pa3); pv_one_i<1, BOFF>(o[1], vb, pa0, pa1, pa2, pa3); pv_one_i<2, BOFF>(o[2], vb, pa0, pa1, pa2, pa3); pv_one_i<3, BOFF>(o[3], vb, pa0, pa1, pa2, pa3);
; }
	ds_write_b128 v211, v[146:149] offset:16384
	s_nop 0
	v_mfma_f32_32x32x16_bf16 v[0:15], v[96:99], v[180:183], v[0:15]
	ds_read_b64_tr_b16 v[180:181], v206 offset:0x8200
	ds_read_b64_tr_b16 v[182:183], v206 offset:0x8a00
	v_mfma_f32_32x32x16_bf16 v[0:15], v[100:103], v[184:187], v[0:15]
	ds_read_b64_tr_b16 v[184:185], v206 offset:0x9200
	ds_read_b64_tr_b16 v[186:187], v206 offset:0x9a00
	v_mfma_f32_32x32x16_bf16 v[0:15], v[104:107], v[216:219], v[0:15]
	ds_read_b64_tr_b16 v[216:217], v206 offset:0xa200
	ds_read_b64_tr_b16 v[218:219], v206 offset:0xaa00
	v_mfma_f32_32x32x16_bf16 v[0:15], v[108:111], v[220:223], v[0:15]
	ds_read_b64_tr_b16 v[220:221], v206 offset:0xb200
	ds_read_b64_tr_b16 v[222:223], v206 offset:0xba00
	s_waitcnt lgkmcnt(0)
	ds_write_b128 v212, v[158:161] offset:16384
	v_mfma_f32_32x32x16_bf16 v[16:31], v[96:99], v[180:183], v[16:31]
	ds_read_b64_tr_b16 v[180:181], v206 offset:0x8400
	ds_read_b64_tr_b16 v[182:183], v206 offset:0x8c00
	v_mfma_f32_32x32x16_bf16 v[16:31], v[100:103], v[184:187], v[16:31]
	ds_read_b64_tr_b16 v[184:185], v206 offset:0x9400
	ds_read_b64_tr_b16 v[186:187], v206 offset:0x9c00
	v_mfma_f32_32x32x16_bf16 v[16:31], v[104:107], v[216:219], v[16:31]
	ds_read_b64_tr_b16 v[216:217], v206 offset:0xa400
	ds_read_b64_tr_b16 v[218:219], v206 offset:0xac00
	v_mfma_f32_32x32x16_bf16 v[16:31], v[108:111], v[220:223], v[16:31]
	ds_read_b64_tr_b16 v[220:221], v206 offset:0xb400
	ds_read_b64_tr_b16 v[222:223], v206 offset:0xbc00
	s_waitcnt lgkmcnt(0)
	ds_write_b128 v213, v[150:153] offset:16384
	v_mfma_f32_32x32x16_bf16 v[32:47], v[96:99], v[180:183], v[32:47]
	ds_read_b64_tr_b16 v[180:181], v206 offset:0x8600
	ds_read_b64_tr_b16 v[182:183], v206 offset:0x8e00
	v_mfma_f32_32x32x16_bf16 v[32:47], v[100:103], v[184:187], v[32:47]
	ds_read_b64_tr_b16 v[184:185], v206 offset:0x9600
	ds_read_b64_tr_b16 v[186:187], v206 offset:0x9e00
	v_mfma_f32_32x32x16_bf16 v[32:47], v[104:107], v[216:219], v[32:47]
	ds_read_b64_tr_b16 v[216:217], v206 offset:0xa600
	ds_read_b64_tr_b16 v[218:219], v206 offset:0xae00
	v_mfma_f32_32x32x16_bf16 v[32:47], v[108:111], v[220:223], v[32:47]
	ds_read_b64_tr_b16 v[220:221], v206 offset:0xb600
	ds_read_b64_tr_b16 v[222:223], v206 offset:0xbe00
	s_waitcnt lgkmcnt(0)
	ds_write_b128 v214, v[154:157] offset:16384
	v_mfma_f32_32x32x16_bf16 v[48:63], v[96:99], v[180:183], v[48:63]
	v_exp_f32_e32 v215, v92
	s_waitcnt vmcnt(4)
	v_exp_f32_e32 v181, v80
	v_exp_f32_e32 v183, v81
	v_exp_f32_e32 v188, v86
	v_exp_f32_e32 v189, v87
	v_exp_f32_e32 v196, v88
	v_mfma_f32_32x32x16_bf16 v[48:63], v[100:103], v[184:187], v[48:63]
	v_exp_f32_e32 v184, v82
	v_exp_f32_e32 v185, v83
	v_exp_f32_e32 v186, v84
	v_exp_f32_e32 v187, v85
	v_exp_f32_e32 v197, v89
	v_exp_f32_e32 v198, v90
	v_exp_f32_e32 v199, v91
	v_mfma_f32_32x32x16_bf16 v[48:63], v[104:107], v[216:219], v[48:63]
	v_exp_f32_e32 v216, v93
	v_exp_f32_e32 v217, v94
	v_exp_f32_e32 v218, v95
	s_waitcnt lgkmcnt(0)
	s_barrier
	v_mfma_f32_32x32x16_bf16 v[48:63], v[108:111], v[220:223], v[48:63]
	ds_read_b128 v[80:83], v207 offset:16384
	ds_read_b128 v[96:99], v207 offset:24576
	ds_read_b128 v[146:149], v208 offset:16384
	ds_read_b128 v[150:153], v208 offset:24576
	v_exp_f32_e32 v154, v72
	v_exp_f32_e32 v155, v73
	v_exp_f32_e32 v156, v74
	v_exp_f32_e32 v157, v75
	v_exp_f32_e32 v158, v76
	v_exp_f32_e32 v159, v77
	v_exp_f32_e32 v160, v78
	v_exp_f32_e32 v79, v79
	s_waitcnt lgkmcnt(3)
	v_mfma_f32_32x32x16_bf16 v[80:95], v[80:83], v[142:145], 0
	v_exp_f32_e32 v236, v64
	v_add_f32_e32 v64, 0, v181
	v_add_f32_e32 v64, v183, v64
	v_add_f32_e32 v64, v184, v64
	s_waitcnt lgkmcnt(2)
	v_mfma_f32_32x32x16_bf16 v[96:111], v[96:99], v[142:145], 0
	v_add_f32_e32 v64, v185, v64
	v_add_f32_e32 v64, v186, v64
	v_add_f32_e32 v64, v187, v64
	s_waitcnt lgkmcnt(1)
	v_mfma_f32_32x32x16_bf16 v[80:95], v[146:149], v[138:141], v[80:95]
	v_add_f32_e32 v64, v188, v64
	v_add_f32_e32 v64, v189, v64
	v_add_f32_e32 v64, v196, v64
	s_waitcnt lgkmcnt(0)
	v_mfma_f32_32x32x16_bf16 v[96:111], v[150:153], v[138:141], v[96:111]
	ds_read_b128 v[146:149], v209 offset:16384
	ds_read_b128 v[150:153], v209 offset:24576
	v_add_f32_e32 v64, v197, v64
	v_add_f32_e32 v64, v198, v64
	v_add_f32_e32 v64, v199, v64
	v_add_f32_e32 v64, v215, v64
	v_exp_f32_e32 v237, v65
	s_waitcnt lgkmcnt(1)
	v_mfma_f32_32x32x16_bf16 v[80:95], v[146:149], v[112:115], v[80:95]
	v_add_f32_e32 v64, v216, v64
	v_exp_f32_e32 v238, v66
	v_add_f32_e32 v64, v217, v64
	v_exp_f32_e32 v239, v67
	s_waitcnt lgkmcnt(0)
	v_mfma_f32_32x32x16_bf16 v[96:111], v[150:153], v[112:115], v[96:111]
	ds_read_b128 v[146:149], v210 offset:16384
	ds_read_b128 v[150:153], v210 offset:24576
	v_add_f32_e32 v64, v218, v64
	v_exp_f32_e32 v247, v68
	v_add_f32_e32 v64, v236, v64
	v_exp_f32_e32 v248, v69
	s_waitcnt lgkmcnt(1)
	v_mfma_f32_32x32x16_bf16 v[80:95], v[146:149], v[116:119], v[80:95]
	v_add_f32_e32 v64, v237, v64
	v_exp_f32_e32 v249, v70
	v_add_f32_e32 v64, v238, v64
	v_exp_f32_e32 v252, v71
	s_waitcnt lgkmcnt(0)
	v_mfma_f32_32x32x16_bf16 v[96:111], v[150:153], v[116:119], v[96:111]
	ds_read_b128 v[146:149], v190 offset:16384
	ds_read_b128 v[150:153], v190 offset:24576
	v_add_f32_e32 v64, v239, v64
	v_add_f32_e32 v64, v247, v64
	v_add_f32_e32 v64, v248, v64
	v_add_f32_e32 v64, v249, v64
	v_add_f32_e32 v64, v252, v64
	v_add_f32_e32 v64, v154, v64
	s_waitcnt lgkmcnt(1)
	v_mfma_f32_32x32x16_bf16 v[80:95], v[146:149], v[120:123], v[80:95]
	v_add_f32_e32 v64, v155, v64
	v_add_f32_e32 v64, v156, v64
	v_add_f32_e32 v64, v157, v64
	v_add_f32_e32 v64, v158, v64
	v_add_f32_e32 v64, v159, v64
	s_waitcnt lgkmcnt(0)
; #define SBAR() __builtin_amdgcn_sched_barrier(0)
; __device__ __forceinline__ void finishSM(f32x16& p0, f32x16& p1, float alpha, float& l_reg, bf16x8& pa0, bf16x8& pa1, bf16x8& pa2, bf16x8& pa3) {
;   for (int r = 0; r < 16; ++r) p1[r] = __builtin_amdgcn_exp2f(p1[r]);
;   float ps = 0; for (int r = 0; r < 16; ++r) ps += p0[r]; for (int r = 0; r < 16; ++r) ps += p1[r];
;   { auto rr = __builtin_amdgcn_permlane32_swap(__float_as_uint(ps), __float_as_uint(ps), false, false);
;     ps = __uint_as_float(rr[0]) + __uint_as_float(rr[1]); }
;   l_reg = l_reg * alpha + ps;
;     ...
;   PK4(p0, 0, pa0); PK4(p0, 8, pa1); PK4(p1, 0, pa2); PK4(p1, 8, pa3);
;     ...
; }
; template <int BOFF> __device__ __forceinline__ void qkt_i(f32x16& p0, f32x16& p1, const int (&kb)[4], const bf16x8* qr) {
;   p0 = f32x16{}; p1 = f32x16{};
; #pragma unroll
;   for (int d0 = 0; d0 < 8; ++d0) { const int off = BOFF + (d0 >> 2) * 128;
;     const bf16x8 b0 = LDSV(kb[d0 & 3] + off), b1 = LDSV(kb[d0 & 3] + off + 8192);
;     p0 = __builtin_amdgcn_mfma_f32_32x32x16_bf16(b0, qr[d0], p0, 0, 0, 0);
;     p1 = __builtin_amdgcn_mfma_f32_32x32x16_bf16(b1, qr[d0], p1, 0, 0, 0); }
; }
; template <int D0, int BOFF> __device__ __forceinline__ void pv_one_i(f32x16& od, int vb, bf16x8 pa0, bf16x8 pa1, bf16x8 pa2, bf16x8 pa3) {
;   const s16x4 l0 = tr_read<BOFF + v_rd_off(D0, 0, 0)>(vb), h0 = tr_read<BOFF + v_rd_off(D0, 0, 1)>(vb), l1 = tr_read<BOFF + v_rd_off(D0, 1, 0)>(vb), h1 = tr_read<BOFF + v_rd_off(D0, 1, 1)>(vb);
;   const s16x4 l2 = tr_read<BOFF + v_rd_off(D0, 2, 0)>(vb), h2 = tr_read<BOFF + v_rd_off(D0, 2, 1)>(vb), l3 = tr_read<BOFF + v_rd_off(D0, 3, 0)>(vb), h3 = tr_read<BOFF + v_rd_off(D0, 3, 1)>(vb);
;   asm volatile("s_waitcnt lgkmcnt(0)" ::: "memory"); SBAR();
;     ...
;   od = __builtin_amdgcn_mfma_f32_32x32x16_bf16(pa0, PK(l0, h0), od, 0, 0, 0);
;   od = __builtin_amdgcn_mfma_f32_32x32x16_bf16(pa1, PK(l1, h1), od, 0, 0, 0);
;   od = __builtin_amdgcn_mfma_f32_32x32x16_bf16(pa2, PK(l2, h2), od, 0, 0, 0);
;   od = __builtin_amdgcn_mfma_f32_32x32x16_bf16(pa3, PK(l3, h3), od, 0, 0, 0);
;     ...
; }
; template <int BOFF> __device__ __forceinline__ void pv_i(f32x16* o, int vb, bf16x8 pa0, bf16x8 pa1, bf16x8 pa2, bf16x8 pa3) {
;   pv_one_i<0, BOFF>(o[0], vb, pa0, pa1, pa2, pa3); pv_one_i<1, BOFF>(o[1], vb, pa0, pa1, pa2, pa3); pv_one_i<2, BOFF>(o[2], vb, pa0, pa1, pa2, pa3); pv_one_i<3, BOFF>(o[3], vb, pa0, pa1, pa2, pa3);
; }
	v_mfma_f32_32x32x16_bf16 v[96:111], v[150:153], v[120:123], v[96:111]
	ds_read_b128 v[146:149], v191 offset:16384
	ds_read_b128 v[150:153], v191 offset:24576
	v_add_f32_e32 v64, v160, v64
	v_add_f32_e32 v180, v79, v64
	v_cvt_pk_bf16_f32 v64, v181, v183
	v_cvt_pk_bf16_f32 v65, v184, v185
	v_cvt_pk_bf16_f32 v66, v186, v187
	v_cvt_pk_bf16_f32 v67, v188, v189
	s_waitcnt lgkmcnt(1)
	v_mfma_f32_32x32x16_bf16 v[80:95], v[146:149], v[124:127], v[80:95]
	v_cvt_pk_bf16_f32 v68, v196, v197
	v_cvt_pk_bf16_f32 v69, v198, v199
	v_cvt_pk_bf16_f32 v70, v215, v216
	v_cvt_pk_bf16_f32 v71, v217, v218
	v_cvt_pk_bf16_f32 v72, v236, v237
	s_waitcnt lgkmcnt(0)
	v_mfma_f32_32x32x16_bf16 v[96:111], v[150:153], v[124:127], v[96:111]
	ds_read_b128 v[146:149], v192 offset:16384
	ds_read_b128 v[150:153], v192 offset:24576
	v_cvt_pk_bf16_f32 v73, v238, v239
	v_cvt_pk_bf16_f32 v74, v247, v248
	v_cvt_pk_bf16_f32 v75, v249, v252
	v_cvt_pk_bf16_f32 v76, v154, v155
	v_cvt_pk_bf16_f32 v77, v156, v157
	v_cvt_pk_bf16_f32 v78, v158, v159
	s_waitcnt lgkmcnt(1)
	v_mfma_f32_32x32x16_bf16 v[80:95], v[146:149], v[130:133], v[80:95]
	v_cvt_pk_bf16_f32 v79, v160, v79
	v_mov_b32_e32 v182, v180
	v_permlane32_swap_b32_e32 v64, v66
	v_permlane32_swap_b32_e32 v65, v67
	v_permlane32_swap_b32_e32 v68, v70
	s_waitcnt lgkmcnt(0)
	v_mfma_f32_32x32x16_bf16 v[96:111], v[150:153], v[130:133], v[96:111]
	ds_read_b128 v[146:149], v193 offset:16384
	ds_read_b128 v[150:153], v193 offset:24576
	v_permlane32_swap_b32_e32 v69, v71
	v_permlane32_swap_b32_e32 v72, v74
	v_permlane32_swap_b32_e32 v73, v75
	v_permlane32_swap_b32_e32 v76, v78
	v_permlane32_swap_b32_e32 v77, v79
	v_permlane32_swap_b32_e32 v180, v182
	s_waitcnt lgkmcnt(1)
	v_mfma_f32_32x32x16_bf16 v[80:95], v[146:149], v[134:137], v[80:95]
	s_waitcnt lgkmcnt(0)
	v_mfma_f32_32x32x16_bf16 v[96:111], v[150:153], v[134:137], v[96:111]
	v_add_co_u32_e32 v150, vcc, s25, v178
	s_nop 1
	v_addc_co_u32_e32 v151, vcc, -1, v179, vcc
	v_add_co_u32_e32 v154, vcc, s45, v178
	s_nop 1
	v_addc_co_u32_e32 v155, vcc, -1, v179, vcc
	global_load_dwordx4 v[146:149], v[150:151], off
	s_nop 0
	global_load_dwordx4 v[150:153], v[150:151], off offset:-512
	s_nop 0
	global_load_dwordx4 v[158:161], v[154:155], off
	s_nop 0
	global_load_dwordx4 v[154:157], v[154:155], off offset:-512
	ds_read_b64_tr_b16 v[184:185], v206 offset:0
	ds_read_b64_tr_b16 v[186:187], v206 offset:0x800
	ds_read_b64_tr_b16 v[216:217], v206 offset:0x1000
	ds_read_b64_tr_b16 v[218:219], v206 offset:0x1800
	ds_read_b64_tr_b16 v[220:221], v206 offset:0x2000
	ds_read_b64_tr_b16 v[222:223], v206 offset:0x2800
	ds_read_b64_tr_b16 v[224:225], v206 offset:0x3000
	ds_read_b64_tr_b16 v[226:227], v206 offset:0x3800
	s_waitcnt lgkmcnt(0)
	s_waitcnt vmcnt(4)
	ds_write_b128 v211, v[162:165] offset:32768
	s_nop 0
	v_mfma_f32_32x32x16_bf16 v[0:15], v[64:67], v[184:187], v[0:15]
	ds_read_b64_tr_b16 v[184:185], v206 offset:0x200
	ds_read_b64_tr_b16 v[186:187], v206 offset:0xa00
	v_mfma_f32_32x32x16_bf16 v[0:15], v[68:71], v[216:219], v[0:15]
	ds_read_b64_tr_b16 v[216:217], v206 offset:0x1200
	ds_read_b64_tr_b16 v[218:219], v206 offset:0x1a00
	v_mfma_f32_32x32x16_bf16 v[0:15], v[72:75], v[220:223], v[0:15]
	ds_read_b64_tr_b16 v[220:221], v206 offset:0x2200
	ds_read_b64_tr_b16 v[222:223], v206 offset:0x2a00
	v_mfma_f32_32x32x16_bf16 v[0:15], v[76:79], v[224:227], v[0:15]
	ds_read_b64_tr_b16 v[224:225], v206 offset:0x3200
	ds_read_b64_tr_b16 v[226:227], v206 offset:0x3a00
	s_waitcnt lgkmcnt(0)
	ds_write_b128 v212, v[174:177] offset:32768
	v_mfma_f32_32x32x16_bf16 v[16:31], v[64:67], v[184:187], v[16:31]
	ds_read_b64_tr_b16 v[184:185], v206 offset:0x400
	ds_read_b64_tr_b16 v[186:187], v206 offset:0xc00
	v_mfma_f32_32x32x16_bf16 v[16:31], v[68:71], v[216:219], v[16:31]
	ds_read_b64_tr_b16 v[216:217], v206 offset:0x1400
	ds_read_b64_tr_b16 v[218:219], v206 offset:0x1c00
	v_mfma_f32_32x32x16_bf16 v[16:31], v[72:75], v[220:223], v[16:31]
	ds_read_b64_tr_b16 v[220:221], v206 offset:0x2400
	ds_read_b64_tr_b16 v[222:223], v206 offset:0x2c00
	v_mfma_f32_32x32x16_bf16 v[16:31], v[76:79], v[224:227], v[16:31]
	ds_read_b64_tr_b16 v[224:225], v206 offset:0x3400
	ds_read_b64_tr_b16 v[226:227], v206 offset:0x3c00
	s_waitcnt lgkmcnt(0)
	ds_write_b128 v213, v[166:169] offset:32768
	v_mfma_f32_32x32x16_bf16 v[32:47], v[64:67], v[184:187], v[32:47]
	ds_read_b64_tr_b16 v[184:185], v206 offset:0x600
	ds_read_b64_tr_b16 v[186:187], v206 offset:0xe00
	v_mfma_f32_32x32x16_bf16 v[32:47], v[68:71], v[216:219], v[32:47]
	ds_read_b64_tr_b16 v[216:217], v206 offset:0x1600
	ds_read_b64_tr_b16 v[218:219], v206 offset:0x1e00
	v_mfma_f32_32x32x16_bf16 v[32:47], v[72:75], v[220:223], v[32:47]
	ds_read_b64_tr_b16 v[220:221], v206 offset:0x2600
	ds_read_b64_tr_b16 v[222:223], v206 offset:0x2e00
	v_mfma_f32_32x32x16_bf16 v[32:47], v[76:79], v[224:227], v[32:47]
	ds_read_b64_tr_b16 v[224:225], v206 offset:0x3600
	ds_read_b64_tr_b16 v[226:227], v206 offset:0x3e00
	s_waitcnt lgkmcnt(0)
	ds_write_b128 v214, v[170:173] offset:32768
	v_mfma_f32_32x32x16_bf16 v[48:63], v[64:67], v[184:187], v[48:63]
	v_exp_f32_e32 v215, v90
	s_waitcnt vmcnt(4)
	v_exp_f32_e32 v184, v80
	v_exp_f32_e32 v185, v81
	v_exp_f32_e32 v186, v82
	v_exp_f32_e32 v187, v83
	v_exp_f32_e32 v188, v84
	v_mfma_f32_32x32x16_bf16 v[48:63], v[68:71], v[216:219], v[48:63]
	v_exp_f32_e32 v219, v94
	v_exp_f32_e32 v189, v85
	v_exp_f32_e32 v196, v86
	v_exp_f32_e32 v197, v87
	v_exp_f32_e32 v198, v88
	v_exp_f32_e32 v199, v89
	v_exp_f32_e32 v216, v91
	v_mfma_f32_32x32x16_bf16 v[48:63], v[72:75], v[220:223], v[48:63]
	v_exp_f32_e32 v220, v95
	v_exp_f32_e32 v217, v92
	v_exp_f32_e32 v218, v93
	s_waitcnt lgkmcnt(0)
	s_barrier
; #define SBAR() __builtin_amdgcn_sched_barrier(0)
; __device__ __forceinline__ void finishSM(f32x16& p0, f32x16& p1, float alpha, float& l_reg, bf16x8& pa0, bf16x8& pa1, bf16x8& pa2, bf16x8& pa3) {
;   for (int r = 0; r < 16; ++r) p1[r] = __builtin_amdgcn_exp2f(p1[r]);
;   float ps = 0; for (int r = 0; r < 16; ++r) ps += p0[r]; for (int r = 0; r < 16; ++r) ps += p1[r];
;   { auto rr = __builtin_amdgcn_permlane32_swap(__float_as_uint(ps), __float_as_uint(ps), false, false);
;     ps = __uint_as_float(rr[0]) + __uint_as_float(rr[1]); }
;   l_reg = l_reg * alpha + ps;
;     ...
;   PK4(p0, 0, pa0); PK4(p0, 8, pa1); PK4(p1, 0, pa2); PK4(p1, 8, pa3);
;     ...
; }
; template <int BOFF> __device__ __forceinline__ void qkt_i(f32x16& p0, f32x16& p1, const int (&kb)[4], const bf16x8* qr) {
;   p0 = f32x16{}; p1 = f32x16{};
; #pragma unroll
;   for (int d0 = 0; d0 < 8; ++d0) { const int off = BOFF + (d0 >> 2) * 128;
;     const bf16x8 b0 = LDSV(kb[d0 & 3] + off), b1 = LDSV(kb[d0 & 3] + off + 8192);
;     p0 = __builtin_amdgcn_mfma_f32_32x32x16_bf16(b0, qr[d0], p0, 0, 0, 0);
;     p1 = __builtin_amdgcn_mfma_f32_32x32x16_bf16(b1, qr[d0], p1, 0, 0, 0); }
; }
; template <int D0, int BOFF> __device__ __forceinline__ void pv_one_i(f32x16& od, int vb, bf16x8 pa0, bf16x8 pa1, bf16x8 pa2, bf16x8 pa3) {
;   const s16x4 l0 = tr_read<BOFF + v_rd_off(D0, 0, 0)>(vb), h0 = tr_read<BOFF + v_rd_off(D0, 0, 1)>(vb), l1 = tr_read<BOFF + v_rd_off(D0, 1, 0)>(vb), h1 = tr_read<BOFF + v_rd_off(D0, 1, 1)>(vb);
;   const s16x4 l2 = tr_read<BOFF + v_rd_off(D0, 2, 0)>(vb), h2 = tr_read<BOFF + v_rd_off(D0, 2, 1)>(vb), l3 = tr_read<BOFF + v_rd_off(D0, 3, 0)>(vb), h3 = tr_read<BOFF + v_rd_off(D0, 3, 1)>(vb);
;   asm volatile("s_waitcnt lgkmcnt(0)" ::: "memory"); SBAR();
;     ...
;   od = __builtin_amdgcn_mfma_f32_32x32x16_bf16(pa0, PK(l0, h0), od, 0, 0, 0);
;   od = __builtin_amdgcn_mfma_f32_32x32x16_bf16(pa1, PK(l1, h1), od, 0, 0, 0);
;   od = __builtin_amdgcn_mfma_f32_32x32x16_bf16(pa2, PK(l2, h2), od, 0, 0, 0);
;   od = __builtin_amdgcn_mfma_f32_32x32x16_bf16(pa3, PK(l3, h3), od, 0, 0, 0);
;     ...
; }
; template <int BOFF> __device__ __forceinline__ void pv_i(f32x16* o, int vb, bf16x8 pa0, bf16x8 pa1, bf16x8 pa2, bf16x8 pa3) {
;   pv_one_i<0, BOFF>(o[0], vb, pa0, pa1, pa2, pa3); pv_one_i<1, BOFF>(o[1], vb, pa0, pa1, pa2, pa3); pv_one_i<2, BOFF>(o[2], vb, pa0, pa1, pa2, pa3); pv_one_i<3, BOFF>(o[3], vb, pa0, pa1, pa2, pa3);
; }
	v_mfma_f32_32x32x16_bf16 v[48:63], v[76:79], v[224:227], v[48:63]
	ds_read_b128 v[64:67], v207 offset:32768
	ds_read_b128 v[80:83], v207 offset:40960
	ds_read_b128 v[162:165], v208 offset:32768
	ds_read_b128 v[166:169], v208 offset:40960
	v_exp_f32_e32 v170, v104
	v_exp_f32_e32 v171, v105
	v_exp_f32_e32 v172, v106
	v_exp_f32_e32 v173, v107
	v_exp_f32_e32 v174, v108
	v_exp_f32_e32 v175, v109
	v_exp_f32_e32 v176, v110
	v_exp_f32_e32 v111, v111
	s_waitcnt lgkmcnt(3)
	v_mfma_f32_32x32x16_bf16 v[64:79], v[64:67], v[142:145], 0
	v_exp_f32_e32 v236, v96
	v_add_f32_e32 v96, 0, v184
	v_add_f32_e32 v96, v185, v96
	v_add_f32_e32 v96, v186, v96
	s_waitcnt lgkmcnt(2)
	v_mfma_f32_32x32x16_bf16 v[80:95], v[80:83], v[142:145], 0
	v_add_f32_e32 v96, v187, v96
	v_add_f32_e32 v96, v188, v96
	v_add_f32_e32 v96, v189, v96
	s_waitcnt lgkmcnt(1)
	v_mfma_f32_32x32x16_bf16 v[64:79], v[162:165], v[138:141], v[64:79]
	v_add_f32_e32 v96, v196, v96
	v_add_f32_e32 v96, v197, v96
	v_add_f32_e32 v96, v198, v96
	s_waitcnt lgkmcnt(0)
	v_mfma_f32_32x32x16_bf16 v[80:95], v[166:169], v[138:141], v[80:95]
	ds_read_b128 v[162:165], v209 offset:32768
	ds_read_b128 v[166:169], v209 offset:40960
	v_add_f32_e32 v96, v199, v96
	v_add_f32_e32 v96, v215, v96
	v_add_f32_e32 v96, v216, v96
	v_add_f32_e32 v96, v217, v96
	v_exp_f32_e32 v237, v97
	s_waitcnt lgkmcnt(1)
	v_mfma_f32_32x32x16_bf16 v[64:79], v[162:165], v[112:115], v[64:79]
	v_add_f32_e32 v96, v218, v96
	v_exp_f32_e32 v238, v98
	v_add_f32_e32 v96, v219, v96
	v_exp_f32_e32 v239, v99
	s_waitcnt lgkmcnt(0)
	v_mfma_f32_32x32x16_bf16 v[80:95], v[166:169], v[112:115], v[80:95]
	ds_read_b128 v[162:165], v210 offset:32768
	ds_read_b128 v[166:169], v210 offset:40960
	v_add_f32_e32 v96, v220, v96
	v_exp_f32_e32 v247, v100
	v_add_f32_e32 v96, v236, v96
	v_exp_f32_e32 v248, v101
	s_waitcnt lgkmcnt(1)
	v_mfma_f32_32x32x16_bf16 v[64:79], v[162:165], v[116:119], v[64:79]
	v_add_f32_e32 v96, v237, v96
	v_exp_f32_e32 v249, v102
	v_add_f32_e32 v96, v238, v96
	v_exp_f32_e32 v252, v103
	s_waitcnt lgkmcnt(0)
	v_mfma_f32_32x32x16_bf16 v[80:95], v[166:169], v[116:119], v[80:95]
	ds_read_b128 v[162:165], v190 offset:32768
	ds_read_b128 v[166:169], v190 offset:40960
	v_add_f32_e32 v96, v239, v96
	v_add_f32_e32 v96, v247, v96
	v_add_f32_e32 v96, v248, v96
	v_add_f32_e32 v96, v249, v96
	v_add_f32_e32 v96, v252, v96
	v_add_f32_e32 v96, v170, v96
	s_waitcnt lgkmcnt(1)
	v_mfma_f32_32x32x16_bf16 v[64:79], v[162:165], v[120:123], v[64:79]
	v_add_f32_e32 v96, v171, v96
	v_add_f32_e32 v96, v172, v96
	v_add_f32_e32 v96, v173, v96
	v_add_f32_e32 v96, v174, v96
	v_add_f32_e32 v96, v175, v96
	s_waitcnt lgkmcnt(0)
	v_mfma_f32_32x32x16_bf16 v[80:95], v[166:169], v[120:123], v[80:95]
	ds_read_b128 v[162:165], v191 offset:32768
	ds_read_b128 v[166:169], v191 offset:40960
	v_add_f32_e32 v96, v176, v96
	v_add_f32_e32 v181, v111, v96
	v_mov_b32_e32 v183, v181
	s_nop 1
	v_permlane32_swap_b32_e32 v181, v183
	v_pk_add_f32 v[96:97], v[180:181], v[182:183]
	s_waitcnt lgkmcnt(1)
	v_mfma_f32_32x32x16_bf16 v[64:79], v[162:165], v[124:127], v[64:79]
	s_nop 0
	v_add_f32_e32 v96, v128, v96
	v_add_f32_e32 v128, v96, v97
	v_cvt_pk_bf16_f32 v96, v184, v185
	v_cvt_pk_bf16_f32 v97, v186, v187
	s_waitcnt lgkmcnt(0)
	v_mfma_f32_32x32x16_bf16 v[80:95], v[166:169], v[124:127], v[80:95]
	ds_read_b128 v[162:165], v192 offset:32768
	ds_read_b128 v[166:169], v192 offset:40960
	v_cvt_pk_bf16_f32 v98, v188, v189
	v_cvt_pk_bf16_f32 v99, v196, v197
	v_cvt_pk_bf16_f32 v100, v198, v199
	v_cvt_pk_bf16_f32 v101, v215, v216
	v_cvt_pk_bf16_f32 v102, v217, v218
	v_cvt_pk_bf16_f32 v103, v219, v220
	s_waitcnt lgkmcnt(1)
	v_mfma_f32_32x32x16_bf16 v[64:79], v[162:165], v[130:133], v[64:79]
	v_cvt_pk_bf16_f32 v104, v236, v237
	v_cvt_pk_bf16_f32 v105, v238, v239
	v_cvt_pk_bf16_f32 v106, v247, v248
	v_cvt_pk_bf16_f32 v107, v249, v252
	v_cvt_pk_bf16_f32 v108, v170, v171
	s_waitcnt lgkmcnt(0)
	v_mfma_f32_32x32x16_bf16 v[80:95], v[166:169], v[130:133], v[80:95]
	ds_read_b128 v[162:165], v193 offset:32768
	ds_read_b128 v[166:169], v193 offset:40960
	v_cvt_pk_bf16_f32 v109, v172, v173
	v_cvt_pk_bf16_f32 v110, v174, v175
	v_cvt_pk_bf16_f32 v111, v176, v111
	s_nop 0
	v_permlane32_swap_b32_e32 v96, v98
	v_permlane32_swap_b32_e32 v97, v99
	s_waitcnt lgkmcnt(1)
	v_mfma_f32_32x32x16_bf16 v[64:79], v[162:165], v[134:137], v[64:79]
	v_permlane32_swap_b32_e32 v100, v102
	v_permlane32_swap_b32_e32 v101, v103
	v_permlane32_swap_b32_e32 v104, v106
	v_permlane32_swap_b32_e32 v105, v107
	v_permlane32_swap_b32_e32 v108, v110
	s_waitcnt lgkmcnt(0)
	v_mfma_f32_32x32x16_bf16 v[80:95], v[166:169], v[134:137], v[80:95]
	v_permlane32_swap_b32_e32 v109, v111
	v_add_co_u32_e32 v166, vcc, s52, v178
	s_nop 1
	v_addc_co_u32_e32 v167, vcc, -1, v179, vcc
	v_add_co_u32_e32 v170, vcc, s53, v178
	s_nop 1
	v_addc_co_u32_e32 v171, vcc, -1, v179, vcc
	global_load_dwordx4 v[162:165], v[166:167], off
	s_nop 0
	global_load_dwordx4 v[166:169], v[166:167], off offset:-512
	s_nop 0
	global_load_dwordx4 v[174:177], v[170:171], off
	s_nop 0
	global_load_dwordx4 v[170:173], v[170:171], off offset:-512
	ds_read_b64_tr_b16 v[180:181], v206 offset:0x4000
	ds_read_b64_tr_b16 v[182:183], v206 offset:0x4800
	ds_read_b64_tr_b16 v[184:185], v206 offset:0x5000
	ds_read_b64_tr_b16 v[186:187], v206 offset:0x5800
	ds_read_b64_tr_b16 v[216:217], v206 offset:0x6000
	ds_read_b64_tr_b16 v[218:219], v206 offset:0x6800
	ds_read_b64_tr_b16 v[220:221], v206 offset:0x7000
	ds_read_b64_tr_b16 v[222:223], v206 offset:0x7800
	s_waitcnt lgkmcnt(0)
	s_waitcnt vmcnt(4)
; __device__ __forceinline__ void partialSM(f32x16& p0, f32x16& p1, float& m_reg, float& mn, float& alpha) {
;     ...
;   for (int r = 0; r < 16; ++r) p0[r] = __builtin_amdgcn_exp2f(p0[r]);
; }
; __device__ __forceinline__ void partialSM_fixed(f32x16& p0) {
;   for (int r = 0; r < 16; ++r) p0[r] = __builtin_amdgcn_exp2f(p0[r]);
; }
; __device__ __forceinline__ void finishSM(f32x16& p0, f32x16& p1, float alpha, float& l_reg, bf16x8& pa0, bf16x8& pa1, bf16x8& pa2, bf16x8& pa3) {
;   for (int r = 0; r < 16; ++r) p1[r] = __builtin_amdgcn_exp2f(p1[r]);
;   float ps = 0; for (int r = 0; r < 16; ++r) ps += p0[r]; for (int r = 0; r < 16; ++r) ps += p1[r];
; template <int BOFF> __device__ __forceinline__ void qkt_i(f32x16& p0, f32x16& p1, const int (&kb)[4], const bf16x8* qr) {
;   p0 = f32x16{}; p1 = f32x16{};
; #pragma unroll
;   for (int d0 = 0; d0 < 8; ++d0) { const int off = BOFF + (d0 >> 2) * 128;
;     const bf16x8 b0 = LDSV(kb[d0 & 3] + off), b1 = LDSV(kb[d0 & 3] + off + 8192);
;     p0 = __builtin_amdgcn_mfma_f32_32x32x16_bf16(b0, qr[d0], p0, 0, 0, 0);
;     p1 = __builtin_amdgcn_mfma_f32_32x32x16_bf16(b1, qr[d0], p1, 0, 0, 0); }
; }
; template <int D0, int BOFF> __device__ __forceinline__ void pv_one_i(f32x16& od, int vb, bf16x8 pa0, bf16x8 pa1, bf16x8 pa2, bf16x8 pa3) {
;   const s16x4 l0 = tr_read<BOFF + v_rd_off(D0, 0, 0)>(vb), h0 = tr_read<BOFF + v_rd_off(D0, 0, 1)>(vb), l1 = tr_read<BOFF + v_rd_off(D0, 1, 0)>(vb), h1 = tr_read<BOFF + v_rd_off(D0, 1, 1)>(vb);
;   const s16x4 l2 = tr_read<BOFF + v_rd_off(D0, 2, 0)>(vb), h2 = tr_read<BOFF + v_rd_off(D0, 2, 1)>(vb), l3 = tr_read<BOFF + v_rd_off(D0, 3, 0)>(vb), h3 = tr_read<BOFF + v_rd_off(D0, 3, 1)>(vb);
;   asm volatile("s_waitcnt lgkmcnt(0)" ::: "memory"); SBAR();
;     ...
;   od = __builtin_amdgcn_mfma_f32_32x32x16_bf16(pa0, PK(l0, h0), od, 0, 0, 0);
;   od = __builtin_amdgcn_mfma_f32_32x32x16_bf16(pa1, PK(l1, h1), od, 0, 0, 0);
;   od = __builtin_amdgcn_mfma_f32_32x32x16_bf16(pa2, PK(l2, h2), od, 0, 0, 0);
;   od = __builtin_amdgcn_mfma_f32_32x32x16_bf16(pa3, PK(l3, h3), od, 0, 0, 0);
;     ...
; }
; template <int BOFF> __device__ __forceinline__ void pv_i(f32x16* o, int vb, bf16x8 pa0, bf16x8 pa1, bf16x8 pa2, bf16x8 pa3) {
;   pv_one_i<0, BOFF>(o[0], vb, pa0, pa1, pa2, pa3); pv_one_i<1, BOFF>(o[1], vb, pa0, pa1, pa2, pa3); pv_one_i<2, BOFF>(o[2], vb, pa0, pa1, pa2, pa3); pv_one_i<3, BOFF>(o[3], vb, pa0, pa1, pa2, pa3);
; }
	ds_write_b128 v211, v[146:149]
	s_nop 0
	v_mfma_f32_32x32x16_bf16 v[0:15], v[96:99], v[180:183], v[0:15]
	ds_read_b64_tr_b16 v[180:181], v206 offset:0x4200
	ds_read_b64_tr_b16 v[182:183], v206 offset:0x4a00
	v_mfma_f32_32x32x16_bf16 v[0:15], v[100:103], v[184:187], v[0:15]
	ds_read_b64_tr_b16 v[184:185], v206 offset:0x5200
	ds_read_b64_tr_b16 v[186:187], v206 offset:0x5a00
	v_mfma_f32_32x32x16_bf16 v[0:15], v[104:107], v[216:219], v[0:15]
	ds_read_b64_tr_b16 v[216:217], v206 offset:0x6200
	ds_read_b64_tr_b16 v[218:219], v206 offset:0x6a00
	v_mfma_f32_32x32x16_bf16 v[0:15], v[108:111], v[220:223], v[0:15]
	ds_read_b64_tr_b16 v[220:221], v206 offset:0x7200
	ds_read_b64_tr_b16 v[222:223], v206 offset:0x7a00
	s_waitcnt lgkmcnt(0)
	ds_write_b128 v212, v[158:161]
	v_mfma_f32_32x32x16_bf16 v[16:31], v[96:99], v[180:183], v[16:31]
	ds_read_b64_tr_b16 v[180:181], v206 offset:0x4400
	ds_read_b64_tr_b16 v[182:183], v206 offset:0x4c00
	v_mfma_f32_32x32x16_bf16 v[16:31], v[100:103], v[184:187], v[16:31]
	ds_read_b64_tr_b16 v[184:185], v206 offset:0x5400
	ds_read_b64_tr_b16 v[186:187], v206 offset:0x5c00
	v_mfma_f32_32x32x16_bf16 v[16:31], v[104:107], v[216:219], v[16:31]
	ds_read_b64_tr_b16 v[216:217], v206 offset:0x6400
	ds_read_b64_tr_b16 v[218:219], v206 offset:0x6c00
	v_mfma_f32_32x32x16_bf16 v[16:31], v[108:111], v[220:223], v[16:31]
	ds_read_b64_tr_b16 v[220:221], v206 offset:0x7400
	ds_read_b64_tr_b16 v[222:223], v206 offset:0x7c00
	s_waitcnt lgkmcnt(0)
	ds_write_b128 v213, v[150:153]
	v_mfma_f32_32x32x16_bf16 v[32:47], v[96:99], v[180:183], v[32:47]
	ds_read_b64_tr_b16 v[180:181], v206 offset:0x4600
	ds_read_b64_tr_b16 v[182:183], v206 offset:0x4e00
	v_mfma_f32_32x32x16_bf16 v[32:47], v[100:103], v[184:187], v[32:47]
	ds_read_b64_tr_b16 v[184:185], v206 offset:0x5600
	ds_read_b64_tr_b16 v[186:187], v206 offset:0x5e00
	v_mfma_f32_32x32x16_bf16 v[32:47], v[104:107], v[216:219], v[32:47]
	ds_read_b64_tr_b16 v[216:217], v206 offset:0x6600
	ds_read_b64_tr_b16 v[218:219], v206 offset:0x6e00
	v_mfma_f32_32x32x16_bf16 v[32:47], v[108:111], v[220:223], v[32:47]
	ds_read_b64_tr_b16 v[220:221], v206 offset:0x7600
	ds_read_b64_tr_b16 v[222:223], v206 offset:0x7e00
	s_waitcnt lgkmcnt(0)
	ds_write_b128 v214, v[154:157]
	v_mfma_f32_32x32x16_bf16 v[48:63], v[96:99], v[180:183], v[48:63]
	s_waitcnt vmcnt(4)
	v_exp_f32_e32 v180, v64
	v_exp_f32_e32 v181, v65
	v_exp_f32_e32 v182, v66
	v_exp_f32_e32 v183, v67
	v_exp_f32_e32 v188, v72
	v_exp_f32_e32 v189, v73
	v_mfma_f32_32x32x16_bf16 v[48:63], v[100:103], v[184:187], v[48:63]
	v_exp_f32_e32 v184, v68
	v_exp_f32_e32 v185, v69
	v_exp_f32_e32 v186, v70
	v_exp_f32_e32 v187, v71
	v_exp_f32_e32 v196, v74
	v_exp_f32_e32 v197, v75
	v_exp_f32_e32 v198, v76
	v_mfma_f32_32x32x16_bf16 v[48:63], v[104:107], v[216:219], v[48:63]
	v_exp_f32_e32 v199, v77
	v_exp_f32_e32 v216, v78
	v_exp_f32_e32 v217, v79
	s_waitcnt lgkmcnt(0)
	s_barrier
	v_mfma_f32_32x32x16_bf16 v[48:63], v[108:111], v[220:223], v[48:63]
	ds_read_b128 v[64:67], v207
	ds_read_b128 v[68:71], v207 offset:8192
	ds_read_b128 v[146:149], v208
	ds_read_b128 v[150:153], v208 offset:8192
	v_exp_f32_e32 v154, v88
	v_exp_f32_e32 v155, v89
	v_exp_f32_e32 v156, v90
	v_exp_f32_e32 v157, v91
	v_exp_f32_e32 v158, v92
	v_exp_f32_e32 v159, v93
	v_exp_f32_e32 v160, v94
	v_exp_f32_e32 v95, v95
	s_waitcnt lgkmcnt(3)
	v_mfma_f32_32x32x16_bf16 v[96:111], v[64:67], v[142:145], 0
	v_exp_f32_e32 v236, v80
	v_add_f32_e32 v80, 0, v180
	v_add_f32_e32 v80, v181, v80
	v_add_f32_e32 v80, v182, v80
	s_waitcnt lgkmcnt(2)
	v_mfma_f32_32x32x16_bf16 v[64:79], v[68:71], v[142:145], 0
	v_add_f32_e32 v80, v183, v80
	v_add_f32_e32 v80, v184, v80
	v_add_f32_e32 v80, v185, v80
	s_waitcnt lgkmcnt(1)
	v_mfma_f32_32x32x16_bf16 v[96:111], v[146:149], v[138:141], v[96:111]
	v_add_f32_e32 v80, v186, v80
	v_add_f32_e32 v80, v187, v80
	v_add_f32_e32 v80, v188, v80
	s_waitcnt lgkmcnt(0)
	v_mfma_f32_32x32x16_bf16 v[64:79], v[150:153], v[138:141], v[64:79]
	ds_read_b128 v[146:149], v209
	ds_read_b128 v[150:153], v209 offset:8192
	v_add_f32_e32 v80, v189, v80
	v_add_f32_e32 v80, v196, v80
	v_add_f32_e32 v80, v197, v80
	v_add_f32_e32 v80, v198, v80
	v_exp_f32_e32 v237, v81
	s_waitcnt lgkmcnt(1)
	v_mfma_f32_32x32x16_bf16 v[96:111], v[146:149], v[112:115], v[96:111]
	v_add_f32_e32 v80, v199, v80
	v_exp_f32_e32 v238, v82
	v_add_f32_e32 v80, v216, v80
	v_exp_f32_e32 v239, v83
	s_waitcnt lgkmcnt(0)
	v_mfma_f32_32x32x16_bf16 v[64:79], v[150:153], v[112:115], v[64:79]
	ds_read_b128 v[146:149], v210
	ds_read_b128 v[150:153], v210 offset:8192
	v_add_f32_e32 v80, v217, v80
	v_exp_f32_e32 v247, v84
	v_add_f32_e32 v80, v236, v80
	v_exp_f32_e32 v248, v85
	s_waitcnt lgkmcnt(1)
	v_mfma_f32_32x32x16_bf16 v[96:111], v[146:149], v[116:119], v[96:111]
	v_add_f32_e32 v80, v237, v80
	v_exp_f32_e32 v249, v86
	v_add_f32_e32 v80, v238, v80
	v_exp_f32_e32 v252, v87
	s_waitcnt lgkmcnt(0)
	v_mfma_f32_32x32x16_bf16 v[64:79], v[150:153], v[116:119], v[64:79]
	ds_read_b128 v[146:149], v190 offset:0
	ds_read_b128 v[150:153], v190 offset:8192
	v_add_f32_e32 v80, v239, v80
	v_add_f32_e32 v80, v247, v80
	v_add_f32_e32 v80, v248, v80
	v_add_f32_e32 v80, v249, v80
	v_add_f32_e32 v80, v252, v80
	v_add_f32_e32 v80, v154, v80
	s_waitcnt lgkmcnt(1)
	v_mfma_f32_32x32x16_bf16 v[96:111], v[146:149], v[120:123], v[96:111]
	v_add_f32_e32 v80, v155, v80
	v_add_f32_e32 v80, v156, v80
	v_add_f32_e32 v80, v157, v80
	v_add_f32_e32 v80, v158, v80
	v_add_f32_e32 v80, v159, v80
	s_waitcnt lgkmcnt(0)
	v_mfma_f32_32x32x16_bf16 v[64:79], v[150:153], v[120:123], v[64:79]
	ds_read_b128 v[146:149], v191 offset:0
	ds_read_b128 v[150:153], v191 offset:8192
	v_add_f32_e32 v80, v160, v80
	v_add_f32_e32 v80, v95, v80
	v_mov_b32_e32 v81, v80
	s_nop 1
	v_permlane32_swap_b32_e32 v80, v81
	v_add_f32_e32 v80, v80, v81
	s_waitcnt lgkmcnt(1)
; #define SBAR() __builtin_amdgcn_sched_barrier(0)
; #define SLOAD(i, k0) do { sr_[i].vs0 = ld8(&Vh[(long)((k0) + sr) * LDK + sc]); sr_[i].vs1 = ld8(&Vh[(long)((k0) + 32 + sr) * LDK + sc]); \
;     sr_[i].ks0 = ld8(&Kh[(long)((k0) + sr) * LDK + sc]); sr_[i].ks1 = ld8(&Kh[(long)((k0) + 32 + sr) * LDK + sc]); } while (0)
; #define SWAIT() asm volatile("s_waitcnt vmcnt(4)" ::: "memory")
; #define NOP_() do { } while (0)
; template <int D0, int BOFF> __device__ __forceinline__ void pv_one_i(f32x16& od, int vb, bf16x8 pa0, bf16x8 pa1, bf16x8 pa2, bf16x8 pa3) {
;   const s16x4 l0 = tr_read<BOFF + v_rd_off(D0, 0, 0)>(vb), h0 = tr_read<BOFF + v_rd_off(D0, 0, 1)>(vb), l1 = tr_read<BOFF + v_rd_off(D0, 1, 0)>(vb), h1 = tr_read<BOFF + v_rd_off(D0, 1, 1)>(vb);
;   const s16x4 l2 = tr_read<BOFF + v_rd_off(D0, 2, 0)>(vb), h2 = tr_read<BOFF + v_rd_off(D0, 2, 1)>(vb), l3 = tr_read<BOFF + v_rd_off(D0, 3, 0)>(vb), h3 = tr_read<BOFF + v_rd_off(D0, 3, 1)>(vb);
;   asm volatile("s_waitcnt lgkmcnt(0)" ::: "memory"); SBAR();
;     ...
;   od = __builtin_amdgcn_mfma_f32_32x32x16_bf16(pa0, PK(l0, h0), od, 0, 0, 0);
;   od = __builtin_amdgcn_mfma_f32_32x32x16_bf16(pa1, PK(l1, h1), od, 0, 0, 0);
;   od = __builtin_amdgcn_mfma_f32_32x32x16_bf16(pa2, PK(l2, h2), od, 0, 0, 0);
;   od = __builtin_amdgcn_mfma_f32_32x32x16_bf16(pa3, PK(l3, h3), od, 0, 0, 0);
;     ...
; }
; template <int BOFF> __device__ __forceinline__ void pv_i(f32x16* o, int vb, bf16x8 pa0, bf16x8 pa1, bf16x8 pa2, bf16x8 pa3) {
;   pv_one_i<0, BOFF>(o[0], vb, pa0, pa1, pa2, pa3); pv_one_i<1, BOFF>(o[1], vb, pa0, pa1, pa2, pa3); pv_one_i<2, BOFF>(o[2], vb, pa0, pa1, pa2, pa3); pv_one_i<3, BOFF>(o[3], vb, pa0, pa1, pa2, pa3);
; }
; template <bool PARTIAL, bool FIXED> ...
;     ...
;   for (; j + 6 < NT; j += 6) {
;     HALF_B(1, 0, SLOAD(1, (j + 2) * KVBLK), do { SWAIT(); SWRITE_I(2, 0); } while (0));
;     HALF_A(2, 1, NOP_(), SLOAD(0, (j + 3) * KVBLK), do { SWAIT(); SWRITE_I(0, 1); } while (0));
;     HALF_B(0, 2, SLOAD(1, (j + 4) * KVBLK), do { SWAIT(); SWRITE_I(1, 0); } while (0));
;     HALF_A(1, 0, NOP_(), SLOAD(0, (j + 5) * KVBLK), do { SWAIT(); SWRITE_I(2, 1); } while (0));
;     HALF_B(2, 1, SLOAD(1, (j + 6) * KVBLK), do { SWAIT(); SWRITE_I(0, 0); } while (0));
;     HALF_A(0, 2, NOP_(), SLOAD(0, (j + 7) * KVBLK), do { SWAIT(); SWRITE_I(1, 1); } while (0));
	v_mfma_f32_32x32x16_bf16 v[96:111], v[146:149], v[124:127], v[96:111]
	v_add_f32_e32 v215, v128, v80
	v_cvt_pk_bf16_f32 v80, v180, v181
	v_cvt_pk_bf16_f32 v81, v182, v183
	v_cvt_pk_bf16_f32 v82, v184, v185
	v_cvt_pk_bf16_f32 v83, v186, v187
	s_waitcnt lgkmcnt(0)
	v_mfma_f32_32x32x16_bf16 v[64:79], v[150:153], v[124:127], v[64:79]
	ds_read_b128 v[146:149], v192 offset:0
	ds_read_b128 v[150:153], v192 offset:8192
	v_cvt_pk_bf16_f32 v84, v188, v189
	v_cvt_pk_bf16_f32 v85, v196, v197
	v_cvt_pk_bf16_f32 v86, v198, v199
	v_cvt_pk_bf16_f32 v87, v216, v217
	v_cvt_pk_bf16_f32 v88, v236, v237
	v_cvt_pk_bf16_f32 v89, v238, v239
	s_waitcnt lgkmcnt(1)
	v_mfma_f32_32x32x16_bf16 v[96:111], v[146:149], v[130:133], v[96:111]
	v_cvt_pk_bf16_f32 v90, v247, v248
	v_cvt_pk_bf16_f32 v91, v249, v252
	v_cvt_pk_bf16_f32 v92, v154, v155
	v_cvt_pk_bf16_f32 v93, v156, v157
	v_cvt_pk_bf16_f32 v94, v158, v159
	s_waitcnt lgkmcnt(0)
	v_mfma_f32_32x32x16_bf16 v[64:79], v[150:153], v[130:133], v[64:79]
	ds_read_b128 v[146:149], v193 offset:0
	ds_read_b128 v[150:153], v193 offset:8192
	v_cvt_pk_bf16_f32 v95, v160, v95
	s_nop 0
	v_permlane32_swap_b32_e32 v80, v82
	v_permlane32_swap_b32_e32 v81, v83
	v_permlane32_swap_b32_e32 v84, v86
	v_permlane32_swap_b32_e32 v85, v87
	s_waitcnt lgkmcnt(1)
	v_mfma_f32_32x32x16_bf16 v[96:111], v[146:149], v[134:137], v[96:111]
	v_permlane32_swap_b32_e32 v88, v90
	v_permlane32_swap_b32_e32 v89, v91
	v_permlane32_swap_b32_e32 v92, v94
	v_permlane32_swap_b32_e32 v93, v95
	s_waitcnt lgkmcnt(0)
	v_mfma_f32_32x32x16_bf16 v[64:79], v[150:153], v[134:137], v[64:79]
	v_add_co_u32_e32 v150, vcc, s58, v178
	s_nop 1
	v_addc_co_u32_e32 v151, vcc, -1, v179, vcc
	global_load_dwordx4 v[146:149], v[150:151], off
	global_load_dwordx4 v[154:157], v[150:151], off offset:-512
	s_nop 0
	global_load_dwordx4 v[150:153], v[178:179], off
	global_load_dwordx4 v[158:161], v[178:179], off offset:-512
	ds_read_b64_tr_b16 v[180:181], v206 offset:0x8000
	ds_read_b64_tr_b16 v[182:183], v206 offset:0x8800
	ds_read_b64_tr_b16 v[184:185], v206 offset:0x9000
	ds_read_b64_tr_b16 v[186:187], v206 offset:0x9800
	ds_read_b64_tr_b16 v[216:217], v206 offset:0xa000
	ds_read_b64_tr_b16 v[218:219], v206 offset:0xa800
	ds_read_b64_tr_b16 v[220:221], v206 offset:0xb000
	ds_read_b64_tr_b16 v[222:223], v206 offset:0xb800
	s_waitcnt lgkmcnt(0)
	s_waitcnt vmcnt(4)
	ds_write_b128 v211, v[162:165] offset:16384
	s_nop 0
	v_mfma_f32_32x32x16_bf16 v[0:15], v[80:83], v[180:183], v[0:15]
	ds_read_b64_tr_b16 v[180:181], v206 offset:0x8200
	ds_read_b64_tr_b16 v[182:183], v206 offset:0x8a00
	v_mfma_f32_32x32x16_bf16 v[0:15], v[84:87], v[184:187], v[0:15]
	ds_read_b64_tr_b16 v[184:185], v206 offset:0x9200
	ds_read_b64_tr_b16 v[186:187], v206 offset:0x9a00
	v_mfma_f32_32x32x16_bf16 v[0:15], v[88:91], v[216:219], v[0:15]
	ds_read_b64_tr_b16 v[216:217], v206 offset:0xa200
	ds_read_b64_tr_b16 v[218:219], v206 offset:0xaa00
	v_mfma_f32_32x32x16_bf16 v[0:15], v[92:95], v[220:223], v[0:15]
	ds_read_b64_tr_b16 v[220:221], v206 offset:0xb200
	ds_read_b64_tr_b16 v[222:223], v206 offset:0xba00
	s_waitcnt lgkmcnt(0)
	ds_write_b128 v212, v[174:177] offset:16384
	v_mfma_f32_32x32x16_bf16 v[16:31], v[80:83], v[180:183], v[16:31]
	ds_read_b64_tr_b16 v[180:181], v206 offset:0x8400
	ds_read_b64_tr_b16 v[182:183], v206 offset:0x8c00
	v_mfma_f32_32x32x16_bf16 v[16:31], v[84:87], v[184:187], v[16:31]
	ds_read_b64_tr_b16 v[184:185], v206 offset:0x9400
	ds_read_b64_tr_b16 v[186:187], v206 offset:0x9c00
	v_mfma_f32_32x32x16_bf16 v[16:31], v[88:91], v[216:219], v[16:31]
	ds_read_b64_tr_b16 v[216:217], v206 offset:0xa400
	ds_read_b64_tr_b16 v[218:219], v206 offset:0xac00
	v_mfma_f32_32x32x16_bf16 v[16:31], v[92:95], v[220:223], v[16:31]
	ds_read_b64_tr_b16 v[220:221], v206 offset:0xb400
	ds_read_b64_tr_b16 v[222:223], v206 offset:0xbc00
	s_waitcnt lgkmcnt(0)
	ds_write_b128 v213, v[166:169] offset:16384
	v_mfma_f32_32x32x16_bf16 v[32:47], v[80:83], v[180:183], v[32:47]
	ds_read_b64_tr_b16 v[180:181], v206 offset:0x8600
	ds_read_b64_tr_b16 v[182:183], v206 offset:0x8e00
	v_mfma_f32_32x32x16_bf16 v[32:47], v[84:87], v[184:187], v[32:47]
	ds_read_b64_tr_b16 v[184:185], v206 offset:0x9600
	ds_read_b64_tr_b16 v[186:187], v206 offset:0x9e00
	v_mfma_f32_32x32x16_bf16 v[32:47], v[88:91], v[216:219], v[32:47]
	ds_read_b64_tr_b16 v[216:217], v206 offset:0xa600
	ds_read_b64_tr_b16 v[218:219], v206 offset:0xae00
	v_mfma_f32_32x32x16_bf16 v[32:47], v[92:95], v[220:223], v[32:47]
	ds_read_b64_tr_b16 v[220:221], v206 offset:0xb600
	ds_read_b64_tr_b16 v[222:223], v206 offset:0xbe00
	s_waitcnt lgkmcnt(0)
	ds_write_b128 v214, v[170:173] offset:16384
	v_mfma_f32_32x32x16_bf16 v[48:63], v[80:83], v[180:183], v[48:63]
	v_exp_f32_e32 v229, v96
	v_exp_f32_e32 v243, v97
	v_exp_f32_e32 v244, v98
	v_exp_f32_e32 v246, v99
	v_exp_f32_e32 v242, v100
	v_exp_f32_e32 v245, v101
	v_exp_f32_e32 v227, v102
	v_mfma_f32_32x32x16_bf16 v[48:63], v[84:87], v[184:187], v[48:63]
	v_exp_f32_e32 v228, v103
	v_exp_f32_e32 v226, v105
	v_exp_f32_e32 v224, v106
	v_exp_f32_e32 v225, v107
	s_waitcnt vmcnt(4)
	s_add_i32 s28, s28, 6
	v_lshl_add_u64 v[178:179], v[178:179], 0, s[60:61]
	v_mfma_f32_32x32x16_bf16 v[48:63], v[88:91], v[216:219], v[48:63]
	v_exp_f32_e32 v219, v110
	s_cmpk_lt_u32 s28, 0x75
	v_mfma_f32_32x32x16_bf16 v[48:63], v[92:95], v[220:223], v[48:63]
	v_exp_f32_e32 v223, v104
	v_exp_f32_e32 v220, v108
	v_exp_f32_e32 v222, v109
	v_exp_f32_e32 v221, v111
	s_cbranch_scc1 .LBB0_352
; #define SWRITE_I(B, i) do { LDSV(wv0 + (B) * 16384) = sr_[i].vs0; LDSV(wv1 + (B) * 16384) = sr_[i].vs1; LDSV(wk0 + (B) * 16384) = sr_[i].ks0; LDSV(wk1 + (B) * 16384) = sr_[i].ks1; } while (0)
; #define NOP_() do { } while (0)
; template <bool PARTIAL, bool FIXED> ...
;     ...
;   if constexpr (!PARTIAL) { const int i1 = tid & 255;
;     warm0 = *(const unsigned*)(Qb_n + (long)(tid >> 1) * LDQ + (tid & 1) * 64);
;     warm1 = *(const unsigned*)((tid < 256 ? Kh_n : Vh_n) + (long)(i1 >> 1) * LDK + (i1 & 1) * 64); }
;   HALF_B(1, 0, NOP_(), SWRITE_I(2, 0));
	v_mov_b32_e32 v252, 0x7fc00000
	v_readlane_b32 s8, v255, 42
	v_readlane_b32 s9, v255, 43
	s_add_u32 s2, s8, s6
	s_addc_u32 s3, s9, s7
	s_lshl_b32 s4, s65, 1
	s_add_u32 s2, s2, s4
	s_addc_u32 s3, s3, 0
	v_ashrrev_i32_e32 v82, 1, v195
	v_mov_b64_e32 v[80:81], s[2:3]
	v_mad_i64_i32 v[80:81], s[2:3], v82, s17, v[80:81]
	v_lshlrev_b32_e32 v82, 7, v195
	v_and_b32_e32 v128, 0x80, v82
	v_lshl_add_u64 v[80:81], v[80:81], 0, v[128:129]
	s_add_u32 s4, s8, s64
	global_load_dword v216, v[80:81], off
	v_cmp_gt_i32_e32 vcc, s14, v195
	v_mov_b32_e32 v80, 0xa00
	v_mov_b32_e32 v81, 0x800
	s_addc_u32 s5, s9, s57
	v_cndmask_b32_e32 v80, v80, v81, vcc
	v_mov_b32_e32 v81, v129
	v_bfe_u32 v82, v195, 1, 7
	v_lshl_add_u64 v[80:81], s[4:5], 0, v[80:81]
	s_lshl_b32 s46, s56, 1
	v_mul_u32_u24_e32 v82, 0x600, v82
	v_lshl_add_u64 v[80:81], v[80:81], 0, s[46:47]
	v_lshlrev_b32_e32 v82, 1, v82
	v_mov_b32_e32 v83, v129
	v_lshl_add_u64 v[80:81], v[80:81], 0, v[82:83]
	v_lshl_add_u64 v[80:81], v[80:81], 0, v[128:129]
	global_load_dword v217, v[80:81], off
	v_and_b32_e32 v247, 0x3fffffc0, v195
	s_waitcnt lgkmcnt(0)
	s_barrier
	ds_read_b128 v[80:83], v207 offset:16384
	ds_read_b128 v[96:99], v207 offset:24576
	ds_read_b128 v[100:103], v208 offset:16384
	ds_read_b128 v[170:173], v208 offset:24576
	v_exp_f32_e32 v104, v68
	v_exp_f32_e32 v105, v69
	s_waitcnt lgkmcnt(3)
	v_mfma_f32_32x32x16_bf16 v[80:95], v[80:83], v[142:145], 0
	v_exp_f32_e32 v106, v70
	v_exp_f32_e32 v107, v71
	v_exp_f32_e32 v108, v72
	v_exp_f32_e32 v109, v73
	v_exp_f32_e32 v110, v74
	v_exp_f32_e32 v111, v75
	v_exp_f32_e32 v196, v76
	s_waitcnt lgkmcnt(1)
	v_mfma_f32_32x32x16_bf16 v[80:95], v[100:103], v[138:141], v[80:95]
	ds_read_b128 v[100:103], v209 offset:16384
	ds_read_b128 v[162:165], v209 offset:24576
	v_exp_f32_e32 v197, v77
	v_exp_f32_e32 v198, v78
	v_exp_f32_e32 v79, v79
	s_waitcnt lgkmcnt(1)
	v_mfma_f32_32x32x16_bf16 v[80:95], v[100:103], v[112:115], v[80:95]
	ds_read_b128 v[100:103], v210 offset:16384
	ds_read_b128 v[166:169], v210 offset:24576
	s_waitcnt lgkmcnt(1)
	v_mfma_f32_32x32x16_bf16 v[80:95], v[100:103], v[116:119], v[80:95]
	ds_read_b128 v[100:103], v190 offset:16384
	ds_read_b128 v[174:177], v190 offset:24576
	s_waitcnt lgkmcnt(1)
	v_mfma_f32_32x32x16_bf16 v[80:95], v[100:103], v[120:123], v[80:95]
	ds_read_b128 v[100:103], v191 offset:16384
	ds_read_b128 v[178:181], v191 offset:24576
	s_waitcnt lgkmcnt(1)
	v_mfma_f32_32x32x16_bf16 v[80:95], v[100:103], v[124:127], v[80:95]
	ds_read_b128 v[100:103], v192 offset:16384
	ds_read_b128 v[182:185], v192 offset:24576
	s_waitcnt lgkmcnt(1)
	v_mfma_f32_32x32x16_bf16 v[80:95], v[100:103], v[130:133], v[80:95]
	ds_read_b128 v[100:103], v193 offset:16384
	ds_read_b128 v[186:189], v193 offset:24576
	s_waitcnt lgkmcnt(1)
	v_mfma_f32_32x32x16_bf16 v[80:95], v[100:103], v[134:137], v[80:95]
	v_exp_f32_e32 v100, v64
	v_add_f32_e32 v64, 0, v229
	v_add_f32_e32 v64, v243, v64
	v_add_f32_e32 v64, v244, v64
	v_add_f32_e32 v64, v246, v64
	v_add_f32_e32 v64, v242, v64
	v_add_f32_e32 v64, v245, v64
	v_add_f32_e32 v64, v227, v64
	v_add_f32_e32 v64, v228, v64
	v_add_f32_e32 v64, v223, v64
	v_add_f32_e32 v64, v226, v64
	v_add_f32_e32 v64, v224, v64
	v_add_f32_e32 v64, v225, v64
	v_add_f32_e32 v64, v220, v64
	v_exp_f32_e32 v101, v65
	v_add_f32_e32 v64, v222, v64
	v_exp_f32_e32 v102, v66
	v_add_f32_e32 v64, v219, v64
	v_exp_f32_e32 v103, v67
	v_add_f32_e32 v64, v221, v64
	v_add_f32_e32 v64, v100, v64
	v_add_f32_e32 v64, v101, v64
	v_add_f32_e32 v64, v102, v64
	v_add_f32_e32 v64, v103, v64
	v_add_f32_e32 v64, v104, v64
	v_add_f32_e32 v64, v105, v64
	v_add_f32_e32 v64, v106, v64
	v_add_f32_e32 v64, v107, v64
	v_add_f32_e32 v64, v108, v64
	v_add_f32_e32 v64, v109, v64
	v_add_f32_e32 v64, v110, v64
	v_add_f32_e32 v64, v111, v64
	v_add_f32_e32 v64, v196, v64
	v_add_f32_e32 v64, v197, v64
	v_add_f32_e32 v64, v198, v64
	v_add_f32_e32 v128, v79, v64
	v_mov_b32_e32 v218, v128
	s_nop 1
	v_permlane32_swap_b32_e32 v128, v218
	v_cvt_pk_bf16_f32 v64, v229, v243
	v_cvt_pk_bf16_f32 v65, v244, v246
	v_cvt_pk_bf16_f32 v66, v242, v245
	v_cvt_pk_bf16_f32 v67, v227, v228
	v_cvt_pk_bf16_f32 v68, v223, v226
	v_cvt_pk_bf16_f32 v69, v224, v225
	v_cvt_pk_bf16_f32 v70, v220, v222
	v_cvt_pk_bf16_f32 v71, v219, v221
	v_cvt_pk_bf16_f32 v72, v100, v101
	v_cvt_pk_bf16_f32 v73, v102, v103
	v_cvt_pk_bf16_f32 v74, v104, v105
	v_cvt_pk_bf16_f32 v75, v106, v107
	v_cvt_pk_bf16_f32 v76, v108, v109
	v_cvt_pk_bf16_f32 v77, v110, v111
	v_cvt_pk_bf16_f32 v78, v196, v197
	v_cvt_pk_bf16_f32 v79, v198, v79
	s_nop 0
	v_permlane32_swap_b32_e32 v64, v66
	v_permlane32_swap_b32_e32 v65, v67
	v_permlane32_swap_b32_e32 v68, v70
	v_permlane32_swap_b32_e32 v69, v71
	v_permlane32_swap_b32_e32 v72, v74
	v_permlane32_swap_b32_e32 v73, v75
	v_permlane32_swap_b32_e32 v76, v78
	v_permlane32_swap_b32_e32 v77, v79
	ds_read_b64_tr_b16 v[100:101], v206 offset:0
	ds_read_b64_tr_b16 v[102:103], v206 offset:0x800
	ds_read_b64_tr_b16 v[104:105], v206 offset:0x1000
	ds_read_b64_tr_b16 v[106:107], v206 offset:0x1800
	ds_read_b64_tr_b16 v[108:109], v206 offset:0x2000
	ds_read_b64_tr_b16 v[110:111], v206 offset:0x2800
	ds_read_b64_tr_b16 v[220:221], v206 offset:0x3000
	ds_read_b64_tr_b16 v[222:223], v206 offset:0x3800
	s_waitcnt lgkmcnt(0)
	s_nop 0
	v_mfma_f32_32x32x16_bf16 v[0:15], v[64:67], v[100:103], v[0:15]
	ds_read_b64_tr_b16 v[100:101], v206 offset:0x200
	ds_read_b64_tr_b16 v[102:103], v206 offset:0xa00
	v_mfma_f32_32x32x16_bf16 v[0:15], v[68:71], v[104:107], v[0:15]
	ds_read_b64_tr_b16 v[104:105], v206 offset:0x1200
	ds_read_b64_tr_b16 v[106:107], v206 offset:0x1a00
	v_mfma_f32_32x32x16_bf16 v[0:15], v[72:75], v[108:111], v[0:15]
	ds_read_b64_tr_b16 v[108:109], v206 offset:0x2200
	ds_read_b64_tr_b16 v[110:111], v206 offset:0x2a00
	v_mfma_f32_32x32x16_bf16 v[0:15], v[76:79], v[220:223], v[0:15]
	ds_read_b64_tr_b16 v[220:221], v206 offset:0x3200
	ds_read_b64_tr_b16 v[222:223], v206 offset:0x3a00
	s_waitcnt lgkmcnt(0)
; #define SBAR() __builtin_amdgcn_sched_barrier(0)
; #define SLOAD(i, k0) do { sr_[i].vs0 = ld8(&Vh[(long)((k0) + sr) * LDK + sc]); sr_[i].vs1 = ld8(&Vh[(long)((k0) + 32 + sr) * LDK + sc]); \
;     sr_[i].ks0 = ld8(&Kh[(long)((k0) + sr) * LDK + sc]); sr_[i].ks1 = ld8(&Kh[(long)((k0) + 32 + sr) * LDK + sc]); } while (0)
; #define SWAIT() asm volatile("s_waitcnt vmcnt(4)" ::: "memory")
; #define SWRITE_I(B, i) do { LDSV(wv0 + (B) * 16384) = sr_[i].vs0; LDSV(wv1 + (B) * 16384) = sr_[i].vs1; LDSV(wk0 + (B) * 16384) = sr_[i].ks0; LDSV(wk1 + (B) * 16384) = sr_[i].ks1; } while (0)
; #define NOP_() do { } while (0)
; template <bool PARTIAL, bool FIXED> ...
;     ...
;   int j = 1;
;   for (; j + 6 < NT; j += 6) {
;     HALF_B(1, 0, SLOAD(1, (j + 2) * KVBLK), do { SWAIT(); SWRITE_I(2, 0); } while (0));
;     HALF_A(2, 1, NOP_(), SLOAD(0, (j + 3) * KVBLK), do { SWAIT(); SWRITE_I(0, 1); } while (0));
;     HALF_B(0, 2, SLOAD(1, (j + 4) * KVBLK), do { SWAIT(); SWRITE_I(1, 0); } while (0));
;     HALF_A(1, 0, NOP_(), SLOAD(0, (j + 5) * KVBLK), do { SWAIT(); SWRITE_I(2, 1); } while (0));
;     HALF_B(2, 1, SLOAD(1, (j + 6) * KVBLK), do { SWAIT(); SWRITE_I(0, 0); } while (0));
;     HALF_A(0, 2, NOP_(), SLOAD(0, (j + 7) * KVBLK), do { SWAIT(); SWRITE_I(1, 1); } while (0));
;   }
;   if constexpr (!PARTIAL) { const int i1 = tid & 255;
;     warm0 = *(const unsigned*)(Qb_n + (long)(tid >> 1) * LDQ + (tid & 1) * 64);
;     warm1 = *(const unsigned*)((tid < 256 ? Kh_n : Vh_n) + (long)(i1 >> 1) * LDK + (i1 & 1) * 64); }
;   HALF_B(1, 0, NOP_(), SWRITE_I(2, 0));
;   HALF_A(2, 1, do { if (mask_last) { asm volatile("; masked tail tile" ::: "memory"); const float NEG = -INFINITY; \
;       _Pragma("unroll") for (int r = 8; r < 16; ++r) pA0[r] = NEG; _Pragma("unroll") for (int r = 0; r < 16; ++r) pA1[r] = NEG; } } while (0), NOP_(), NOP_());
;     ...
;   SBAR(); finishSM(pA0, pA1, alA, l_reg, pa0, pa1, pa2, pa3); SBAR();
;   pv_i<2 * 16384>(o, vbi, pa0, pa1, pa2, pa3);
	v_mfma_f32_32x32x16_bf16 v[16:31], v[64:67], v[100:103], v[16:31]
	ds_read_b64_tr_b16 v[100:101], v206 offset:0x400
	ds_read_b64_tr_b16 v[102:103], v206 offset:0xc00
	v_mfma_f32_32x32x16_bf16 v[16:31], v[68:71], v[104:107], v[16:31]
	ds_read_b64_tr_b16 v[104:105], v206 offset:0x1400
	ds_read_b64_tr_b16 v[106:107], v206 offset:0x1c00
	v_mfma_f32_32x32x16_bf16 v[16:31], v[72:75], v[108:111], v[16:31]
	ds_read_b64_tr_b16 v[108:109], v206 offset:0x2400
	ds_read_b64_tr_b16 v[110:111], v206 offset:0x2c00
	v_mfma_f32_32x32x16_bf16 v[16:31], v[76:79], v[220:223], v[16:31]
	ds_read_b64_tr_b16 v[220:221], v206 offset:0x3400
	ds_read_b64_tr_b16 v[222:223], v206 offset:0x3c00
	s_waitcnt lgkmcnt(0)
	v_mfma_f32_32x32x16_bf16 v[32:47], v[64:67], v[100:103], v[32:47]
	ds_read_b64_tr_b16 v[100:101], v206 offset:0x600
	ds_read_b64_tr_b16 v[102:103], v206 offset:0xe00
	v_mfma_f32_32x32x16_bf16 v[32:47], v[68:71], v[104:107], v[32:47]
	ds_read_b64_tr_b16 v[104:105], v206 offset:0x1600
	ds_read_b64_tr_b16 v[106:107], v206 offset:0x1e00
	v_mfma_f32_32x32x16_bf16 v[32:47], v[72:75], v[108:111], v[32:47]
	ds_read_b64_tr_b16 v[108:109], v206 offset:0x2600
	ds_read_b64_tr_b16 v[110:111], v206 offset:0x2e00
	v_mfma_f32_32x32x16_bf16 v[32:47], v[76:79], v[220:223], v[32:47]
	ds_read_b64_tr_b16 v[220:221], v206 offset:0x3600
	ds_read_b64_tr_b16 v[222:223], v206 offset:0x3e00
	s_waitcnt lgkmcnt(0)
	v_mfma_f32_32x32x16_bf16 v[48:63], v[64:67], v[100:103], v[48:63]
	s_waitcnt vmcnt(5)
	ds_write_b128 v211, v[146:149] offset:32768
	s_waitcnt vmcnt(3)
	ds_write_b128 v212, v[150:153] offset:32768
	ds_write_b128 v213, v[154:157] offset:32768
	s_waitcnt vmcnt(2)
	ds_write_b128 v214, v[158:161] offset:32768
	s_waitcnt lgkmcnt(0)
	s_barrier
	v_mfma_f32_32x32x16_bf16 v[48:63], v[68:71], v[104:107], v[48:63]
	v_mfma_f32_32x32x16_bf16 v[48:63], v[72:75], v[108:111], v[48:63]
	v_mfma_f32_32x32x16_bf16 v[48:63], v[76:79], v[220:223], v[48:63]
	ds_read_b128 v[64:67], v207 offset:32768
	ds_read_b128 v[100:103], v208 offset:32768
	s_add_i32 s2, 0, 0x18000
	s_waitcnt lgkmcnt(1)
	v_mfma_f32_32x32x16_bf16 v[64:79], v[64:67], v[142:145], 0
	s_waitcnt lgkmcnt(0)
	v_mfma_f32_32x32x16_bf16 v[64:79], v[100:103], v[138:141], v[64:79]
	ds_read_b128 v[100:103], v209 offset:32768
	s_waitcnt lgkmcnt(0)
	v_mfma_f32_32x32x16_bf16 v[64:79], v[100:103], v[112:115], v[64:79]
	ds_read_b128 v[100:103], v210 offset:32768
	s_waitcnt lgkmcnt(0)
	v_mfma_f32_32x32x16_bf16 v[64:79], v[100:103], v[116:119], v[64:79]
	ds_read_b128 v[100:103], v190 offset:32768
	s_waitcnt lgkmcnt(0)
	v_mfma_f32_32x32x16_bf16 v[64:79], v[100:103], v[120:123], v[64:79]
	ds_read_b128 v[100:103], v191 offset:32768
	s_waitcnt lgkmcnt(0)
	v_mfma_f32_32x32x16_bf16 v[64:79], v[100:103], v[124:127], v[64:79]
	ds_read_b128 v[100:103], v192 offset:32768
	s_waitcnt lgkmcnt(0)
	v_mfma_f32_32x32x16_bf16 v[64:79], v[100:103], v[130:133], v[64:79]
	ds_read_b128 v[100:103], v193 offset:32768
	s_waitcnt lgkmcnt(0)
	v_and_b32_e32 v190, 63, v195
	v_lshlrev_b32_e32 v191, 4, v195
	v_and_b32_e32 v192, 31, v195
	v_bfe_u32 v193, v195, 5, 1
	v_mfma_f32_32x32x16_bf16 v[64:79], v[100:103], v[134:137], v[64:79]
	v_mfma_f32_32x32x16_bf16 v[96:111], v[96:99], v[142:145], 0
	s_nop 10
	v_exp_f32_e32 v72, v80
	v_exp_f32_e32 v80, v81
	v_exp_f32_e32 v73, v82
	v_exp_f32_e32 v81, v83
	v_exp_f32_e32 v74, v84
	v_add_f32_e32 v84, 0, v72
	v_exp_f32_e32 v82, v85
	v_mfma_f32_32x32x16_bf16 v[96:111], v[170:173], v[138:141], v[96:111]
	v_add_f32_e32 v84, v80, v84
	v_exp_f32_e32 v75, v86
	v_add_f32_e32 v84, v73, v84
	v_exp_f32_e32 v83, v87
	v_add_f32_e32 v84, v81, v84
	v_exp_f32_e32 v76, v88
	v_add_f32_e32 v84, v74, v84
	v_mfma_f32_32x32x16_bf16 v[96:111], v[162:165], v[112:115], v[96:111]
	v_exp_f32_e32 v85, v89
	v_add_f32_e32 v84, v82, v84
	v_exp_f32_e32 v77, v90
	v_add_f32_e32 v84, v75, v84
	v_exp_f32_e32 v87, v91
	v_add_f32_e32 v84, v83, v84
	v_exp_f32_e32 v78, v92
	v_mfma_f32_32x32x16_bf16 v[96:111], v[166:169], v[116:119], v[96:111]
	v_add_f32_e32 v84, v76, v84
	v_exp_f32_e32 v89, v93
	v_add_f32_e32 v84, v85, v84
	v_exp_f32_e32 v79, v94
	v_add_f32_e32 v84, v77, v84
	v_exp_f32_e32 v90, v95
	v_add_f32_e32 v84, v87, v84
	v_mfma_f32_32x32x16_bf16 v[96:111], v[174:177], v[120:123], v[96:111]
	v_add_f32_e32 v84, v78, v84
	v_add_f32_e32 v84, v89, v84
	v_add_f32_e32 v84, v79, v84
	v_add_f32_e32 v84, v90, v84
	v_lshl_add_u32 v88, v247, 2, s2
	v_cvt_pk_bf16_f32 v72, v72, v80
	v_cvt_pk_bf16_f32 v73, v73, v81
	v_mfma_f32_32x32x16_bf16 v[96:111], v[178:181], v[124:127], v[96:111]
	v_cvt_pk_bf16_f32 v74, v74, v82
	v_cvt_pk_bf16_f32 v75, v75, v83
	v_cvt_pk_bf16_f32 v76, v76, v85
	v_cvt_pk_bf16_f32 v77, v77, v87
	v_cvt_pk_bf16_f32 v78, v78, v89
	v_cvt_pk_bf16_f32 v79, v79, v90
	s_nop 0
	v_permlane32_swap_b32_e32 v72, v74
	v_mfma_f32_32x32x16_bf16 v[96:111], v[182:185], v[130:133], v[96:111]
	v_permlane32_swap_b32_e32 v73, v75
	v_permlane32_swap_b32_e32 v76, v78
	v_permlane32_swap_b32_e32 v77, v79
	v_mfma_f32_32x32x16_bf16 v[96:111], v[186:189], v[134:137], v[96:111]
	s_nop 11
	v_exp_f32_e32 v91, v96
	v_exp_f32_e32 v92, v97
	v_exp_f32_e32 v93, v98
	v_exp_f32_e32 v94, v99
	v_exp_f32_e32 v95, v100
	v_add_f32_e32 v84, v84, v91
	v_exp_f32_e32 v96, v101
	v_add_f32_e32 v84, v92, v84
	v_exp_f32_e32 v97, v102
	v_add_f32_e32 v84, v93, v84
	v_exp_f32_e32 v98, v103
	v_add_f32_e32 v84, v94, v84
	v_exp_f32_e32 v99, v104
	v_add_f32_e32 v84, v95, v84
	v_exp_f32_e32 v100, v105
	v_add_f32_e32 v84, v96, v84
	v_exp_f32_e32 v101, v106
	v_add_f32_e32 v84, v97, v84
	v_exp_f32_e32 v102, v107
	v_add_f32_e32 v84, v98, v84
	v_exp_f32_e32 v103, v108
	v_add_f32_e32 v84, v99, v84
	v_exp_f32_e32 v104, v109
	v_add_f32_e32 v84, v100, v84
	v_exp_f32_e32 v105, v110
	v_add_f32_e32 v84, v101, v84
	v_exp_f32_e32 v106, v111
	v_add_f32_e32 v84, v102, v84
	v_add_f32_e32 v84, v103, v84
	v_add_f32_e32 v84, v104, v84
	v_add_f32_e32 v84, v105, v84
	v_add_f32_e32 v84, v106, v84
	v_mov_b32_e32 v86, v84
	s_nop 1
	v_permlane32_swap_b32_e32 v84, v86
	v_cvt_pk_bf16_f32 v80, v91, v92
	v_cvt_pk_bf16_f32 v81, v93, v94
	v_cvt_pk_bf16_f32 v82, v95, v96
	v_cvt_pk_bf16_f32 v83, v97, v98
	v_cvt_pk_bf16_f32 v90, v99, v100
	v_cvt_pk_bf16_f32 v91, v101, v102
	v_cvt_pk_bf16_f32 v92, v103, v104
	v_cvt_pk_bf16_f32 v93, v105, v106
	s_nop 0
	v_permlane32_swap_b32_e32 v80, v82
	v_permlane32_swap_b32_e32 v81, v83
	v_permlane32_swap_b32_e32 v90, v92
	v_permlane32_swap_b32_e32 v91, v93
	ds_read_b64_tr_b16 v[94:95], v206 offset:0x4000
	ds_read_b64_tr_b16 v[96:97], v206 offset:0x4800
	ds_read_b64_tr_b16 v[98:99], v206 offset:0x5000
	ds_read_b64_tr_b16 v[100:101], v206 offset:0x5800
	ds_read_b64_tr_b16 v[102:103], v206 offset:0x6000
	ds_read_b64_tr_b16 v[104:105], v206 offset:0x6800
	ds_read_b64_tr_b16 v[106:107], v206 offset:0x7000
	ds_read_b64_tr_b16 v[108:109], v206 offset:0x7800
	s_waitcnt lgkmcnt(0)
; #define SBAR() __builtin_amdgcn_sched_barrier(0)
; __device__ __forceinline__ int crow(int r, int hi) { return (r & 3) + 8 * (r >> 2) + 4 * hi; }
; template <int D0, int BOFF> __device__ __forceinline__ void pv_one_i(f32x16& od, int vb, bf16x8 pa0, bf16x8 pa1, bf16x8 pa2, bf16x8 pa3) {
;   const s16x4 l0 = tr_read<BOFF + v_rd_off(D0, 0, 0)>(vb), h0 = tr_read<BOFF + v_rd_off(D0, 0, 1)>(vb), l1 = tr_read<BOFF + v_rd_off(D0, 1, 0)>(vb), h1 = tr_read<BOFF + v_rd_off(D0, 1, 1)>(vb);
;   const s16x4 l2 = tr_read<BOFF + v_rd_off(D0, 2, 0)>(vb), h2 = tr_read<BOFF + v_rd_off(D0, 2, 1)>(vb), l3 = tr_read<BOFF + v_rd_off(D0, 3, 0)>(vb), h3 = tr_read<BOFF + v_rd_off(D0, 3, 1)>(vb);
;   asm volatile("s_waitcnt lgkmcnt(0)" ::: "memory"); SBAR();
;     ...
;   od = __builtin_amdgcn_mfma_f32_32x32x16_bf16(pa0, PK(l0, h0), od, 0, 0, 0);
;   od = __builtin_amdgcn_mfma_f32_32x32x16_bf16(pa1, PK(l1, h1), od, 0, 0, 0);
;   od = __builtin_amdgcn_mfma_f32_32x32x16_bf16(pa2, PK(l2, h2), od, 0, 0, 0);
;   od = __builtin_amdgcn_mfma_f32_32x32x16_bf16(pa3, PK(l3, h3), od, 0, 0, 0);
;     ...
; }
; template <int BOFF> __device__ __forceinline__ void pv_i(f32x16* o, int vb, bf16x8 pa0, bf16x8 pa1, bf16x8 pa2, bf16x8 pa3) {
;   pv_one_i<0, BOFF>(o[0], vb, pa0, pa1, pa2, pa3); pv_one_i<1, BOFF>(o[1], vb, pa0, pa1, pa2, pa3); pv_one_i<2, BOFF>(o[2], vb, pa0, pa1, pa2, pa3); pv_one_i<3, BOFF>(o[3], vb, pa0, pa1, pa2, pa3);
; }
; template <bool PARTIAL, bool FIXED> ...
;     ...
;   SBAR(); finishSM(pA0, pA1, alA, l_reg, pa0, pa1, pa2, pa3); SBAR();
;   pv_i<2 * 16384>(o, vbi, pa0, pa1, pa2, pa3);
;     ...
;   if (PARTIAL) {
;     if (wid < 2) { float* po = PO + (wid * QBLK) * 128;
; #pragma unroll
;       for (int r = 0; r < 16; ++r) { const int orow = crow(r, hi);
; #pragma unroll
;         for (int d0 = 0; d0 < 4; ++d0) po[orow * 128 + d0 * 32 + r32] = o[d0][r]; }
;       if (hi == 0) { PO[8192 + (wid * QBLK + r32) * 2] = m_reg; PO[8192 + (wid * QBLK + r32) * 2 + 1] = l_reg; } }
;     __syncthreads();
;     return;
;   }
;   if (hi == 0) li_l[r32] = l_reg; asm volatile("s_waitcnt lgkmcnt(0)" ::: "memory");
	s_nop 0
	v_mfma_f32_32x32x16_bf16 v[0:15], v[72:75], v[94:97], v[0:15]
	ds_read_b64_tr_b16 v[94:95], v206 offset:0x4200
	ds_read_b64_tr_b16 v[96:97], v206 offset:0x4a00
	v_mfma_f32_32x32x16_bf16 v[0:15], v[76:79], v[98:101], v[0:15]
	ds_read_b64_tr_b16 v[98:99], v206 offset:0x5200
	ds_read_b64_tr_b16 v[100:101], v206 offset:0x5a00
	v_mfma_f32_32x32x16_bf16 v[0:15], v[80:83], v[102:105], v[0:15]
	ds_read_b64_tr_b16 v[102:103], v206 offset:0x6200
	ds_read_b64_tr_b16 v[104:105], v206 offset:0x6a00
	v_mfma_f32_32x32x16_bf16 v[0:15], v[90:93], v[106:109], v[0:15]
	ds_read_b64_tr_b16 v[106:107], v206 offset:0x7200
	ds_read_b64_tr_b16 v[108:109], v206 offset:0x7a00
	s_waitcnt lgkmcnt(0)
	v_mfma_f32_32x32x16_bf16 v[16:31], v[72:75], v[94:97], v[16:31]
	ds_read_b64_tr_b16 v[94:95], v206 offset:0x4400
	ds_read_b64_tr_b16 v[96:97], v206 offset:0x4c00
	v_mfma_f32_32x32x16_bf16 v[16:31], v[76:79], v[98:101], v[16:31]
	ds_read_b64_tr_b16 v[98:99], v206 offset:0x5400
	ds_read_b64_tr_b16 v[100:101], v206 offset:0x5c00
	v_mfma_f32_32x32x16_bf16 v[16:31], v[80:83], v[102:105], v[16:31]
	ds_read_b64_tr_b16 v[102:103], v206 offset:0x6400
	ds_read_b64_tr_b16 v[104:105], v206 offset:0x6c00
	v_mfma_f32_32x32x16_bf16 v[16:31], v[90:93], v[106:109], v[16:31]
	ds_read_b64_tr_b16 v[106:107], v206 offset:0x7400
	ds_read_b64_tr_b16 v[108:109], v206 offset:0x7c00
	s_waitcnt lgkmcnt(0)
	v_mfma_f32_32x32x16_bf16 v[32:47], v[72:75], v[94:97], v[32:47]
	ds_read_b64_tr_b16 v[94:95], v206 offset:0x4600
	ds_read_b64_tr_b16 v[96:97], v206 offset:0x4e00
	v_mfma_f32_32x32x16_bf16 v[32:47], v[76:79], v[98:101], v[32:47]
	ds_read_b64_tr_b16 v[98:99], v206 offset:0x5600
	ds_read_b64_tr_b16 v[100:101], v206 offset:0x5e00
	v_mfma_f32_32x32x16_bf16 v[32:47], v[80:83], v[102:105], v[32:47]
	ds_read_b64_tr_b16 v[102:103], v206 offset:0x6600
	ds_read_b64_tr_b16 v[104:105], v206 offset:0x6e00
	v_mfma_f32_32x32x16_bf16 v[32:47], v[90:93], v[106:109], v[32:47]
	ds_read_b64_tr_b16 v[106:107], v206 offset:0x7600
	ds_read_b64_tr_b16 v[108:109], v206 offset:0x7e00
	s_waitcnt lgkmcnt(0)
	v_mfma_f32_32x32x16_bf16 v[48:63], v[72:75], v[94:97], v[48:63]
	v_exp_f32_e32 v64, v64
	v_exp_f32_e32 v65, v65
	v_exp_f32_e32 v66, v66
	v_exp_f32_e32 v67, v67
	v_exp_f32_e32 v68, v68
	v_exp_f32_e32 v69, v69
	v_exp_f32_e32 v70, v70
	v_mfma_f32_32x32x16_bf16 v[48:63], v[76:79], v[98:101], v[48:63]
	v_exp_f32_e32 v71, v71
	v_mfma_f32_32x32x16_bf16 v[48:63], v[80:83], v[102:105], v[48:63]
	v_mfma_f32_32x32x16_bf16 v[48:63], v[90:93], v[106:109], v[48:63]
	v_add_f32_e32 v72, 0, v64
	v_add_f32_e32 v72, v65, v72
	v_add_f32_e32 v72, v66, v72
	v_add_f32_e32 v72, v67, v72
	v_add_f32_e32 v72, v68, v72
	v_add_f32_e32 v72, v69, v72
	v_add_f32_e32 v72, v70, v72
	v_add_f32_e32 v72, v71, v72
	v_add_f32_e32 v85, 0, v72
	v_mov_b32_e32 v87, v85
	s_nop 1
	v_permlane32_swap_b32_e32 v85, v87
	v_cvt_pk_bf16_f32 v64, v64, v65
	v_cvt_pk_bf16_f32 v65, v66, v67
	v_cvt_pk_bf16_f32 v66, v68, v69
	v_cvt_pk_bf16_f32 v67, v70, v71
	v_cvt_pk_bf16_f32 v68, v129, v129
	v_cvt_pk_bf16_f32 v69, v129, v129
	v_cvt_pk_bf16_f32 v70, v129, v129
	v_cvt_pk_bf16_f32 v71, v129, v129
	v_cvt_pk_bf16_f32 v72, v129, v129
	v_cvt_pk_bf16_f32 v73, v129, v129
	v_cvt_pk_bf16_f32 v74, v129, v129
	v_cvt_pk_bf16_f32 v75, v129, v129
	v_cvt_pk_bf16_f32 v76, v129, v129
	v_cvt_pk_bf16_f32 v77, v129, v129
	v_cvt_pk_bf16_f32 v78, v129, v129
	v_cvt_pk_bf16_f32 v79, v129, v129
	s_nop 0
	v_permlane32_swap_b32_e32 v64, v66
	v_permlane32_swap_b32_e32 v65, v67
	v_permlane32_swap_b32_e32 v68, v70
	v_permlane32_swap_b32_e32 v69, v71
	v_permlane32_swap_b32_e32 v72, v74
	v_permlane32_swap_b32_e32 v73, v75
	v_permlane32_swap_b32_e32 v76, v78
	v_permlane32_swap_b32_e32 v77, v79
	ds_read_b64_tr_b16 v[80:81], v206 offset:0x8000
	ds_read_b64_tr_b16 v[82:83], v206 offset:0x8800
	ds_read_b64_tr_b16 v[90:91], v206 offset:0x9000
	ds_read_b64_tr_b16 v[92:93], v206 offset:0x9800
	ds_read_b64_tr_b16 v[94:95], v206 offset:0xa000
	ds_read_b64_tr_b16 v[96:97], v206 offset:0xa800
	ds_read_b64_tr_b16 v[98:99], v206 offset:0xb000
	ds_read_b64_tr_b16 v[100:101], v206 offset:0xb800
	s_waitcnt lgkmcnt(0)
	s_nop 0
	v_mfma_f32_32x32x16_bf16 v[0:15], v[64:67], v[80:83], v[0:15]
	ds_read_b64_tr_b16 v[80:81], v206 offset:0x8200
	ds_read_b64_tr_b16 v[82:83], v206 offset:0x8a00
	v_mfma_f32_32x32x16_bf16 v[0:15], v[68:71], v[90:93], v[0:15]
	ds_read_b64_tr_b16 v[90:91], v206 offset:0x9200
	ds_read_b64_tr_b16 v[92:93], v206 offset:0x9a00
	v_mfma_f32_32x32x16_bf16 v[0:15], v[72:75], v[94:97], v[0:15]
	ds_read_b64_tr_b16 v[94:95], v206 offset:0xa200
	ds_read_b64_tr_b16 v[96:97], v206 offset:0xaa00
	v_mfma_f32_32x32x16_bf16 v[0:15], v[76:79], v[98:101], v[0:15]
	ds_read_b64_tr_b16 v[98:99], v206 offset:0xb200
	ds_read_b64_tr_b16 v[100:101], v206 offset:0xba00
	s_waitcnt lgkmcnt(0)
	v_mfma_f32_32x32x16_bf16 v[16:31], v[64:67], v[80:83], v[16:31]
	ds_read_b64_tr_b16 v[80:81], v206 offset:0x8400
	ds_read_b64_tr_b16 v[82:83], v206 offset:0x8c00
	v_mfma_f32_32x32x16_bf16 v[16:31], v[68:71], v[90:93], v[16:31]
	ds_read_b64_tr_b16 v[90:91], v206 offset:0x9400
	ds_read_b64_tr_b16 v[92:93], v206 offset:0x9c00
	v_mfma_f32_32x32x16_bf16 v[16:31], v[72:75], v[94:97], v[16:31]
	ds_read_b64_tr_b16 v[94:95], v206 offset:0xa400
	ds_read_b64_tr_b16 v[96:97], v206 offset:0xac00
	v_mfma_f32_32x32x16_bf16 v[16:31], v[76:79], v[98:101], v[16:31]
	ds_read_b64_tr_b16 v[98:99], v206 offset:0xb400
	ds_read_b64_tr_b16 v[100:101], v206 offset:0xbc00
	s_waitcnt lgkmcnt(0)
	v_mfma_f32_32x32x16_bf16 v[32:47], v[64:67], v[80:83], v[32:47]
	ds_read_b64_tr_b16 v[80:81], v206 offset:0x8600
	ds_read_b64_tr_b16 v[82:83], v206 offset:0x8e00
	v_mfma_f32_32x32x16_bf16 v[32:47], v[68:71], v[90:93], v[32:47]
	ds_read_b64_tr_b16 v[90:91], v206 offset:0x9600
	ds_read_b64_tr_b16 v[92:93], v206 offset:0x9e00
	v_mfma_f32_32x32x16_bf16 v[32:47], v[72:75], v[94:97], v[32:47]
	ds_read_b64_tr_b16 v[94:95], v206 offset:0xa600
	ds_read_b64_tr_b16 v[96:97], v206 offset:0xae00
	v_mfma_f32_32x32x16_bf16 v[32:47], v[76:79], v[98:101], v[32:47]
	ds_read_b64_tr_b16 v[98:99], v206 offset:0xb600
	ds_read_b64_tr_b16 v[100:101], v206 offset:0xbe00
	s_waitcnt lgkmcnt(0)
	v_mfma_f32_32x32x16_bf16 v[48:63], v[64:67], v[80:83], v[48:63]
	v_cmp_gt_u32_e32 vcc, 32, v190
	v_mfma_f32_32x32x16_bf16 v[48:63], v[68:71], v[90:93], v[48:63]
	v_mfma_f32_32x32x16_bf16 v[48:63], v[72:75], v[94:97], v[48:63]
	v_mfma_f32_32x32x16_bf16 v[48:63], v[76:79], v[98:101], v[48:63]
	s_and_saveexec_b64 s[28:29], vcc
	s_cbranch_execz .LBB0_309
	v_add_f32_e32 v64, v128, v218
	v_add_f32_e32 v66, v215, v64
	v_pk_add_f32 v[64:65], v[84:85], v[86:87]
	v_lshl_add_u32 v67, v192, 2, v88
	v_add_f32_e32 v64, v66, v64
	v_add_f32_e32 v64, v64, v65
	ds_write_b32 v67, v64
	s_branch .LBB0_309

; #define PG8_STAGE(bufoff, gbase, voff) do { _Pragma("unroll") for (int _i = 0; _i < 2; ++_i) \
;         __builtin_amdgcn_global_load_lds((const unsigned*)((const char*)(gbase) + (voff)[_i]), (PG8_LAS unsigned*)(lds + (bufoff) + ldsw + _i * 8192), 16, 0, 0); } while (0)
; #define PG8_LDA(dst, b, h) do { _Pragma("unroll") for (int m = 0; m < 4; ++m) _Pragma("unroll") for (int k = 0; k < 2; ++k) dst[m][k] = *(const PG8_LAS bf16x8*)(lds + PG8_SA(b, h) + aoff + m * 2048 + k * 1024); } while (0)
; #define PG8_LDB(dst, b, h) do { _Pragma("unroll") for (int n = 0; n < 2; ++n) _Pragma("unroll") for (int k = 0; k < 2; ++k) dst[n][k] = *(const PG8_LAS bf16x8*)(lds + PG8_SB(b, h) + boff + n * 2048 + k * 1024); } while (0)
; #define PG8_MMA(ai, bj, At, Bt) do { __builtin_amdgcn_s_setprio(1); _Pragma("unroll") for (int m = 0; m < 4; ++m) _Pragma("unroll") for (int n = 0; n < 2; ++n) _Pragma("unroll") for (int k = 0; k < 2; ++k) \
;         acc[ai][bj][m][n] = __builtin_amdgcn_mfma_f32_16x16x32_bf16(Bt[n][k], At[m][k], acc[ai][bj][m][n], 0, 0, 0); __builtin_amdgcn_s_setprio(0); } while (0)
; #define PG8_WAIT_V(n) asm volatile("s_waitcnt vmcnt(" #n ")" ::: "memory")
; #define PG8_BAR __builtin_amdgcn_s_barrier()
; template <class Epi, class Sched, bool ALIGN_EPI = false, bool SP2 = false>
; __device__ __forceinline__ void gemm_phase(PG8_LAS unsigned char* lds, const Gemm g, const Sched& S, const Epi& E) {
;     ...
;         for (int t = 0; t < ntu; t += 2) {
;             const bool last = (t == ntu - 2);
;             const char* a1 = cA + (size_t)(t + 1) * kstep;
;             const char* a2 = last ? nA : cA + (size_t)(t + 2) * kstep; const char* b2 = last ? nB : cB + (size_t)(t + 2) * kstep;
;             const char* a3 = a2 + kstep; const char* b3 = b2 + kstep;
;             if (last && has_next) S.a_ready(nxt);
;             if constexpr (SP2) {
;             PG8_LDB(B0, 0, 0); PG8_LDB(B1, 0, 1); PG8_SCHED; PG8_LDA(At, 0, 0); PG8_STAGE(PG8_SA(1, 1), a1 + hstep, voffA);
;             PG8_WAIT_V(8); PG8_WAIT_L(0); PG8_BAR; PG8_MMA(0, 0, At, B0); PG8_MMA(0, 1, At, B1); PG8_BAR; PG8_SCHED;
;             PG8_LDA(At, 0, 1); PG8_STAGE(PG8_SB(0, 0), b2, voffB); PG8_STAGE(PG8_SB(0, 1), b2 + hstep, voffB); PG8_STAGE(PG8_SA(0, 0), a2, voffA);
;             PG8_WAIT_V(8); PG8_WAIT_L(0); PG8_BAR; if (full) { PG8_MMA(1, 0, At, B0); PG8_MMA(1, 1, At, B1); } PG8_BAR; PG8_SCHED;
.LBB0_500:
	s_add_u32 s2, s80, 0xfffc0080
	s_addc_u32 s3, s81, -1
	s_add_i32 s4, 0, 0x10000
	s_cmp_eq_u32 s90, 12
	s_cselect_b32 s31, s1, s3
	s_cselect_b32 s30, s35, s2
	v_add_u32_e32 v128, s4, v226
	s_cselect_b32 s29, s51, s89
	s_cselect_b32 s28, s87, s88
	s_add_i32 s5, 0, 0x14000
	ds_read_b128 v[146:149], v128
	ds_read_b128 v[150:153], v128 offset:1024
	ds_read_b128 v[154:157], v128 offset:2048
	ds_read_b128 v[158:161], v128 offset:3072
	v_add_u32_e32 v128, s5, v226
	ds_read_b128 v[130:133], v128
	ds_read_b128 v[134:137], v128 offset:1024
	ds_read_b128 v[138:141], v128 offset:2048
	ds_read_b128 v[142:145], v128 offset:3072
	v_lshl_add_u64 v[196:197], s[80:81], 0, v[214:215]
	s_add_i32 m0, s65, 0xc000
	s_waitcnt lgkmcnt(7)
	ds_read_b128 v[162:165], v228
	ds_read_b128 v[166:169], v228 offset:1024
	ds_read_b128 v[170:173], v228 offset:2048
	ds_read_b128 v[174:177], v228 offset:3072
	ds_read_b128 v[178:181], v228 offset:4096
	ds_read_b128 v[182:185], v228 offset:5120
	ds_read_b128 v[186:189], v228 offset:6144
	ds_read_b128 v[190:193], v228 offset:7168
	global_load_lds_dwordx4 v[196:197], off
	v_lshl_add_u64 v[196:197], s[80:81], 0, v[216:217]
	s_add_i32 m0, s65, 0xe000
	s_nop 0
	global_load_lds_dwordx4 v[196:197], off
	s_waitcnt vmcnt(8)
	s_waitcnt lgkmcnt(0)
	s_barrier
	s_setprio 1
	s_waitcnt lgkmcnt(0)
	v_mfma_f32_16x16x32_bf16 v[124:127], v[146:149], v[162:165], v[124:127]
	v_mfma_f32_16x16x32_bf16 v[120:123], v[154:157], v[162:165], v[120:123]
	v_mfma_f32_16x16x32_bf16 v[108:111], v[146:149], v[170:173], v[108:111]
	v_mfma_f32_16x16x32_bf16 v[104:107], v[154:157], v[170:173], v[104:107]
	v_mfma_f32_16x16x32_bf16 v[92:95], v[146:149], v[178:181], v[92:95]
	v_mfma_f32_16x16x32_bf16 v[88:91], v[154:157], v[178:181], v[88:91]
	v_mfma_f32_16x16x32_bf16 v[76:79], v[146:149], v[186:189], v[76:79]
	v_mfma_f32_16x16x32_bf16 v[72:75], v[154:157], v[186:189], v[72:75]
	v_mfma_f32_16x16x32_bf16 v[124:127], v[150:153], v[166:169], v[124:127]
	v_mfma_f32_16x16x32_bf16 v[120:123], v[158:161], v[166:169], v[120:123]
	v_mfma_f32_16x16x32_bf16 v[108:111], v[150:153], v[174:177], v[108:111]
	v_mfma_f32_16x16x32_bf16 v[104:107], v[158:161], v[174:177], v[104:107]
	v_mfma_f32_16x16x32_bf16 v[92:95], v[150:153], v[182:185], v[92:95]
	v_mfma_f32_16x16x32_bf16 v[88:91], v[158:161], v[182:185], v[88:91]
	v_mfma_f32_16x16x32_bf16 v[76:79], v[150:153], v[190:193], v[76:79]
	v_mfma_f32_16x16x32_bf16 v[72:75], v[158:161], v[190:193], v[72:75]
	s_setprio 0
	s_setprio 1
	v_mfma_f32_16x16x32_bf16 v[116:119], v[130:133], v[162:165], v[116:119]
	v_mfma_f32_16x16x32_bf16 v[112:115], v[138:141], v[162:165], v[112:115]
	v_mfma_f32_16x16x32_bf16 v[100:103], v[130:133], v[170:173], v[100:103]
	v_mfma_f32_16x16x32_bf16 v[96:99], v[138:141], v[170:173], v[96:99]
	v_mfma_f32_16x16x32_bf16 v[84:87], v[130:133], v[178:181], v[84:87]
	v_mfma_f32_16x16x32_bf16 v[80:83], v[138:141], v[178:181], v[80:83]
	v_mfma_f32_16x16x32_bf16 v[68:71], v[130:133], v[186:189], v[68:71]
	v_mfma_f32_16x16x32_bf16 v[64:67], v[138:141], v[186:189], v[64:67]
	v_mfma_f32_16x16x32_bf16 v[116:119], v[134:137], v[166:169], v[116:119]
	v_mfma_f32_16x16x32_bf16 v[112:115], v[142:145], v[166:169], v[112:115]
	v_mfma_f32_16x16x32_bf16 v[100:103], v[134:137], v[174:177], v[100:103]
	v_mfma_f32_16x16x32_bf16 v[96:99], v[142:145], v[174:177], v[96:99]
	v_mfma_f32_16x16x32_bf16 v[84:87], v[134:137], v[182:185], v[84:87]
	v_mfma_f32_16x16x32_bf16 v[80:83], v[142:145], v[182:185], v[80:83]
	v_mfma_f32_16x16x32_bf16 v[68:71], v[134:137], v[190:193], v[68:71]
	v_mfma_f32_16x16x32_bf16 v[64:67], v[142:145], v[190:193], v[64:67]
	s_setprio 0
	s_barrier
	s_add_i32 s2, s4, s64
	v_lshl_add_u64 v[218:219], s[28:29], 0, v[208:209]
	s_mov_b32 m0, s2
	ds_read_b128 v[186:189], v228 offset:16384
	ds_read_b128 v[190:193], v228 offset:17408
	ds_read_b128 v[178:181], v228 offset:18432
	ds_read_b128 v[182:185], v228 offset:19456
	ds_read_b128 v[170:173], v228 offset:20480
	ds_read_b128 v[174:177], v228 offset:21504
	ds_read_b128 v[162:165], v228 offset:22528
	ds_read_b128 v[166:169], v228 offset:23552
	global_load_lds_dwordx4 v[218:219], off
	s_add_i32 m0, s2, 0x2000
	s_add_u32 s2, s28, 0x40000
	v_lshl_add_u64 v[220:221], s[28:29], 0, v[212:213]
	s_addc_u32 s3, s29, 0
	s_add_i32 s4, s5, s64
	global_load_lds_dwordx4 v[220:221], off
	v_lshl_add_u64 v[196:197], s[2:3], 0, v[208:209]
	s_mov_b32 m0, s4
	v_lshl_add_u64 v[222:223], s[30:31], 0, v[206:207]
	global_load_lds_dwordx4 v[196:197], off
	v_lshl_add_u64 v[196:197], s[2:3], 0, v[212:213]
	s_add_i32 m0, s4, 0x2000
	v_lshl_add_u64 v[224:225], s[30:31], 0, v[210:211]
	global_load_lds_dwordx4 v[196:197], off
	s_mov_b32 m0, s65
	v_cndmask_b32_e64 v128, 0, 1, s[78:79]
	global_load_lds_dwordx4 v[222:223], off
	s_mov_b32 m0, s70
	v_cmp_ne_u32_e64 s[38:39], 1, v128
	global_load_lds_dwordx4 v[224:225], off
	s_waitcnt vmcnt(8)
	s_waitcnt lgkmcnt(0)
	s_andn2_b64 vcc, exec, s[78:79]
	s_barrier
	s_cbranch_vccnz .LBB0_502
; #define PG8_STAGE(bufoff, gbase, voff) do { _Pragma("unroll") for (int _i = 0; _i < 2; ++_i) \
;         __builtin_amdgcn_global_load_lds((const unsigned*)((const char*)(gbase) + (voff)[_i]), (PG8_LAS unsigned*)(lds + (bufoff) + ldsw + _i * 8192), 16, 0, 0); } while (0)
; #define PG8_LDA(dst, b, h) do { _Pragma("unroll") for (int m = 0; m < 4; ++m) _Pragma("unroll") for (int k = 0; k < 2; ++k) dst[m][k] = *(const PG8_LAS bf16x8*)(lds + PG8_SA(b, h) + aoff + m * 2048 + k * 1024); } while (0)
; #define PG8_LDB(dst, b, h) do { _Pragma("unroll") for (int n = 0; n < 2; ++n) _Pragma("unroll") for (int k = 0; k < 2; ++k) dst[n][k] = *(const PG8_LAS bf16x8*)(lds + PG8_SB(b, h) + boff + n * 2048 + k * 1024); } while (0)
; #define PG8_MMA(ai, bj, At, Bt) do { __builtin_amdgcn_s_setprio(1); _Pragma("unroll") for (int m = 0; m < 4; ++m) _Pragma("unroll") for (int n = 0; n < 2; ++n) _Pragma("unroll") for (int k = 0; k < 2; ++k) \
;         acc[ai][bj][m][n] = __builtin_amdgcn_mfma_f32_16x16x32_bf16(Bt[n][k], At[m][k], acc[ai][bj][m][n], 0, 0, 0); __builtin_amdgcn_s_setprio(0); } while (0)
; #define PG8_WAIT_V(n) asm volatile("s_waitcnt vmcnt(" #n ")" ::: "memory")
; #define PG8_WAIT_L(n) asm volatile("s_waitcnt lgkmcnt(" #n ")" ::: "memory")
; #define PG8_BAR __builtin_amdgcn_s_barrier()
; #define PG8_SCHED __builtin_amdgcn_sched_barrier(0)
; template <class Epi, class Sched, bool ALIGN_EPI = false, bool SP2 = false>
; __device__ __forceinline__ void gemm_phase(PG8_LAS unsigned char* lds, const Gemm g, const Sched& S, const Epi& E) {
;     ...
;             PG8_WAIT_V(8); PG8_WAIT_L(0); PG8_BAR; if (full) { PG8_MMA(1, 0, At, B0); PG8_MMA(1, 1, At, B1); } PG8_BAR; PG8_SCHED;
;             PG8_LDB(B0, 1, 0); PG8_LDB(B1, 1, 1); PG8_SCHED; PG8_LDA(At, 1, 0); PG8_STAGE(PG8_SA(0, 1), a2 + hstep, voffA);
;             PG8_WAIT_V(8); PG8_WAIT_L(0); PG8_BAR; PG8_MMA(0, 0, At, B0); PG8_MMA(0, 1, At, B1); PG8_BAR; PG8_SCHED;
	s_setprio 1
	s_waitcnt lgkmcnt(0)
	v_mfma_f32_16x16x32_bf16 v[60:63], v[146:149], v[186:189], v[60:63]
	v_mfma_f32_16x16x32_bf16 v[56:59], v[154:157], v[186:189], v[56:59]
	v_mfma_f32_16x16x32_bf16 v[44:47], v[146:149], v[178:181], v[44:47]
	v_mfma_f32_16x16x32_bf16 v[40:43], v[154:157], v[178:181], v[40:43]
	v_mfma_f32_16x16x32_bf16 v[28:31], v[146:149], v[170:173], v[28:31]
	v_mfma_f32_16x16x32_bf16 v[24:27], v[154:157], v[170:173], v[24:27]
	v_mfma_f32_16x16x32_bf16 v[12:15], v[146:149], v[162:165], v[12:15]
	v_mfma_f32_16x16x32_bf16 v[8:11], v[154:157], v[162:165], v[8:11]
	v_mfma_f32_16x16x32_bf16 v[60:63], v[150:153], v[190:193], v[60:63]
	v_mfma_f32_16x16x32_bf16 v[56:59], v[158:161], v[190:193], v[56:59]
	v_mfma_f32_16x16x32_bf16 v[44:47], v[150:153], v[182:185], v[44:47]
	v_mfma_f32_16x16x32_bf16 v[40:43], v[158:161], v[182:185], v[40:43]
	v_mfma_f32_16x16x32_bf16 v[28:31], v[150:153], v[174:177], v[28:31]
	v_mfma_f32_16x16x32_bf16 v[24:27], v[158:161], v[174:177], v[24:27]
	v_mfma_f32_16x16x32_bf16 v[12:15], v[150:153], v[166:169], v[12:15]
	v_mfma_f32_16x16x32_bf16 v[8:11], v[158:161], v[166:169], v[8:11]
	s_setprio 0
	s_setprio 1
	v_mfma_f32_16x16x32_bf16 v[52:55], v[130:133], v[186:189], v[52:55]
	v_mfma_f32_16x16x32_bf16 v[48:51], v[138:141], v[186:189], v[48:51]
	v_mfma_f32_16x16x32_bf16 v[36:39], v[130:133], v[178:181], v[36:39]
	v_mfma_f32_16x16x32_bf16 v[32:35], v[138:141], v[178:181], v[32:35]
	v_mfma_f32_16x16x32_bf16 v[20:23], v[130:133], v[170:173], v[20:23]
	v_mfma_f32_16x16x32_bf16 v[16:19], v[138:141], v[170:173], v[16:19]
	v_mfma_f32_16x16x32_bf16 v[4:7], v[130:133], v[162:165], v[4:7]
	v_mfma_f32_16x16x32_bf16 v[0:3], v[138:141], v[162:165], v[0:3]
	v_mfma_f32_16x16x32_bf16 v[52:55], v[134:137], v[190:193], v[52:55]
	v_mfma_f32_16x16x32_bf16 v[48:51], v[142:145], v[190:193], v[48:51]
	v_mfma_f32_16x16x32_bf16 v[36:39], v[134:137], v[182:185], v[36:39]
	v_mfma_f32_16x16x32_bf16 v[32:35], v[142:145], v[182:185], v[32:35]
	v_mfma_f32_16x16x32_bf16 v[20:23], v[134:137], v[174:177], v[20:23]
	v_mfma_f32_16x16x32_bf16 v[16:19], v[142:145], v[174:177], v[16:19]
	v_mfma_f32_16x16x32_bf16 v[4:7], v[134:137], v[166:169], v[4:7]
	v_mfma_f32_16x16x32_bf16 v[0:3], v[142:145], v[166:169], v[0:3]
	s_setprio 0
.LBB0_502:
	s_barrier
	s_add_i32 s4, 0, 0x18000
	v_add_u32_e32 v128, s4, v226
	s_add_i32 s5, 0, 0x1c000
	ds_read_b128 v[146:149], v128
	ds_read_b128 v[150:153], v128 offset:1024
	ds_read_b128 v[154:157], v128 offset:2048
	ds_read_b128 v[158:161], v128 offset:3072
	v_add_u32_e32 v128, s5, v226
	ds_read_b128 v[130:133], v128
	ds_read_b128 v[134:137], v128 offset:1024
	ds_read_b128 v[138:141], v128 offset:2048
	ds_read_b128 v[142:145], v128 offset:3072
	s_add_u32 s2, s30, 0x40000
	s_addc_u32 s3, s31, 0
	s_mov_b32 m0, s71
	v_lshl_add_u64 v[196:197], s[2:3], 0, v[206:207]
	s_waitcnt lgkmcnt(7)
	ds_read_b128 v[162:165], v228 offset:32768
	ds_read_b128 v[166:169], v228 offset:33792
	ds_read_b128 v[170:173], v228 offset:34816
	ds_read_b128 v[174:177], v228 offset:35840
	ds_read_b128 v[178:181], v228 offset:36864
	ds_read_b128 v[182:185], v228 offset:37888
	ds_read_b128 v[186:189], v228 offset:38912
	ds_read_b128 v[190:193], v228 offset:39936
	global_load_lds_dwordx4 v[196:197], off
	v_lshl_add_u64 v[196:197], s[2:3], 0, v[210:211]
	s_mov_b32 m0, s77
	s_nop 0
	global_load_lds_dwordx4 v[196:197], off
	s_waitcnt vmcnt(8)
	s_waitcnt lgkmcnt(0)
	s_barrier
	s_setprio 1
	s_waitcnt lgkmcnt(0)
	v_mfma_f32_16x16x32_bf16 v[124:127], v[146:149], v[162:165], v[124:127]
	v_mfma_f32_16x16x32_bf16 v[120:123], v[154:157], v[162:165], v[120:123]
	v_mfma_f32_16x16x32_bf16 v[108:111], v[146:149], v[170:173], v[108:111]
	v_mfma_f32_16x16x32_bf16 v[104:107], v[154:157], v[170:173], v[104:107]
	v_mfma_f32_16x16x32_bf16 v[92:95], v[146:149], v[178:181], v[92:95]
	v_mfma_f32_16x16x32_bf16 v[88:91], v[154:157], v[178:181], v[88:91]
	v_mfma_f32_16x16x32_bf16 v[76:79], v[146:149], v[186:189], v[76:79]
	v_mfma_f32_16x16x32_bf16 v[72:75], v[154:157], v[186:189], v[72:75]
	v_mfma_f32_16x16x32_bf16 v[124:127], v[150:153], v[166:169], v[124:127]
	v_mfma_f32_16x16x32_bf16 v[120:123], v[158:161], v[166:169], v[120:123]
	v_mfma_f32_16x16x32_bf16 v[108:111], v[150:153], v[174:177], v[108:111]
	v_mfma_f32_16x16x32_bf16 v[104:107], v[158:161], v[174:177], v[104:107]
	v_mfma_f32_16x16x32_bf16 v[92:95], v[150:153], v[182:185], v[92:95]
	v_mfma_f32_16x16x32_bf16 v[88:91], v[158:161], v[182:185], v[88:91]
	v_mfma_f32_16x16x32_bf16 v[76:79], v[150:153], v[190:193], v[76:79]
	v_mfma_f32_16x16x32_bf16 v[72:75], v[158:161], v[190:193], v[72:75]
	s_setprio 0
	s_setprio 1
	v_mfma_f32_16x16x32_bf16 v[116:119], v[130:133], v[162:165], v[116:119]
	v_mfma_f32_16x16x32_bf16 v[112:115], v[138:141], v[162:165], v[112:115]
	v_mfma_f32_16x16x32_bf16 v[100:103], v[130:133], v[170:173], v[100:103]
	v_mfma_f32_16x16x32_bf16 v[96:99], v[138:141], v[170:173], v[96:99]
	v_mfma_f32_16x16x32_bf16 v[84:87], v[130:133], v[178:181], v[84:87]
	v_mfma_f32_16x16x32_bf16 v[80:83], v[138:141], v[178:181], v[80:83]
	v_mfma_f32_16x16x32_bf16 v[68:71], v[130:133], v[186:189], v[68:71]
	v_mfma_f32_16x16x32_bf16 v[64:67], v[138:141], v[186:189], v[64:67]
	v_mfma_f32_16x16x32_bf16 v[116:119], v[134:137], v[166:169], v[116:119]
	v_mfma_f32_16x16x32_bf16 v[112:115], v[142:145], v[166:169], v[112:115]
	v_mfma_f32_16x16x32_bf16 v[100:103], v[134:137], v[174:177], v[100:103]
	v_mfma_f32_16x16x32_bf16 v[96:99], v[142:145], v[174:177], v[96:99]
	v_mfma_f32_16x16x32_bf16 v[84:87], v[134:137], v[182:185], v[84:87]
	v_mfma_f32_16x16x32_bf16 v[80:83], v[142:145], v[182:185], v[80:83]
	v_mfma_f32_16x16x32_bf16 v[68:71], v[134:137], v[190:193], v[68:71]
	v_mfma_f32_16x16x32_bf16 v[64:67], v[142:145], v[190:193], v[64:67]
	s_setprio 0
	s_barrier
; #define PG8_STAGE(bufoff, gbase, voff) do { _Pragma("unroll") for (int _i = 0; _i < 2; ++_i) \
;         __builtin_amdgcn_global_load_lds((const unsigned*)((const char*)(gbase) + (voff)[_i]), (PG8_LAS unsigned*)(lds + (bufoff) + ldsw + _i * 8192), 16, 0, 0); } while (0)
; #define PG8_LDA(dst, b, h) do { _Pragma("unroll") for (int m = 0; m < 4; ++m) _Pragma("unroll") for (int k = 0; k < 2; ++k) dst[m][k] = *(const PG8_LAS bf16x8*)(lds + PG8_SA(b, h) + aoff + m * 2048 + k * 1024); } while (0)
; #define PG8_LDB(dst, b, h) do { _Pragma("unroll") for (int n = 0; n < 2; ++n) _Pragma("unroll") for (int k = 0; k < 2; ++k) dst[n][k] = *(const PG8_LAS bf16x8*)(lds + PG8_SB(b, h) + boff + n * 2048 + k * 1024); } while (0)
; #define PG8_WAIT_V(n) asm volatile("s_waitcnt vmcnt(" #n ")" ::: "memory")
; #define PG8_WAIT_L(n) asm volatile("s_waitcnt lgkmcnt(" #n ")" ::: "memory")
; #define PG8_BAR __builtin_amdgcn_s_barrier()
; #define PG8_SCHED __builtin_amdgcn_sched_barrier(0)
; template <class Epi, class Sched, bool ALIGN_EPI = false, bool SP2 = false>
; __device__ __forceinline__ void gemm_phase(PG8_LAS unsigned char* lds, const Gemm g, const Sched& S, const Epi& E) {
;     ...
;             const char* a3 = a2 + kstep; const char* b3 = b2 + kstep;
;             if (last && has_next) S.a_ready(nxt);
;             if constexpr (SP2) {
;             PG8_LDB(B0, 0, 0); PG8_LDB(B1, 0, 1); PG8_SCHED; PG8_LDA(At, 0, 0); PG8_STAGE(PG8_SA(1, 1), a1 + hstep, voffA);
;             PG8_WAIT_V(8); PG8_WAIT_L(0); PG8_BAR; PG8_MMA(0, 0, At, B0); PG8_MMA(0, 1, At, B1); PG8_BAR; PG8_SCHED;
;             PG8_LDA(At, 0, 1); PG8_STAGE(PG8_SB(0, 0), b2, voffB); PG8_STAGE(PG8_SB(0, 1), b2 + hstep, voffB); PG8_STAGE(PG8_SA(0, 0), a2, voffA);
;             PG8_WAIT_V(8); PG8_WAIT_L(0); PG8_BAR; if (full) { PG8_MMA(1, 0, At, B0); PG8_MMA(1, 1, At, B1); } PG8_BAR; PG8_SCHED;
;             PG8_LDB(B0, 1, 0); PG8_LDB(B1, 1, 1); PG8_SCHED; PG8_LDA(At, 1, 0); PG8_STAGE(PG8_SA(0, 1), a2 + hstep, voffA);
;             PG8_WAIT_V(8); PG8_WAIT_L(0); PG8_BAR; PG8_MMA(0, 0, At, B0); PG8_MMA(0, 1, At, B1); PG8_BAR; PG8_SCHED;
;             PG8_LDA(At, 1, 1); PG8_STAGE(PG8_SB(1, 0), b3, voffB); PG8_STAGE(PG8_SB(1, 1), b3 + hstep, voffB); PG8_STAGE(PG8_SA(1, 0), a3, voffA);
;             PG8_WAIT_V(8); PG8_WAIT_L(0); PG8_BAR; if (full) { PG8_MMA(1, 0, At, B0); PG8_MMA(1, 1, At, B1); } PG8_BAR; PG8_SCHED;
	s_add_i32 s2, s4, s64
	v_lshl_add_u64 v[196:197], v[218:219], 0, s[26:27]
	s_mov_b32 m0, s2
	ds_read_b128 v[186:189], v228 offset:49152
	ds_read_b128 v[190:193], v228 offset:50176
	ds_read_b128 v[178:181], v228 offset:51200
	ds_read_b128 v[182:185], v228 offset:52224
	ds_read_b128 v[170:173], v228 offset:53248
	ds_read_b128 v[174:177], v228 offset:54272
	ds_read_b128 v[162:165], v228 offset:55296
	ds_read_b128 v[166:169], v228 offset:56320
	global_load_lds_dwordx4 v[196:197], off
	s_add_i32 m0, s2, 0x2000
	s_add_u32 s2, s28, 0x40080
	v_lshl_add_u64 v[196:197], v[220:221], 0, s[26:27]
	s_addc_u32 s3, s29, 0
	s_add_i32 s4, s5, s64
	global_load_lds_dwordx4 v[196:197], off
	v_lshl_add_u64 v[196:197], s[2:3], 0, v[208:209]
	s_mov_b32 m0, s4
	s_and_b64 vcc, exec, s[38:39]
	global_load_lds_dwordx4 v[196:197], off
	v_lshl_add_u64 v[196:197], s[2:3], 0, v[212:213]
	s_add_i32 m0, s4, 0x2000
	s_nop 0
	global_load_lds_dwordx4 v[196:197], off
	v_lshl_add_u64 v[196:197], v[222:223], 0, s[26:27]
	s_mov_b32 m0, s82
	s_nop 0
	global_load_lds_dwordx4 v[196:197], off
	v_lshl_add_u64 v[196:197], v[224:225], 0, s[26:27]
	s_mov_b32 m0, s83
	s_nop 0
	global_load_lds_dwordx4 v[196:197], off
	s_waitcnt vmcnt(8)
	s_waitcnt lgkmcnt(0)
	s_barrier
	s_cbranch_vccnz .LBB0_499
	s_setprio 1
	s_waitcnt lgkmcnt(0)
	v_mfma_f32_16x16x32_bf16 v[60:63], v[146:149], v[186:189], v[60:63]
	v_mfma_f32_16x16x32_bf16 v[56:59], v[154:157], v[186:189], v[56:59]
	v_mfma_f32_16x16x32_bf16 v[44:47], v[146:149], v[178:181], v[44:47]
	v_mfma_f32_16x16x32_bf16 v[40:43], v[154:157], v[178:181], v[40:43]
	v_mfma_f32_16x16x32_bf16 v[28:31], v[146:149], v[170:173], v[28:31]
	v_mfma_f32_16x16x32_bf16 v[24:27], v[154:157], v[170:173], v[24:27]
	v_mfma_f32_16x16x32_bf16 v[12:15], v[146:149], v[162:165], v[12:15]
	v_mfma_f32_16x16x32_bf16 v[8:11], v[154:157], v[162:165], v[8:11]
	v_mfma_f32_16x16x32_bf16 v[60:63], v[150:153], v[190:193], v[60:63]
	v_mfma_f32_16x16x32_bf16 v[56:59], v[158:161], v[190:193], v[56:59]
	v_mfma_f32_16x16x32_bf16 v[44:47], v[150:153], v[182:185], v[44:47]
	v_mfma_f32_16x16x32_bf16 v[40:43], v[158:161], v[182:185], v[40:43]
	v_mfma_f32_16x16x32_bf16 v[28:31], v[150:153], v[174:177], v[28:31]
	v_mfma_f32_16x16x32_bf16 v[24:27], v[158:161], v[174:177], v[24:27]
	v_mfma_f32_16x16x32_bf16 v[12:15], v[150:153], v[166:169], v[12:15]
	v_mfma_f32_16x16x32_bf16 v[8:11], v[158:161], v[166:169], v[8:11]
	s_setprio 0
	s_setprio 1
	v_mfma_f32_16x16x32_bf16 v[52:55], v[130:133], v[186:189], v[52:55]
	v_mfma_f32_16x16x32_bf16 v[48:51], v[138:141], v[186:189], v[48:51]
	v_mfma_f32_16x16x32_bf16 v[36:39], v[130:133], v[178:181], v[36:39]
	v_mfma_f32_16x16x32_bf16 v[32:35], v[138:141], v[178:181], v[32:35]
	v_mfma_f32_16x16x32_bf16 v[20:23], v[130:133], v[170:173], v[20:23]
	v_mfma_f32_16x16x32_bf16 v[16:19], v[138:141], v[170:173], v[16:19]
	v_mfma_f32_16x16x32_bf16 v[4:7], v[130:133], v[162:165], v[4:7]
	v_mfma_f32_16x16x32_bf16 v[0:3], v[138:141], v[162:165], v[0:3]
	v_mfma_f32_16x16x32_bf16 v[52:55], v[134:137], v[190:193], v[52:55]
	v_mfma_f32_16x16x32_bf16 v[48:51], v[142:145], v[190:193], v[48:51]
	v_mfma_f32_16x16x32_bf16 v[36:39], v[134:137], v[182:185], v[36:39]
	v_mfma_f32_16x16x32_bf16 v[32:35], v[142:145], v[182:185], v[32:35]
	v_mfma_f32_16x16x32_bf16 v[20:23], v[134:137], v[174:177], v[20:23]
	v_mfma_f32_16x16x32_bf16 v[16:19], v[142:145], v[174:177], v[16:19]
	v_mfma_f32_16x16x32_bf16 v[4:7], v[134:137], v[166:169], v[4:7]
	v_mfma_f32_16x16x32_bf16 v[0:3], v[142:145], v[166:169], v[0:3]
	s_setprio 0
	s_branch .LBB0_499

; #define PG8_STAGE(bufoff, gbase, voff) do { _Pragma("unroll") for (int _i = 0; _i < 2; ++_i) \
;         __builtin_amdgcn_global_load_lds((const unsigned*)((const char*)(gbase) + (voff)[_i]), (PG8_LAS unsigned*)(lds + (bufoff) + ldsw + _i * 8192), 16, 0, 0); } while (0)
; #define PG8_LDA(dst, b, h) do { _Pragma("unroll") for (int m = 0; m < 4; ++m) _Pragma("unroll") for (int k = 0; k < 2; ++k) dst[m][k] = *(const PG8_LAS bf16x8*)(lds + PG8_SA(b, h) + aoff + m * 2048 + k * 1024); } while (0)
; #define PG8_LDB(dst, b, h) do { _Pragma("unroll") for (int n = 0; n < 2; ++n) _Pragma("unroll") for (int k = 0; k < 2; ++k) dst[n][k] = *(const PG8_LAS bf16x8*)(lds + PG8_SB(b, h) + boff + n * 2048 + k * 1024); } while (0)
; #define PG8_MMA(ai, bj, At, Bt) do { __builtin_amdgcn_s_setprio(1); _Pragma("unroll") for (int m = 0; m < 4; ++m) _Pragma("unroll") for (int n = 0; n < 2; ++n) _Pragma("unroll") for (int k = 0; k < 2; ++k) \
;         acc[ai][bj][m][n] = __builtin_amdgcn_mfma_f32_16x16x32_bf16(Bt[n][k], At[m][k], acc[ai][bj][m][n], 0, 0, 0); __builtin_amdgcn_s_setprio(0); } while (0)
; #define PG8_WAIT_V(n) asm volatile("s_waitcnt vmcnt(" #n ")" ::: "memory")
; #define PG8_BAR __builtin_amdgcn_s_barrier()
; template <class Epi, class Sched, bool ALIGN_EPI = false, bool SP2 = false>
; __device__ __forceinline__ void gemm_phase(PG8_LAS unsigned char* lds, const Gemm g, const Sched& S, const Epi& E) {
;     ...
;         for (int t = 0; t < ntu; t += 2) {
;             const bool last = (t == ntu - 2);
;             const char* a1 = cA + (size_t)(t + 1) * kstep;
;             const char* a2 = last ? nA : cA + (size_t)(t + 2) * kstep; const char* b2 = last ? nB : cB + (size_t)(t + 2) * kstep;
;             const char* a3 = a2 + kstep; const char* b3 = b2 + kstep;
;             if (last && has_next) S.a_ready(nxt);
;             if constexpr (SP2) {
;             PG8_LDB(B0, 0, 0); PG8_LDB(B1, 0, 1); PG8_SCHED; PG8_LDA(At, 0, 0); PG8_STAGE(PG8_SA(1, 1), a1 + hstep, voffA);
;             PG8_WAIT_V(8); PG8_WAIT_L(0); PG8_BAR; PG8_MMA(0, 0, At, B0); PG8_MMA(0, 1, At, B1); PG8_BAR; PG8_SCHED;
;             PG8_LDA(At, 0, 1); PG8_STAGE(PG8_SB(0, 0), b2, voffB); PG8_STAGE(PG8_SB(0, 1), b2 + hstep, voffB); PG8_STAGE(PG8_SA(0, 0), a2, voffA);
;             PG8_WAIT_V(8); PG8_WAIT_L(0); PG8_BAR; if (full) { PG8_MMA(1, 0, At, B0); PG8_MMA(1, 1, At, B1); } PG8_BAR; PG8_SCHED;
.LBB0_916:
	s_add_u32 s2, s48, 0xfffc0080
	s_addc_u32 s3, s49, -1
	s_add_i32 s4, 0, 0x10000
	s_cmp_eq_u32 s79, s51
	s_cselect_b32 s35, s85, s3
	s_cselect_b32 s34, s84, s2
	v_add_u32_e32 v128, s4, v195
	s_cselect_b32 s29, s87, s50
	s_cselect_b32 s28, s86, s83
	s_add_i32 s5, 0, 0x14000
	ds_read_b128 v[146:149], v128
	ds_read_b128 v[150:153], v128 offset:1024
	ds_read_b128 v[154:157], v128 offset:2048
	ds_read_b128 v[158:161], v128 offset:3072
	v_add_u32_e32 v128, s5, v195
	ds_read_b128 v[130:133], v128
	ds_read_b128 v[134:137], v128 offset:1024
	ds_read_b128 v[138:141], v128 offset:2048
	ds_read_b128 v[142:145], v128 offset:3072
	v_lshl_add_u64 v[196:197], s[48:49], 0, v[218:219]
	s_add_i32 m0, s70, 0xc000
	s_waitcnt lgkmcnt(7)
	ds_read_b128 v[162:165], v242
	ds_read_b128 v[166:169], v242 offset:1024
	ds_read_b128 v[170:173], v242 offset:2048
	ds_read_b128 v[174:177], v242 offset:3072
	ds_read_b128 v[178:181], v242 offset:4096
	ds_read_b128 v[182:185], v242 offset:5120
	ds_read_b128 v[186:189], v242 offset:6144
	ds_read_b128 v[190:193], v242 offset:7168
	global_load_lds_dwordx4 v[196:197], off
	v_lshl_add_u64 v[196:197], s[48:49], 0, v[220:221]
	s_add_i32 m0, s70, 0xe000
	s_nop 0
	global_load_lds_dwordx4 v[196:197], off
	s_waitcnt vmcnt(8)
	s_waitcnt lgkmcnt(0)
	s_barrier
	s_setprio 1
	s_waitcnt lgkmcnt(0)
	v_mfma_f32_16x16x32_bf16 v[124:127], v[146:149], v[162:165], v[124:127]
	v_mfma_f32_16x16x32_bf16 v[120:123], v[154:157], v[162:165], v[120:123]
	v_mfma_f32_16x16x32_bf16 v[116:119], v[146:149], v[170:173], v[116:119]
	v_mfma_f32_16x16x32_bf16 v[112:115], v[154:157], v[170:173], v[112:115]
	v_mfma_f32_16x16x32_bf16 v[104:107], v[146:149], v[178:181], v[104:107]
	v_mfma_f32_16x16x32_bf16 v[96:99], v[154:157], v[178:181], v[96:99]
	v_mfma_f32_16x16x32_bf16 v[88:91], v[146:149], v[186:189], v[88:91]
	v_mfma_f32_16x16x32_bf16 v[80:83], v[154:157], v[186:189], v[80:83]
	v_mfma_f32_16x16x32_bf16 v[124:127], v[150:153], v[166:169], v[124:127]
	v_mfma_f32_16x16x32_bf16 v[120:123], v[158:161], v[166:169], v[120:123]
	v_mfma_f32_16x16x32_bf16 v[116:119], v[150:153], v[174:177], v[116:119]
	v_mfma_f32_16x16x32_bf16 v[112:115], v[158:161], v[174:177], v[112:115]
	v_mfma_f32_16x16x32_bf16 v[104:107], v[150:153], v[182:185], v[104:107]
	v_mfma_f32_16x16x32_bf16 v[96:99], v[158:161], v[182:185], v[96:99]
	v_mfma_f32_16x16x32_bf16 v[88:91], v[150:153], v[190:193], v[88:91]
	v_mfma_f32_16x16x32_bf16 v[80:83], v[158:161], v[190:193], v[80:83]
	s_setprio 0
	s_setprio 1
	v_mfma_f32_16x16x32_bf16 v[108:111], v[130:133], v[162:165], v[108:111]
	v_mfma_f32_16x16x32_bf16 v[100:103], v[138:141], v[162:165], v[100:103]
	v_mfma_f32_16x16x32_bf16 v[92:95], v[130:133], v[170:173], v[92:95]
	v_mfma_f32_16x16x32_bf16 v[84:87], v[138:141], v[170:173], v[84:87]
	v_mfma_f32_16x16x32_bf16 v[76:79], v[130:133], v[178:181], v[76:79]
	v_mfma_f32_16x16x32_bf16 v[72:75], v[138:141], v[178:181], v[72:75]
	v_mfma_f32_16x16x32_bf16 v[68:71], v[130:133], v[186:189], v[68:71]
	v_mfma_f32_16x16x32_bf16 v[56:59], v[138:141], v[186:189], v[56:59]
	v_mfma_f32_16x16x32_bf16 v[108:111], v[134:137], v[166:169], v[108:111]
	v_mfma_f32_16x16x32_bf16 v[100:103], v[142:145], v[166:169], v[100:103]
	v_mfma_f32_16x16x32_bf16 v[92:95], v[134:137], v[174:177], v[92:95]
	v_mfma_f32_16x16x32_bf16 v[84:87], v[142:145], v[174:177], v[84:87]
	v_mfma_f32_16x16x32_bf16 v[76:79], v[134:137], v[182:185], v[76:79]
	v_mfma_f32_16x16x32_bf16 v[72:75], v[142:145], v[182:185], v[72:75]
	v_mfma_f32_16x16x32_bf16 v[68:71], v[134:137], v[190:193], v[68:71]
	v_mfma_f32_16x16x32_bf16 v[56:59], v[142:145], v[190:193], v[56:59]
	s_setprio 0
	s_barrier
	s_add_i32 s2, s4, s65
	v_lshl_add_u64 v[222:223], s[28:29], 0, v[208:209]
	s_mov_b32 m0, s2
	ds_read_b128 v[186:189], v242 offset:16384
	ds_read_b128 v[190:193], v242 offset:17408
	ds_read_b128 v[178:181], v242 offset:18432
	ds_read_b128 v[182:185], v242 offset:19456
	ds_read_b128 v[170:173], v242 offset:20480
	ds_read_b128 v[174:177], v242 offset:21504
	ds_read_b128 v[162:165], v242 offset:22528
	ds_read_b128 v[166:169], v242 offset:23552
	global_load_lds_dwordx4 v[222:223], off
	s_add_i32 m0, s2, 0x2000
	s_add_u32 s2, s28, 0x40000
	v_lshl_add_u64 v[224:225], s[28:29], 0, v[212:213]
	s_addc_u32 s3, s29, 0
	s_add_i32 s4, s5, s65
	global_load_lds_dwordx4 v[224:225], off
	v_lshl_add_u64 v[196:197], s[2:3], 0, v[208:209]
	s_mov_b32 m0, s4
	v_lshl_add_u64 v[226:227], s[34:35], 0, v[206:207]
	global_load_lds_dwordx4 v[196:197], off
	v_lshl_add_u64 v[196:197], s[2:3], 0, v[212:213]
	s_add_i32 m0, s4, 0x2000
	v_lshl_add_u64 v[228:229], s[34:35], 0, v[210:211]
	global_load_lds_dwordx4 v[196:197], off
	s_mov_b32 m0, s70
	v_cndmask_b32_e64 v128, 0, 1, s[92:93]
	global_load_lds_dwordx4 v[226:227], off
	s_mov_b32 m0, s71
	v_cmp_ne_u32_e64 s[38:39], 1, v128
	global_load_lds_dwordx4 v[228:229], off
	s_waitcnt vmcnt(8)
	s_waitcnt lgkmcnt(0)
	s_andn2_b64 vcc, exec, s[92:93]
	s_barrier
	s_cbranch_vccnz .LBB0_918
; #define PG8_STAGE(bufoff, gbase, voff) do { _Pragma("unroll") for (int _i = 0; _i < 2; ++_i) \
;         __builtin_amdgcn_global_load_lds((const unsigned*)((const char*)(gbase) + (voff)[_i]), (PG8_LAS unsigned*)(lds + (bufoff) + ldsw + _i * 8192), 16, 0, 0); } while (0)
; #define PG8_LDA(dst, b, h) do { _Pragma("unroll") for (int m = 0; m < 4; ++m) _Pragma("unroll") for (int k = 0; k < 2; ++k) dst[m][k] = *(const PG8_LAS bf16x8*)(lds + PG8_SA(b, h) + aoff + m * 2048 + k * 1024); } while (0)
; #define PG8_LDB(dst, b, h) do { _Pragma("unroll") for (int n = 0; n < 2; ++n) _Pragma("unroll") for (int k = 0; k < 2; ++k) dst[n][k] = *(const PG8_LAS bf16x8*)(lds + PG8_SB(b, h) + boff + n * 2048 + k * 1024); } while (0)
; #define PG8_MMA(ai, bj, At, Bt) do { __builtin_amdgcn_s_setprio(1); _Pragma("unroll") for (int m = 0; m < 4; ++m) _Pragma("unroll") for (int n = 0; n < 2; ++n) _Pragma("unroll") for (int k = 0; k < 2; ++k) \
;         acc[ai][bj][m][n] = __builtin_amdgcn_mfma_f32_16x16x32_bf16(Bt[n][k], At[m][k], acc[ai][bj][m][n], 0, 0, 0); __builtin_amdgcn_s_setprio(0); } while (0)
; #define PG8_WAIT_V(n) asm volatile("s_waitcnt vmcnt(" #n ")" ::: "memory")
; #define PG8_WAIT_L(n) asm volatile("s_waitcnt lgkmcnt(" #n ")" ::: "memory")
; #define PG8_BAR __builtin_amdgcn_s_barrier()
; #define PG8_SCHED __builtin_amdgcn_sched_barrier(0)
; template <class Epi, class Sched, bool ALIGN_EPI = false, bool SP2 = false>
; __device__ __forceinline__ void gemm_phase(PG8_LAS unsigned char* lds, const Gemm g, const Sched& S, const Epi& E) {
;     ...
;             PG8_WAIT_V(8); PG8_WAIT_L(0); PG8_BAR; if (full) { PG8_MMA(1, 0, At, B0); PG8_MMA(1, 1, At, B1); } PG8_BAR; PG8_SCHED;
;             PG8_LDB(B0, 1, 0); PG8_LDB(B1, 1, 1); PG8_SCHED; PG8_LDA(At, 1, 0); PG8_STAGE(PG8_SA(0, 1), a2 + hstep, voffA);
;             PG8_WAIT_V(8); PG8_WAIT_L(0); PG8_BAR; PG8_MMA(0, 0, At, B0); PG8_MMA(0, 1, At, B1); PG8_BAR; PG8_SCHED;
	s_setprio 1
	s_waitcnt lgkmcnt(0)
	v_mfma_f32_16x16x32_bf16 v[64:67], v[146:149], v[186:189], v[64:67]
	v_mfma_f32_16x16x32_bf16 v[60:63], v[154:157], v[186:189], v[60:63]
	v_mfma_f32_16x16x32_bf16 v[44:47], v[146:149], v[178:181], v[44:47]
	v_mfma_f32_16x16x32_bf16 v[40:43], v[154:157], v[178:181], v[40:43]
	v_mfma_f32_16x16x32_bf16 v[28:31], v[146:149], v[170:173], v[28:31]
	v_mfma_f32_16x16x32_bf16 v[24:27], v[154:157], v[170:173], v[24:27]
	v_mfma_f32_16x16x32_bf16 v[12:15], v[146:149], v[162:165], v[12:15]
	v_mfma_f32_16x16x32_bf16 v[8:11], v[154:157], v[162:165], v[8:11]
	v_mfma_f32_16x16x32_bf16 v[64:67], v[150:153], v[190:193], v[64:67]
	v_mfma_f32_16x16x32_bf16 v[60:63], v[158:161], v[190:193], v[60:63]
	v_mfma_f32_16x16x32_bf16 v[44:47], v[150:153], v[182:185], v[44:47]
	v_mfma_f32_16x16x32_bf16 v[40:43], v[158:161], v[182:185], v[40:43]
	v_mfma_f32_16x16x32_bf16 v[28:31], v[150:153], v[174:177], v[28:31]
	v_mfma_f32_16x16x32_bf16 v[24:27], v[158:161], v[174:177], v[24:27]
	v_mfma_f32_16x16x32_bf16 v[12:15], v[150:153], v[166:169], v[12:15]
	v_mfma_f32_16x16x32_bf16 v[8:11], v[158:161], v[166:169], v[8:11]
	s_setprio 0
	s_setprio 1
	v_mfma_f32_16x16x32_bf16 v[52:55], v[130:133], v[186:189], v[52:55]
	v_mfma_f32_16x16x32_bf16 v[48:51], v[138:141], v[186:189], v[48:51]
	v_mfma_f32_16x16x32_bf16 v[36:39], v[130:133], v[178:181], v[36:39]
	v_mfma_f32_16x16x32_bf16 v[32:35], v[138:141], v[178:181], v[32:35]
	v_mfma_f32_16x16x32_bf16 v[20:23], v[130:133], v[170:173], v[20:23]
	v_mfma_f32_16x16x32_bf16 v[16:19], v[138:141], v[170:173], v[16:19]
	v_mfma_f32_16x16x32_bf16 v[4:7], v[130:133], v[162:165], v[4:7]
	v_mfma_f32_16x16x32_bf16 v[0:3], v[138:141], v[162:165], v[0:3]
	v_mfma_f32_16x16x32_bf16 v[52:55], v[134:137], v[190:193], v[52:55]
	v_mfma_f32_16x16x32_bf16 v[48:51], v[142:145], v[190:193], v[48:51]
	v_mfma_f32_16x16x32_bf16 v[36:39], v[134:137], v[182:185], v[36:39]
	v_mfma_f32_16x16x32_bf16 v[32:35], v[142:145], v[182:185], v[32:35]
	v_mfma_f32_16x16x32_bf16 v[20:23], v[134:137], v[174:177], v[20:23]
	v_mfma_f32_16x16x32_bf16 v[16:19], v[142:145], v[174:177], v[16:19]
	v_mfma_f32_16x16x32_bf16 v[4:7], v[134:137], v[166:169], v[4:7]
	v_mfma_f32_16x16x32_bf16 v[0:3], v[142:145], v[166:169], v[0:3]
	s_setprio 0
.LBB0_918:
	s_barrier
	s_add_i32 s4, 0, 0x18000
	v_add_u32_e32 v128, s4, v195
	s_add_i32 s5, 0, 0x1c000
	ds_read_b128 v[146:149], v128
	ds_read_b128 v[150:153], v128 offset:1024
	ds_read_b128 v[154:157], v128 offset:2048
	ds_read_b128 v[158:161], v128 offset:3072
	v_add_u32_e32 v128, s5, v195
	ds_read_b128 v[130:133], v128
	ds_read_b128 v[134:137], v128 offset:1024
	ds_read_b128 v[138:141], v128 offset:2048
	ds_read_b128 v[142:145], v128 offset:3072
	s_add_u32 s2, s34, 0x40000
	s_addc_u32 s3, s35, 0
	s_mov_b32 m0, s73
	v_lshl_add_u64 v[196:197], s[2:3], 0, v[206:207]
	s_waitcnt lgkmcnt(7)
	ds_read_b128 v[162:165], v242 offset:32768
	ds_read_b128 v[166:169], v242 offset:33792
	ds_read_b128 v[170:173], v242 offset:34816
	ds_read_b128 v[174:177], v242 offset:35840
	ds_read_b128 v[178:181], v242 offset:36864
	ds_read_b128 v[182:185], v242 offset:37888
	ds_read_b128 v[186:189], v242 offset:38912
	ds_read_b128 v[190:193], v242 offset:39936
	global_load_lds_dwordx4 v[196:197], off
	v_lshl_add_u64 v[196:197], s[2:3], 0, v[210:211]
	s_mov_b32 m0, s77
	s_nop 0
	global_load_lds_dwordx4 v[196:197], off
	s_waitcnt vmcnt(8)
	s_waitcnt lgkmcnt(0)
	s_barrier
	s_setprio 1
	s_waitcnt lgkmcnt(0)
	v_mfma_f32_16x16x32_bf16 v[124:127], v[146:149], v[162:165], v[124:127]
	v_mfma_f32_16x16x32_bf16 v[120:123], v[154:157], v[162:165], v[120:123]
	v_mfma_f32_16x16x32_bf16 v[116:119], v[146:149], v[170:173], v[116:119]
	v_mfma_f32_16x16x32_bf16 v[112:115], v[154:157], v[170:173], v[112:115]
	v_mfma_f32_16x16x32_bf16 v[104:107], v[146:149], v[178:181], v[104:107]
	v_mfma_f32_16x16x32_bf16 v[96:99], v[154:157], v[178:181], v[96:99]
	v_mfma_f32_16x16x32_bf16 v[88:91], v[146:149], v[186:189], v[88:91]
	v_mfma_f32_16x16x32_bf16 v[80:83], v[154:157], v[186:189], v[80:83]
	v_mfma_f32_16x16x32_bf16 v[124:127], v[150:153], v[166:169], v[124:127]
	v_mfma_f32_16x16x32_bf16 v[120:123], v[158:161], v[166:169], v[120:123]
	v_mfma_f32_16x16x32_bf16 v[116:119], v[150:153], v[174:177], v[116:119]
	v_mfma_f32_16x16x32_bf16 v[112:115], v[158:161], v[174:177], v[112:115]
	v_mfma_f32_16x16x32_bf16 v[104:107], v[150:153], v[182:185], v[104:107]
	v_mfma_f32_16x16x32_bf16 v[96:99], v[158:161], v[182:185], v[96:99]
	v_mfma_f32_16x16x32_bf16 v[88:91], v[150:153], v[190:193], v[88:91]
	v_mfma_f32_16x16x32_bf16 v[80:83], v[158:161], v[190:193], v[80:83]
	s_setprio 0
	s_setprio 1
	v_mfma_f32_16x16x32_bf16 v[108:111], v[130:133], v[162:165], v[108:111]
	v_mfma_f32_16x16x32_bf16 v[100:103], v[138:141], v[162:165], v[100:103]
	v_mfma_f32_16x16x32_bf16 v[92:95], v[130:133], v[170:173], v[92:95]
	v_mfma_f32_16x16x32_bf16 v[84:87], v[138:141], v[170:173], v[84:87]
	v_mfma_f32_16x16x32_bf16 v[76:79], v[130:133], v[178:181], v[76:79]
	v_mfma_f32_16x16x32_bf16 v[72:75], v[138:141], v[178:181], v[72:75]
	v_mfma_f32_16x16x32_bf16 v[68:71], v[130:133], v[186:189], v[68:71]
	v_mfma_f32_16x16x32_bf16 v[56:59], v[138:141], v[186:189], v[56:59]
	v_mfma_f32_16x16x32_bf16 v[108:111], v[134:137], v[166:169], v[108:111]
	v_mfma_f32_16x16x32_bf16 v[100:103], v[142:145], v[166:169], v[100:103]
	v_mfma_f32_16x16x32_bf16 v[92:95], v[134:137], v[174:177], v[92:95]
	v_mfma_f32_16x16x32_bf16 v[84:87], v[142:145], v[174:177], v[84:87]
	v_mfma_f32_16x16x32_bf16 v[76:79], v[134:137], v[182:185], v[76:79]
	v_mfma_f32_16x16x32_bf16 v[72:75], v[142:145], v[182:185], v[72:75]
	v_mfma_f32_16x16x32_bf16 v[68:71], v[134:137], v[190:193], v[68:71]
	v_mfma_f32_16x16x32_bf16 v[56:59], v[142:145], v[190:193], v[56:59]
	s_setprio 0
	s_barrier
; #define PG8_STAGE(bufoff, gbase, voff) do { _Pragma("unroll") for (int _i = 0; _i < 2; ++_i) \
;         __builtin_amdgcn_global_load_lds((const unsigned*)((const char*)(gbase) + (voff)[_i]), (PG8_LAS unsigned*)(lds + (bufoff) + ldsw + _i * 8192), 16, 0, 0); } while (0)
; #define PG8_LDA(dst, b, h) do { _Pragma("unroll") for (int m = 0; m < 4; ++m) _Pragma("unroll") for (int k = 0; k < 2; ++k) dst[m][k] = *(const PG8_LAS bf16x8*)(lds + PG8_SA(b, h) + aoff + m * 2048 + k * 1024); } while (0)
; #define PG8_LDB(dst, b, h) do { _Pragma("unroll") for (int n = 0; n < 2; ++n) _Pragma("unroll") for (int k = 0; k < 2; ++k) dst[n][k] = *(const PG8_LAS bf16x8*)(lds + PG8_SB(b, h) + boff + n * 2048 + k * 1024); } while (0)
; #define PG8_WAIT_V(n) asm volatile("s_waitcnt vmcnt(" #n ")" ::: "memory")
; #define PG8_WAIT_L(n) asm volatile("s_waitcnt lgkmcnt(" #n ")" ::: "memory")
; #define PG8_BAR __builtin_amdgcn_s_barrier()
; #define PG8_SCHED __builtin_amdgcn_sched_barrier(0)
; template <class Epi, class Sched, bool ALIGN_EPI = false, bool SP2 = false>
; __device__ __forceinline__ void gemm_phase(PG8_LAS unsigned char* lds, const Gemm g, const Sched& S, const Epi& E) {
;     ...
;             const char* a3 = a2 + kstep; const char* b3 = b2 + kstep;
;             if (last && has_next) S.a_ready(nxt);
;             if constexpr (SP2) {
;             PG8_LDB(B0, 0, 0); PG8_LDB(B1, 0, 1); PG8_SCHED; PG8_LDA(At, 0, 0); PG8_STAGE(PG8_SA(1, 1), a1 + hstep, voffA);
;             PG8_WAIT_V(8); PG8_WAIT_L(0); PG8_BAR; PG8_MMA(0, 0, At, B0); PG8_MMA(0, 1, At, B1); PG8_BAR; PG8_SCHED;
;             PG8_LDA(At, 0, 1); PG8_STAGE(PG8_SB(0, 0), b2, voffB); PG8_STAGE(PG8_SB(0, 1), b2 + hstep, voffB); PG8_STAGE(PG8_SA(0, 0), a2, voffA);
;             PG8_WAIT_V(8); PG8_WAIT_L(0); PG8_BAR; if (full) { PG8_MMA(1, 0, At, B0); PG8_MMA(1, 1, At, B1); } PG8_BAR; PG8_SCHED;
;             PG8_LDB(B0, 1, 0); PG8_LDB(B1, 1, 1); PG8_SCHED; PG8_LDA(At, 1, 0); PG8_STAGE(PG8_SA(0, 1), a2 + hstep, voffA);
;             PG8_WAIT_V(8); PG8_WAIT_L(0); PG8_BAR; PG8_MMA(0, 0, At, B0); PG8_MMA(0, 1, At, B1); PG8_BAR; PG8_SCHED;
;             PG8_LDA(At, 1, 1); PG8_STAGE(PG8_SB(1, 0), b3, voffB); PG8_STAGE(PG8_SB(1, 1), b3 + hstep, voffB); PG8_STAGE(PG8_SA(1, 0), a3, voffA);
;             PG8_WAIT_V(8); PG8_WAIT_L(0); PG8_BAR; if (full) { PG8_MMA(1, 0, At, B0); PG8_MMA(1, 1, At, B1); } PG8_BAR; PG8_SCHED;
	s_add_i32 s2, s4, s65
	v_lshl_add_u64 v[196:197], v[222:223], 0, s[26:27]
	s_mov_b32 m0, s2
	ds_read_b128 v[186:189], v242 offset:49152
	ds_read_b128 v[190:193], v242 offset:50176
	ds_read_b128 v[178:181], v242 offset:51200
	ds_read_b128 v[182:185], v242 offset:52224
	ds_read_b128 v[170:173], v242 offset:53248
	ds_read_b128 v[174:177], v242 offset:54272
	ds_read_b128 v[162:165], v242 offset:55296
	ds_read_b128 v[166:169], v242 offset:56320
	global_load_lds_dwordx4 v[196:197], off
	s_add_i32 m0, s2, 0x2000
	s_add_u32 s2, s28, 0x40080
	v_lshl_add_u64 v[196:197], v[224:225], 0, s[26:27]
	s_addc_u32 s3, s29, 0
	s_add_i32 s4, s5, s65
	global_load_lds_dwordx4 v[196:197], off
	v_lshl_add_u64 v[196:197], s[2:3], 0, v[208:209]
	s_mov_b32 m0, s4
	s_and_b64 vcc, exec, s[38:39]
	global_load_lds_dwordx4 v[196:197], off
	v_lshl_add_u64 v[196:197], s[2:3], 0, v[212:213]
	s_add_i32 m0, s4, 0x2000
	s_nop 0
	global_load_lds_dwordx4 v[196:197], off
	v_lshl_add_u64 v[196:197], v[226:227], 0, s[26:27]
	s_mov_b32 m0, s81
	s_nop 0
	global_load_lds_dwordx4 v[196:197], off
	v_lshl_add_u64 v[196:197], v[228:229], 0, s[26:27]
	s_mov_b32 m0, s88
	s_nop 0
	global_load_lds_dwordx4 v[196:197], off
	s_waitcnt vmcnt(8)
	s_waitcnt lgkmcnt(0)
	s_barrier
	s_cbranch_vccnz .LBB0_915
	s_setprio 1
	s_waitcnt lgkmcnt(0)
	v_mfma_f32_16x16x32_bf16 v[64:67], v[146:149], v[186:189], v[64:67]
	v_mfma_f32_16x16x32_bf16 v[60:63], v[154:157], v[186:189], v[60:63]
	v_mfma_f32_16x16x32_bf16 v[44:47], v[146:149], v[178:181], v[44:47]
	v_mfma_f32_16x16x32_bf16 v[40:43], v[154:157], v[178:181], v[40:43]
	v_mfma_f32_16x16x32_bf16 v[28:31], v[146:149], v[170:173], v[28:31]
	v_mfma_f32_16x16x32_bf16 v[24:27], v[154:157], v[170:173], v[24:27]
	v_mfma_f32_16x16x32_bf16 v[12:15], v[146:149], v[162:165], v[12:15]
	v_mfma_f32_16x16x32_bf16 v[8:11], v[154:157], v[162:165], v[8:11]
	v_mfma_f32_16x16x32_bf16 v[64:67], v[150:153], v[190:193], v[64:67]
	v_mfma_f32_16x16x32_bf16 v[60:63], v[158:161], v[190:193], v[60:63]
	v_mfma_f32_16x16x32_bf16 v[44:47], v[150:153], v[182:185], v[44:47]
	v_mfma_f32_16x16x32_bf16 v[40:43], v[158:161], v[182:185], v[40:43]
	v_mfma_f32_16x16x32_bf16 v[28:31], v[150:153], v[174:177], v[28:31]
	v_mfma_f32_16x16x32_bf16 v[24:27], v[158:161], v[174:177], v[24:27]
	v_mfma_f32_16x16x32_bf16 v[12:15], v[150:153], v[166:169], v[12:15]
	v_mfma_f32_16x16x32_bf16 v[8:11], v[158:161], v[166:169], v[8:11]
	s_setprio 0
	s_setprio 1
	v_mfma_f32_16x16x32_bf16 v[52:55], v[130:133], v[186:189], v[52:55]
	v_mfma_f32_16x16x32_bf16 v[48:51], v[138:141], v[186:189], v[48:51]
	v_mfma_f32_16x16x32_bf16 v[36:39], v[130:133], v[178:181], v[36:39]
	v_mfma_f32_16x16x32_bf16 v[32:35], v[138:141], v[178:181], v[32:35]
	v_mfma_f32_16x16x32_bf16 v[20:23], v[130:133], v[170:173], v[20:23]
	v_mfma_f32_16x16x32_bf16 v[16:19], v[138:141], v[170:173], v[16:19]
	v_mfma_f32_16x16x32_bf16 v[4:7], v[130:133], v[162:165], v[4:7]
	v_mfma_f32_16x16x32_bf16 v[0:3], v[138:141], v[162:165], v[0:3]
	v_mfma_f32_16x16x32_bf16 v[52:55], v[134:137], v[190:193], v[52:55]
	v_mfma_f32_16x16x32_bf16 v[48:51], v[142:145], v[190:193], v[48:51]
	v_mfma_f32_16x16x32_bf16 v[36:39], v[134:137], v[182:185], v[36:39]
	v_mfma_f32_16x16x32_bf16 v[32:35], v[142:145], v[182:185], v[32:35]
	v_mfma_f32_16x16x32_bf16 v[20:23], v[134:137], v[174:177], v[20:23]
	v_mfma_f32_16x16x32_bf16 v[16:19], v[142:145], v[174:177], v[16:19]
	v_mfma_f32_16x16x32_bf16 v[4:7], v[134:137], v[166:169], v[4:7]
	v_mfma_f32_16x16x32_bf16 v[0:3], v[142:145], v[166:169], v[0:3]
	s_setprio 0
	s_branch .LBB0_915

; #define PG8_STAGE(bufoff, gbase, voff) do { _Pragma("unroll") for (int _i = 0; _i < 2; ++_i) \
;         __builtin_amdgcn_global_load_lds((const unsigned*)((const char*)(gbase) + (voff)[_i]), (PG8_LAS unsigned*)(lds + (bufoff) + ldsw + _i * 8192), 16, 0, 0); } while (0)
; #define PG8_LDA(dst, b, h) do { _Pragma("unroll") for (int m = 0; m < 4; ++m) _Pragma("unroll") for (int k = 0; k < 2; ++k) dst[m][k] = *(const PG8_LAS bf16x8*)(lds + PG8_SA(b, h) + aoff + m * 2048 + k * 1024); } while (0)
; #define PG8_LDB(dst, b, h) do { _Pragma("unroll") for (int n = 0; n < 2; ++n) _Pragma("unroll") for (int k = 0; k < 2; ++k) dst[n][k] = *(const PG8_LAS bf16x8*)(lds + PG8_SB(b, h) + boff + n * 2048 + k * 1024); } while (0)
; #define PG8_MMA(ai, bj, At, Bt) do { __builtin_amdgcn_s_setprio(1); _Pragma("unroll") for (int m = 0; m < 4; ++m) _Pragma("unroll") for (int n = 0; n < 2; ++n) _Pragma("unroll") for (int k = 0; k < 2; ++k) \
;         acc[ai][bj][m][n] = __builtin_amdgcn_mfma_f32_16x16x32_bf16(Bt[n][k], At[m][k], acc[ai][bj][m][n], 0, 0, 0); __builtin_amdgcn_s_setprio(0); } while (0)
; #define PG8_WAIT_V(n) asm volatile("s_waitcnt vmcnt(" #n ")" ::: "memory")
; #define PG8_BAR __builtin_amdgcn_s_barrier()
; template <class Epi, class Sched, bool ALIGN_EPI = false, bool SP2 = false>
; __device__ __forceinline__ void gemm_phase(PG8_LAS unsigned char* lds, const Gemm g, const Sched& S, const Epi& E) {
;     ...
;         for (int t = 0; t < ntu; t += 2) {
;             const bool last = (t == ntu - 2);
;             const char* a1 = cA + (size_t)(t + 1) * kstep;
;             const char* a2 = last ? nA : cA + (size_t)(t + 2) * kstep; const char* b2 = last ? nB : cB + (size_t)(t + 2) * kstep;
;             const char* a3 = a2 + kstep; const char* b3 = b2 + kstep;
;             if (last && has_next) S.a_ready(nxt);
;             if constexpr (SP2) {
;             PG8_LDB(B0, 0, 0); PG8_LDB(B1, 0, 1); PG8_SCHED; PG8_LDA(At, 0, 0); PG8_STAGE(PG8_SA(1, 1), a1 + hstep, voffA);
;             PG8_WAIT_V(8); PG8_WAIT_L(0); PG8_BAR; PG8_MMA(0, 0, At, B0); PG8_MMA(0, 1, At, B1); PG8_BAR; PG8_SCHED;
;             PG8_LDA(At, 0, 1); PG8_STAGE(PG8_SB(0, 0), b2, voffB); PG8_STAGE(PG8_SB(0, 1), b2 + hstep, voffB); PG8_STAGE(PG8_SA(0, 0), a2, voffA);
;             PG8_WAIT_V(8); PG8_WAIT_L(0); PG8_BAR; if (full) { PG8_MMA(1, 0, At, B0); PG8_MMA(1, 1, At, B1); } PG8_BAR; PG8_SCHED;
.LBB0_1079:
	s_add_u32 s2, s48, 0xfffc0080
	s_addc_u32 s3, s49, -1
	s_add_i32 s4, 0, 0x10000
	s_cmp_eq_u32 s12, 12
	s_cselect_b32 s35, s1, s3
	s_cselect_b32 s34, s90, s2
	v_add_u32_e32 v128, s4, v226
	s_cselect_b32 s29, s75, s50
	s_cselect_b32 s28, s91, s92
	s_add_i32 s5, 0, 0x14000
	ds_read_b128 v[146:149], v128
	ds_read_b128 v[150:153], v128 offset:1024
	ds_read_b128 v[154:157], v128 offset:2048
	ds_read_b128 v[158:161], v128 offset:3072
	v_add_u32_e32 v128, s5, v226
	ds_read_b128 v[130:133], v128
	ds_read_b128 v[134:137], v128 offset:1024
	ds_read_b128 v[138:141], v128 offset:2048
	ds_read_b128 v[142:145], v128 offset:3072
	v_lshl_add_u64 v[196:197], s[48:49], 0, v[214:215]
	s_add_i32 m0, s70, 0xc000
	s_waitcnt lgkmcnt(7)
	ds_read_b128 v[162:165], v228
	ds_read_b128 v[166:169], v228 offset:1024
	ds_read_b128 v[170:173], v228 offset:2048
	ds_read_b128 v[174:177], v228 offset:3072
	ds_read_b128 v[178:181], v228 offset:4096
	ds_read_b128 v[182:185], v228 offset:5120
	ds_read_b128 v[186:189], v228 offset:6144
	ds_read_b128 v[190:193], v228 offset:7168
	global_load_lds_dwordx4 v[196:197], off
	v_lshl_add_u64 v[196:197], s[48:49], 0, v[216:217]
	s_add_i32 m0, s70, 0xe000
	s_nop 0
	global_load_lds_dwordx4 v[196:197], off
	s_waitcnt vmcnt(8)
	s_waitcnt lgkmcnt(0)
	s_barrier
	s_setprio 1
	s_waitcnt lgkmcnt(0)
	v_mfma_f32_16x16x32_bf16 v[124:127], v[146:149], v[162:165], v[124:127]
	v_mfma_f32_16x16x32_bf16 v[120:123], v[154:157], v[162:165], v[120:123]
	v_mfma_f32_16x16x32_bf16 v[108:111], v[146:149], v[170:173], v[108:111]
	v_mfma_f32_16x16x32_bf16 v[104:107], v[154:157], v[170:173], v[104:107]
	v_mfma_f32_16x16x32_bf16 v[92:95], v[146:149], v[178:181], v[92:95]
	v_mfma_f32_16x16x32_bf16 v[88:91], v[154:157], v[178:181], v[88:91]
	v_mfma_f32_16x16x32_bf16 v[76:79], v[146:149], v[186:189], v[76:79]
	v_mfma_f32_16x16x32_bf16 v[72:75], v[154:157], v[186:189], v[72:75]
	v_mfma_f32_16x16x32_bf16 v[124:127], v[150:153], v[166:169], v[124:127]
	v_mfma_f32_16x16x32_bf16 v[120:123], v[158:161], v[166:169], v[120:123]
	v_mfma_f32_16x16x32_bf16 v[108:111], v[150:153], v[174:177], v[108:111]
	v_mfma_f32_16x16x32_bf16 v[104:107], v[158:161], v[174:177], v[104:107]
	v_mfma_f32_16x16x32_bf16 v[92:95], v[150:153], v[182:185], v[92:95]
	v_mfma_f32_16x16x32_bf16 v[88:91], v[158:161], v[182:185], v[88:91]
	v_mfma_f32_16x16x32_bf16 v[76:79], v[150:153], v[190:193], v[76:79]
	v_mfma_f32_16x16x32_bf16 v[72:75], v[158:161], v[190:193], v[72:75]
	s_setprio 0
	s_setprio 1
	v_mfma_f32_16x16x32_bf16 v[116:119], v[130:133], v[162:165], v[116:119]
	v_mfma_f32_16x16x32_bf16 v[112:115], v[138:141], v[162:165], v[112:115]
	v_mfma_f32_16x16x32_bf16 v[100:103], v[130:133], v[170:173], v[100:103]
	v_mfma_f32_16x16x32_bf16 v[96:99], v[138:141], v[170:173], v[96:99]
	v_mfma_f32_16x16x32_bf16 v[84:87], v[130:133], v[178:181], v[84:87]
	v_mfma_f32_16x16x32_bf16 v[80:83], v[138:141], v[178:181], v[80:83]
	v_mfma_f32_16x16x32_bf16 v[68:71], v[130:133], v[186:189], v[68:71]
	v_mfma_f32_16x16x32_bf16 v[64:67], v[138:141], v[186:189], v[64:67]
	v_mfma_f32_16x16x32_bf16 v[116:119], v[134:137], v[166:169], v[116:119]
	v_mfma_f32_16x16x32_bf16 v[112:115], v[142:145], v[166:169], v[112:115]
	v_mfma_f32_16x16x32_bf16 v[100:103], v[134:137], v[174:177], v[100:103]
	v_mfma_f32_16x16x32_bf16 v[96:99], v[142:145], v[174:177], v[96:99]
	v_mfma_f32_16x16x32_bf16 v[84:87], v[134:137], v[182:185], v[84:87]
	v_mfma_f32_16x16x32_bf16 v[80:83], v[142:145], v[182:185], v[80:83]
	v_mfma_f32_16x16x32_bf16 v[68:71], v[134:137], v[190:193], v[68:71]
	v_mfma_f32_16x16x32_bf16 v[64:67], v[142:145], v[190:193], v[64:67]
	s_setprio 0
	s_barrier
	s_add_i32 s2, s4, s65
	v_lshl_add_u64 v[218:219], s[28:29], 0, v[208:209]
	s_mov_b32 m0, s2
	ds_read_b128 v[186:189], v228 offset:16384
	ds_read_b128 v[190:193], v228 offset:17408
	ds_read_b128 v[178:181], v228 offset:18432
	ds_read_b128 v[182:185], v228 offset:19456
	ds_read_b128 v[170:173], v228 offset:20480
	ds_read_b128 v[174:177], v228 offset:21504
	ds_read_b128 v[162:165], v228 offset:22528
	ds_read_b128 v[166:169], v228 offset:23552
	global_load_lds_dwordx4 v[218:219], off
	s_add_i32 m0, s2, 0x2000
	s_add_u32 s2, s28, 0x40000
	v_lshl_add_u64 v[220:221], s[28:29], 0, v[212:213]
	s_addc_u32 s3, s29, 0
	s_add_i32 s4, s5, s65
	global_load_lds_dwordx4 v[220:221], off
	v_lshl_add_u64 v[196:197], s[2:3], 0, v[208:209]
	s_mov_b32 m0, s4
	v_lshl_add_u64 v[222:223], s[34:35], 0, v[206:207]
	global_load_lds_dwordx4 v[196:197], off
	v_lshl_add_u64 v[196:197], s[2:3], 0, v[212:213]
	s_add_i32 m0, s4, 0x2000
	v_lshl_add_u64 v[224:225], s[34:35], 0, v[210:211]
	global_load_lds_dwordx4 v[196:197], off
	s_mov_b32 m0, s70
	v_cndmask_b32_e64 v128, 0, 1, s[82:83]
	global_load_lds_dwordx4 v[222:223], off
	s_mov_b32 m0, s71
	v_cmp_ne_u32_e64 s[38:39], 1, v128
	global_load_lds_dwordx4 v[224:225], off
	s_waitcnt vmcnt(8)
	s_waitcnt lgkmcnt(0)
	s_andn2_b64 vcc, exec, s[82:83]
	s_barrier
	s_cbranch_vccnz .LBB0_1081
; #define PG8_STAGE(bufoff, gbase, voff) do { _Pragma("unroll") for (int _i = 0; _i < 2; ++_i) \
;         __builtin_amdgcn_global_load_lds((const unsigned*)((const char*)(gbase) + (voff)[_i]), (PG8_LAS unsigned*)(lds + (bufoff) + ldsw + _i * 8192), 16, 0, 0); } while (0)
; #define PG8_LDA(dst, b, h) do { _Pragma("unroll") for (int m = 0; m < 4; ++m) _Pragma("unroll") for (int k = 0; k < 2; ++k) dst[m][k] = *(const PG8_LAS bf16x8*)(lds + PG8_SA(b, h) + aoff + m * 2048 + k * 1024); } while (0)
; #define PG8_LDB(dst, b, h) do { _Pragma("unroll") for (int n = 0; n < 2; ++n) _Pragma("unroll") for (int k = 0; k < 2; ++k) dst[n][k] = *(const PG8_LAS bf16x8*)(lds + PG8_SB(b, h) + boff + n * 2048 + k * 1024); } while (0)
; #define PG8_MMA(ai, bj, At, Bt) do { __builtin_amdgcn_s_setprio(1); _Pragma("unroll") for (int m = 0; m < 4; ++m) _Pragma("unroll") for (int n = 0; n < 2; ++n) _Pragma("unroll") for (int k = 0; k < 2; ++k) \
;         acc[ai][bj][m][n] = __builtin_amdgcn_mfma_f32_16x16x32_bf16(Bt[n][k], At[m][k], acc[ai][bj][m][n], 0, 0, 0); __builtin_amdgcn_s_setprio(0); } while (0)
; #define PG8_WAIT_V(n) asm volatile("s_waitcnt vmcnt(" #n ")" ::: "memory")
; #define PG8_WAIT_L(n) asm volatile("s_waitcnt lgkmcnt(" #n ")" ::: "memory")
; #define PG8_BAR __builtin_amdgcn_s_barrier()
; #define PG8_SCHED __builtin_amdgcn_sched_barrier(0)
; template <class Epi, class Sched, bool ALIGN_EPI = false, bool SP2 = false>
; __device__ __forceinline__ void gemm_phase(PG8_LAS unsigned char* lds, const Gemm g, const Sched& S, const Epi& E) {
;     ...
;             PG8_WAIT_V(8); PG8_WAIT_L(0); PG8_BAR; if (full) { PG8_MMA(1, 0, At, B0); PG8_MMA(1, 1, At, B1); } PG8_BAR; PG8_SCHED;
;             PG8_LDB(B0, 1, 0); PG8_LDB(B1, 1, 1); PG8_SCHED; PG8_LDA(At, 1, 0); PG8_STAGE(PG8_SA(0, 1), a2 + hstep, voffA);
;             PG8_WAIT_V(8); PG8_WAIT_L(0); PG8_BAR; PG8_MMA(0, 0, At, B0); PG8_MMA(0, 1, At, B1); PG8_BAR; PG8_SCHED;
	s_setprio 1
	s_waitcnt lgkmcnt(0)
	v_mfma_f32_16x16x32_bf16 v[60:63], v[146:149], v[186:189], v[60:63]
	v_mfma_f32_16x16x32_bf16 v[52:55], v[154:157], v[186:189], v[52:55]
	v_mfma_f32_16x16x32_bf16 v[44:47], v[146:149], v[178:181], v[44:47]
	v_mfma_f32_16x16x32_bf16 v[36:39], v[154:157], v[178:181], v[36:39]
	v_mfma_f32_16x16x32_bf16 v[28:31], v[146:149], v[170:173], v[28:31]
	v_mfma_f32_16x16x32_bf16 v[20:23], v[154:157], v[170:173], v[20:23]
	v_mfma_f32_16x16x32_bf16 v[12:15], v[146:149], v[162:165], v[12:15]
	v_mfma_f32_16x16x32_bf16 v[4:7], v[154:157], v[162:165], v[4:7]
	v_mfma_f32_16x16x32_bf16 v[60:63], v[150:153], v[190:193], v[60:63]
	v_mfma_f32_16x16x32_bf16 v[52:55], v[158:161], v[190:193], v[52:55]
	v_mfma_f32_16x16x32_bf16 v[44:47], v[150:153], v[182:185], v[44:47]
	v_mfma_f32_16x16x32_bf16 v[36:39], v[158:161], v[182:185], v[36:39]
	v_mfma_f32_16x16x32_bf16 v[28:31], v[150:153], v[174:177], v[28:31]
	v_mfma_f32_16x16x32_bf16 v[20:23], v[158:161], v[174:177], v[20:23]
	v_mfma_f32_16x16x32_bf16 v[12:15], v[150:153], v[166:169], v[12:15]
	v_mfma_f32_16x16x32_bf16 v[4:7], v[158:161], v[166:169], v[4:7]
	s_setprio 0
	s_setprio 1
	v_mfma_f32_16x16x32_bf16 v[56:59], v[130:133], v[186:189], v[56:59]
	v_mfma_f32_16x16x32_bf16 v[48:51], v[138:141], v[186:189], v[48:51]
	v_mfma_f32_16x16x32_bf16 v[40:43], v[130:133], v[178:181], v[40:43]
	v_mfma_f32_16x16x32_bf16 v[32:35], v[138:141], v[178:181], v[32:35]
	v_mfma_f32_16x16x32_bf16 v[24:27], v[130:133], v[170:173], v[24:27]
	v_mfma_f32_16x16x32_bf16 v[16:19], v[138:141], v[170:173], v[16:19]
	v_mfma_f32_16x16x32_bf16 v[8:11], v[130:133], v[162:165], v[8:11]
	v_mfma_f32_16x16x32_bf16 v[0:3], v[138:141], v[162:165], v[0:3]
	v_mfma_f32_16x16x32_bf16 v[56:59], v[134:137], v[190:193], v[56:59]
	v_mfma_f32_16x16x32_bf16 v[48:51], v[142:145], v[190:193], v[48:51]
	v_mfma_f32_16x16x32_bf16 v[40:43], v[134:137], v[182:185], v[40:43]
	v_mfma_f32_16x16x32_bf16 v[32:35], v[142:145], v[182:185], v[32:35]
	v_mfma_f32_16x16x32_bf16 v[24:27], v[134:137], v[174:177], v[24:27]
	v_mfma_f32_16x16x32_bf16 v[16:19], v[142:145], v[174:177], v[16:19]
	v_mfma_f32_16x16x32_bf16 v[8:11], v[134:137], v[166:169], v[8:11]
	v_mfma_f32_16x16x32_bf16 v[0:3], v[142:145], v[166:169], v[0:3]
	s_setprio 0
.LBB0_1081:
	s_barrier
	s_add_i32 s4, 0, 0x18000
	v_add_u32_e32 v128, s4, v226
	s_add_i32 s5, 0, 0x1c000
	ds_read_b128 v[146:149], v128
	ds_read_b128 v[150:153], v128 offset:1024
	ds_read_b128 v[154:157], v128 offset:2048
	ds_read_b128 v[158:161], v128 offset:3072
	v_add_u32_e32 v128, s5, v226
	ds_read_b128 v[130:133], v128
	ds_read_b128 v[134:137], v128 offset:1024
	ds_read_b128 v[138:141], v128 offset:2048
	ds_read_b128 v[142:145], v128 offset:3072
	s_add_u32 s2, s34, 0x40000
	s_addc_u32 s3, s35, 0
	s_mov_b32 m0, s73
	v_lshl_add_u64 v[196:197], s[2:3], 0, v[206:207]
	s_waitcnt lgkmcnt(7)
	ds_read_b128 v[162:165], v228 offset:32768
	ds_read_b128 v[166:169], v228 offset:33792
	ds_read_b128 v[170:173], v228 offset:34816
	ds_read_b128 v[174:177], v228 offset:35840
	ds_read_b128 v[178:181], v228 offset:36864
	ds_read_b128 v[182:185], v228 offset:37888
	ds_read_b128 v[186:189], v228 offset:38912
	ds_read_b128 v[190:193], v228 offset:39936
	global_load_lds_dwordx4 v[196:197], off
	v_lshl_add_u64 v[196:197], s[2:3], 0, v[210:211]
	s_mov_b32 m0, s81
	s_nop 0
	global_load_lds_dwordx4 v[196:197], off
	s_waitcnt vmcnt(8)
	s_waitcnt lgkmcnt(0)
	s_barrier
	s_setprio 1
	s_waitcnt lgkmcnt(0)
	v_mfma_f32_16x16x32_bf16 v[124:127], v[146:149], v[162:165], v[124:127]
	v_mfma_f32_16x16x32_bf16 v[120:123], v[154:157], v[162:165], v[120:123]
	v_mfma_f32_16x16x32_bf16 v[108:111], v[146:149], v[170:173], v[108:111]
	v_mfma_f32_16x16x32_bf16 v[104:107], v[154:157], v[170:173], v[104:107]
	v_mfma_f32_16x16x32_bf16 v[92:95], v[146:149], v[178:181], v[92:95]
	v_mfma_f32_16x16x32_bf16 v[88:91], v[154:157], v[178:181], v[88:91]
	v_mfma_f32_16x16x32_bf16 v[76:79], v[146:149], v[186:189], v[76:79]
	v_mfma_f32_16x16x32_bf16 v[72:75], v[154:157], v[186:189], v[72:75]
	v_mfma_f32_16x16x32_bf16 v[124:127], v[150:153], v[166:169], v[124:127]
	v_mfma_f32_16x16x32_bf16 v[120:123], v[158:161], v[166:169], v[120:123]
	v_mfma_f32_16x16x32_bf16 v[108:111], v[150:153], v[174:177], v[108:111]
	v_mfma_f32_16x16x32_bf16 v[104:107], v[158:161], v[174:177], v[104:107]
	v_mfma_f32_16x16x32_bf16 v[92:95], v[150:153], v[182:185], v[92:95]
	v_mfma_f32_16x16x32_bf16 v[88:91], v[158:161], v[182:185], v[88:91]
	v_mfma_f32_16x16x32_bf16 v[76:79], v[150:153], v[190:193], v[76:79]
	v_mfma_f32_16x16x32_bf16 v[72:75], v[158:161], v[190:193], v[72:75]
	s_setprio 0
	s_setprio 1
	v_mfma_f32_16x16x32_bf16 v[116:119], v[130:133], v[162:165], v[116:119]
	v_mfma_f32_16x16x32_bf16 v[112:115], v[138:141], v[162:165], v[112:115]
	v_mfma_f32_16x16x32_bf16 v[100:103], v[130:133], v[170:173], v[100:103]
	v_mfma_f32_16x16x32_bf16 v[96:99], v[138:141], v[170:173], v[96:99]
	v_mfma_f32_16x16x32_bf16 v[84:87], v[130:133], v[178:181], v[84:87]
	v_mfma_f32_16x16x32_bf16 v[80:83], v[138:141], v[178:181], v[80:83]
	v_mfma_f32_16x16x32_bf16 v[68:71], v[130:133], v[186:189], v[68:71]
	v_mfma_f32_16x16x32_bf16 v[64:67], v[138:141], v[186:189], v[64:67]
	v_mfma_f32_16x16x32_bf16 v[116:119], v[134:137], v[166:169], v[116:119]
	v_mfma_f32_16x16x32_bf16 v[112:115], v[142:145], v[166:169], v[112:115]
	v_mfma_f32_16x16x32_bf16 v[100:103], v[134:137], v[174:177], v[100:103]
	v_mfma_f32_16x16x32_bf16 v[96:99], v[142:145], v[174:177], v[96:99]
	v_mfma_f32_16x16x32_bf16 v[84:87], v[134:137], v[182:185], v[84:87]
	v_mfma_f32_16x16x32_bf16 v[80:83], v[142:145], v[182:185], v[80:83]
	v_mfma_f32_16x16x32_bf16 v[68:71], v[134:137], v[190:193], v[68:71]
	v_mfma_f32_16x16x32_bf16 v[64:67], v[142:145], v[190:193], v[64:67]
	s_setprio 0
	s_barrier
; #define PG8_STAGE(bufoff, gbase, voff) do { _Pragma("unroll") for (int _i = 0; _i < 2; ++_i) \
;         __builtin_amdgcn_global_load_lds((const unsigned*)((const char*)(gbase) + (voff)[_i]), (PG8_LAS unsigned*)(lds + (bufoff) + ldsw + _i * 8192), 16, 0, 0); } while (0)
; #define PG8_LDA(dst, b, h) do { _Pragma("unroll") for (int m = 0; m < 4; ++m) _Pragma("unroll") for (int k = 0; k < 2; ++k) dst[m][k] = *(const PG8_LAS bf16x8*)(lds + PG8_SA(b, h) + aoff + m * 2048 + k * 1024); } while (0)
; #define PG8_LDB(dst, b, h) do { _Pragma("unroll") for (int n = 0; n < 2; ++n) _Pragma("unroll") for (int k = 0; k < 2; ++k) dst[n][k] = *(const PG8_LAS bf16x8*)(lds + PG8_SB(b, h) + boff + n * 2048 + k * 1024); } while (0)
; #define PG8_WAIT_V(n) asm volatile("s_waitcnt vmcnt(" #n ")" ::: "memory")
; #define PG8_WAIT_L(n) asm volatile("s_waitcnt lgkmcnt(" #n ")" ::: "memory")
; #define PG8_BAR __builtin_amdgcn_s_barrier()
; #define PG8_SCHED __builtin_amdgcn_sched_barrier(0)
; template <class Epi, class Sched, bool ALIGN_EPI = false, bool SP2 = false>
; __device__ __forceinline__ void gemm_phase(PG8_LAS unsigned char* lds, const Gemm g, const Sched& S, const Epi& E) {
;     ...
;             const char* a3 = a2 + kstep; const char* b3 = b2 + kstep;
;             if (last && has_next) S.a_ready(nxt);
;             if constexpr (SP2) {
;             PG8_LDB(B0, 0, 0); PG8_LDB(B1, 0, 1); PG8_SCHED; PG8_LDA(At, 0, 0); PG8_STAGE(PG8_SA(1, 1), a1 + hstep, voffA);
;             PG8_WAIT_V(8); PG8_WAIT_L(0); PG8_BAR; PG8_MMA(0, 0, At, B0); PG8_MMA(0, 1, At, B1); PG8_BAR; PG8_SCHED;
;             PG8_LDA(At, 0, 1); PG8_STAGE(PG8_SB(0, 0), b2, voffB); PG8_STAGE(PG8_SB(0, 1), b2 + hstep, voffB); PG8_STAGE(PG8_SA(0, 0), a2, voffA);
;             PG8_WAIT_V(8); PG8_WAIT_L(0); PG8_BAR; if (full) { PG8_MMA(1, 0, At, B0); PG8_MMA(1, 1, At, B1); } PG8_BAR; PG8_SCHED;
;             PG8_LDB(B0, 1, 0); PG8_LDB(B1, 1, 1); PG8_SCHED; PG8_LDA(At, 1, 0); PG8_STAGE(PG8_SA(0, 1), a2 + hstep, voffA);
;             PG8_WAIT_V(8); PG8_WAIT_L(0); PG8_BAR; PG8_MMA(0, 0, At, B0); PG8_MMA(0, 1, At, B1); PG8_BAR; PG8_SCHED;
;             PG8_LDA(At, 1, 1); PG8_STAGE(PG8_SB(1, 0), b3, voffB); PG8_STAGE(PG8_SB(1, 1), b3 + hstep, voffB); PG8_STAGE(PG8_SA(1, 0), a3, voffA);
;             PG8_WAIT_V(8); PG8_WAIT_L(0); PG8_BAR; if (full) { PG8_MMA(1, 0, At, B0); PG8_MMA(1, 1, At, B1); } PG8_BAR; PG8_SCHED;
	s_add_i32 s2, s4, s65
	v_lshl_add_u64 v[196:197], v[218:219], 0, s[26:27]
	s_mov_b32 m0, s2
	ds_read_b128 v[186:189], v228 offset:49152
	ds_read_b128 v[190:193], v228 offset:50176
	ds_read_b128 v[178:181], v228 offset:51200
	ds_read_b128 v[182:185], v228 offset:52224
	ds_read_b128 v[170:173], v228 offset:53248
	ds_read_b128 v[174:177], v228 offset:54272
	ds_read_b128 v[162:165], v228 offset:55296
	ds_read_b128 v[166:169], v228 offset:56320
	global_load_lds_dwordx4 v[196:197], off
	s_add_i32 m0, s2, 0x2000
	s_add_u32 s2, s28, 0x40080
	v_lshl_add_u64 v[196:197], v[220:221], 0, s[26:27]
	s_addc_u32 s3, s29, 0
	s_add_i32 s4, s5, s65
	global_load_lds_dwordx4 v[196:197], off
	v_lshl_add_u64 v[196:197], s[2:3], 0, v[208:209]
	s_mov_b32 m0, s4
	s_and_b64 vcc, exec, s[38:39]
	global_load_lds_dwordx4 v[196:197], off
	v_lshl_add_u64 v[196:197], s[2:3], 0, v[212:213]
	s_add_i32 m0, s4, 0x2000
	s_nop 0
	global_load_lds_dwordx4 v[196:197], off
	v_lshl_add_u64 v[196:197], v[222:223], 0, s[26:27]
	s_mov_b32 m0, s84
	s_nop 0
	global_load_lds_dwordx4 v[196:197], off
	v_lshl_add_u64 v[196:197], v[224:225], 0, s[26:27]
	s_mov_b32 m0, s85
	s_nop 0
	global_load_lds_dwordx4 v[196:197], off
	s_waitcnt vmcnt(8)
	s_waitcnt lgkmcnt(0)
	s_barrier
	s_cbranch_vccnz .LBB0_1078
	s_setprio 1
	s_waitcnt lgkmcnt(0)
	v_mfma_f32_16x16x32_bf16 v[60:63], v[146:149], v[186:189], v[60:63]
	v_mfma_f32_16x16x32_bf16 v[52:55], v[154:157], v[186:189], v[52:55]
	v_mfma_f32_16x16x32_bf16 v[44:47], v[146:149], v[178:181], v[44:47]
	v_mfma_f32_16x16x32_bf16 v[36:39], v[154:157], v[178:181], v[36:39]
	v_mfma_f32_16x16x32_bf16 v[28:31], v[146:149], v[170:173], v[28:31]
	v_mfma_f32_16x16x32_bf16 v[20:23], v[154:157], v[170:173], v[20:23]
	v_mfma_f32_16x16x32_bf16 v[12:15], v[146:149], v[162:165], v[12:15]
	v_mfma_f32_16x16x32_bf16 v[4:7], v[154:157], v[162:165], v[4:7]
	v_mfma_f32_16x16x32_bf16 v[60:63], v[150:153], v[190:193], v[60:63]
	v_mfma_f32_16x16x32_bf16 v[52:55], v[158:161], v[190:193], v[52:55]
	v_mfma_f32_16x16x32_bf16 v[44:47], v[150:153], v[182:185], v[44:47]
	v_mfma_f32_16x16x32_bf16 v[36:39], v[158:161], v[182:185], v[36:39]
	v_mfma_f32_16x16x32_bf16 v[28:31], v[150:153], v[174:177], v[28:31]
	v_mfma_f32_16x16x32_bf16 v[20:23], v[158:161], v[174:177], v[20:23]
	v_mfma_f32_16x16x32_bf16 v[12:15], v[150:153], v[166:169], v[12:15]
	v_mfma_f32_16x16x32_bf16 v[4:7], v[158:161], v[166:169], v[4:7]
	s_setprio 0
	s_setprio 1
	v_mfma_f32_16x16x32_bf16 v[56:59], v[130:133], v[186:189], v[56:59]
	v_mfma_f32_16x16x32_bf16 v[48:51], v[138:141], v[186:189], v[48:51]
	v_mfma_f32_16x16x32_bf16 v[40:43], v[130:133], v[178:181], v[40:43]
	v_mfma_f32_16x16x32_bf16 v[32:35], v[138:141], v[178:181], v[32:35]
	v_mfma_f32_16x16x32_bf16 v[24:27], v[130:133], v[170:173], v[24:27]
	v_mfma_f32_16x16x32_bf16 v[16:19], v[138:141], v[170:173], v[16:19]
	v_mfma_f32_16x16x32_bf16 v[8:11], v[130:133], v[162:165], v[8:11]
	v_mfma_f32_16x16x32_bf16 v[0:3], v[138:141], v[162:165], v[0:3]
	v_mfma_f32_16x16x32_bf16 v[56:59], v[134:137], v[190:193], v[56:59]
	v_mfma_f32_16x16x32_bf16 v[48:51], v[142:145], v[190:193], v[48:51]
	v_mfma_f32_16x16x32_bf16 v[40:43], v[134:137], v[182:185], v[40:43]
	v_mfma_f32_16x16x32_bf16 v[32:35], v[142:145], v[182:185], v[32:35]
	v_mfma_f32_16x16x32_bf16 v[24:27], v[134:137], v[174:177], v[24:27]
	v_mfma_f32_16x16x32_bf16 v[16:19], v[142:145], v[174:177], v[16:19]
	v_mfma_f32_16x16x32_bf16 v[8:11], v[134:137], v[166:169], v[8:11]
	v_mfma_f32_16x16x32_bf16 v[0:3], v[142:145], v[166:169], v[0:3]
	s_setprio 0
	s_branch .LBB0_1078

; #define PG8_STAGE(bufoff, gbase, voff) do { _Pragma("unroll") for (int _i = 0; _i < 2; ++_i) \
;         __builtin_amdgcn_global_load_lds((const unsigned*)((const char*)(gbase) + (voff)[_i]), (PG8_LAS unsigned*)(lds + (bufoff) + ldsw + _i * 8192), 16, 0, 0); } while (0)
; #define PG8_LDA(dst, b, h) do { _Pragma("unroll") for (int m = 0; m < 4; ++m) _Pragma("unroll") for (int k = 0; k < 2; ++k) dst[m][k] = *(const PG8_LAS bf16x8*)(lds + PG8_SA(b, h) + aoff + m * 2048 + k * 1024); } while (0)
; #define PG8_LDB(dst, b, h) do { _Pragma("unroll") for (int n = 0; n < 2; ++n) _Pragma("unroll") for (int k = 0; k < 2; ++k) dst[n][k] = *(const PG8_LAS bf16x8*)(lds + PG8_SB(b, h) + boff + n * 2048 + k * 1024); } while (0)
; #define PG8_MMA(ai, bj, At, Bt) do { __builtin_amdgcn_s_setprio(1); _Pragma("unroll") for (int m = 0; m < 4; ++m) _Pragma("unroll") for (int n = 0; n < 2; ++n) _Pragma("unroll") for (int k = 0; k < 2; ++k) \
;         acc[ai][bj][m][n] = __builtin_amdgcn_mfma_f32_16x16x32_bf16(Bt[n][k], At[m][k], acc[ai][bj][m][n], 0, 0, 0); __builtin_amdgcn_s_setprio(0); } while (0)
; #define PG8_WAIT_V(n) asm volatile("s_waitcnt vmcnt(" #n ")" ::: "memory")
; #define PG8_BAR __builtin_amdgcn_s_barrier()
; template <class Epi, class Sched, bool ALIGN_EPI = false, bool SP2 = false>
; __device__ __forceinline__ void gemm_phase(PG8_LAS unsigned char* lds, const Gemm g, const Sched& S, const Epi& E) {
;     ...
;         for (int t = 0; t < ntu; t += 2) {
;             const bool last = (t == ntu - 2);
;             const char* a1 = cA + (size_t)(t + 1) * kstep;
;             const char* a2 = last ? nA : cA + (size_t)(t + 2) * kstep; const char* b2 = last ? nB : cB + (size_t)(t + 2) * kstep;
;             const char* a3 = a2 + kstep; const char* b3 = b2 + kstep;
;             if (last && has_next) S.a_ready(nxt);
;             if constexpr (SP2) {
;             PG8_LDB(B0, 0, 0); PG8_LDB(B1, 0, 1); PG8_SCHED; PG8_LDA(At, 0, 0); PG8_STAGE(PG8_SA(1, 1), a1 + hstep, voffA);
;             PG8_WAIT_V(8); PG8_WAIT_L(0); PG8_BAR; PG8_MMA(0, 0, At, B0); PG8_MMA(0, 1, At, B1); PG8_BAR; PG8_SCHED;
;             PG8_LDA(At, 0, 1); PG8_STAGE(PG8_SB(0, 0), b2, voffB); PG8_STAGE(PG8_SB(0, 1), b2 + hstep, voffB); PG8_STAGE(PG8_SA(0, 0), a2, voffA);
;             PG8_WAIT_V(8); PG8_WAIT_L(0); PG8_BAR; if (full) { PG8_MMA(1, 0, At, B0); PG8_MMA(1, 1, At, B1); } PG8_BAR; PG8_SCHED;
.LBB0_1171:
	s_mov_b64 s[38:39], s[80:81]
	s_add_u32 s80, s38, 0x100
	s_addc_u32 s81, s39, 0
	s_add_i32 s2, 0, 0x10000
	s_cmp_eq_u32 s94, s95
	s_cselect_b32 s35, s77, s81
	s_cselect_b32 s34, s76, s80
	v_add_u32_e32 v128, s2, v195
	s_cselect_b32 s29, s79, s51
	s_cselect_b32 s28, s78, s50
	s_add_i32 s4, 0, 0x14000
	ds_read_b128 v[146:149], v128
	ds_read_b128 v[150:153], v128 offset:1024
	ds_read_b128 v[154:157], v128 offset:2048
	ds_read_b128 v[158:161], v128 offset:3072
	v_add_u32_e32 v128, s4, v195
	ds_read_b128 v[130:133], v128
	ds_read_b128 v[134:137], v128 offset:1024
	ds_read_b128 v[138:141], v128 offset:2048
	ds_read_b128 v[142:145], v128 offset:3072
	v_lshl_add_u64 v[196:197], s[38:39], 0, v[218:219]
	s_add_i32 m0, s70, 0xc000
	s_waitcnt lgkmcnt(7)
	ds_read_b128 v[162:165], v242
	ds_read_b128 v[166:169], v242 offset:1024
	ds_read_b128 v[170:173], v242 offset:2048
	ds_read_b128 v[174:177], v242 offset:3072
	ds_read_b128 v[178:181], v242 offset:4096
	ds_read_b128 v[182:185], v242 offset:5120
	ds_read_b128 v[186:189], v242 offset:6144
	ds_read_b128 v[190:193], v242 offset:7168
	global_load_lds_dwordx4 v[196:197], off
	v_lshl_add_u64 v[196:197], s[38:39], 0, v[220:221]
	s_add_i32 m0, s70, 0xe000
	s_nop 0
	global_load_lds_dwordx4 v[196:197], off
	s_waitcnt vmcnt(8)
	s_waitcnt lgkmcnt(0)
	s_barrier
	s_setprio 1
	s_waitcnt lgkmcnt(0)
	v_mfma_f32_16x16x32_bf16 v[124:127], v[146:149], v[162:165], v[124:127]
	v_mfma_f32_16x16x32_bf16 v[120:123], v[154:157], v[162:165], v[120:123]
	v_mfma_f32_16x16x32_bf16 v[116:119], v[146:149], v[170:173], v[116:119]
	v_mfma_f32_16x16x32_bf16 v[112:115], v[154:157], v[170:173], v[112:115]
	v_mfma_f32_16x16x32_bf16 v[104:107], v[146:149], v[178:181], v[104:107]
	v_mfma_f32_16x16x32_bf16 v[96:99], v[154:157], v[178:181], v[96:99]
	v_mfma_f32_16x16x32_bf16 v[88:91], v[146:149], v[186:189], v[88:91]
	v_mfma_f32_16x16x32_bf16 v[80:83], v[154:157], v[186:189], v[80:83]
	v_mfma_f32_16x16x32_bf16 v[124:127], v[150:153], v[166:169], v[124:127]
	v_mfma_f32_16x16x32_bf16 v[120:123], v[158:161], v[166:169], v[120:123]
	v_mfma_f32_16x16x32_bf16 v[116:119], v[150:153], v[174:177], v[116:119]
	v_mfma_f32_16x16x32_bf16 v[112:115], v[158:161], v[174:177], v[112:115]
	v_mfma_f32_16x16x32_bf16 v[104:107], v[150:153], v[182:185], v[104:107]
	v_mfma_f32_16x16x32_bf16 v[96:99], v[158:161], v[182:185], v[96:99]
	v_mfma_f32_16x16x32_bf16 v[88:91], v[150:153], v[190:193], v[88:91]
	v_mfma_f32_16x16x32_bf16 v[80:83], v[158:161], v[190:193], v[80:83]
	s_setprio 0
	s_setprio 1
	v_mfma_f32_16x16x32_bf16 v[108:111], v[130:133], v[162:165], v[108:111]
	v_mfma_f32_16x16x32_bf16 v[100:103], v[138:141], v[162:165], v[100:103]
	v_mfma_f32_16x16x32_bf16 v[92:95], v[130:133], v[170:173], v[92:95]
	v_mfma_f32_16x16x32_bf16 v[84:87], v[138:141], v[170:173], v[84:87]
	v_mfma_f32_16x16x32_bf16 v[76:79], v[130:133], v[178:181], v[76:79]
	v_mfma_f32_16x16x32_bf16 v[72:75], v[138:141], v[178:181], v[72:75]
	v_mfma_f32_16x16x32_bf16 v[68:71], v[130:133], v[186:189], v[68:71]
	v_mfma_f32_16x16x32_bf16 v[56:59], v[138:141], v[186:189], v[56:59]
	v_mfma_f32_16x16x32_bf16 v[108:111], v[134:137], v[166:169], v[108:111]
	v_mfma_f32_16x16x32_bf16 v[100:103], v[142:145], v[166:169], v[100:103]
	v_mfma_f32_16x16x32_bf16 v[92:95], v[134:137], v[174:177], v[92:95]
	v_mfma_f32_16x16x32_bf16 v[84:87], v[142:145], v[174:177], v[84:87]
	v_mfma_f32_16x16x32_bf16 v[76:79], v[134:137], v[182:185], v[76:79]
	v_mfma_f32_16x16x32_bf16 v[72:75], v[142:145], v[182:185], v[72:75]
	v_mfma_f32_16x16x32_bf16 v[68:71], v[134:137], v[190:193], v[68:71]
	v_mfma_f32_16x16x32_bf16 v[56:59], v[142:145], v[190:193], v[56:59]
	s_setprio 0
	s_barrier
	s_add_i32 s2, s2, s65
	v_lshl_add_u64 v[222:223], s[28:29], 0, v[208:209]
	s_mov_b32 m0, s2
	ds_read_b128 v[186:189], v242 offset:16384
	ds_read_b128 v[190:193], v242 offset:17408
	ds_read_b128 v[178:181], v242 offset:18432
	ds_read_b128 v[182:185], v242 offset:19456
	ds_read_b128 v[170:173], v242 offset:20480
	ds_read_b128 v[174:177], v242 offset:21504
	ds_read_b128 v[162:165], v242 offset:22528
	ds_read_b128 v[166:169], v242 offset:23552
	global_load_lds_dwordx4 v[222:223], off
	s_add_i32 m0, s2, 0x2000
	s_add_u32 s2, s28, 0xb0000
	v_lshl_add_u64 v[224:225], s[28:29], 0, v[212:213]
	s_addc_u32 s3, s29, 0
	s_add_i32 s4, s4, s65
	global_load_lds_dwordx4 v[224:225], off
	v_lshl_add_u64 v[196:197], s[2:3], 0, v[208:209]
	s_mov_b32 m0, s4
	v_lshl_add_u64 v[226:227], s[34:35], 0, v[206:207]
	global_load_lds_dwordx4 v[196:197], off
	v_lshl_add_u64 v[196:197], s[2:3], 0, v[212:213]
	s_add_i32 m0, s4, 0x2000
	v_lshl_add_u64 v[228:229], s[34:35], 0, v[210:211]
	global_load_lds_dwordx4 v[196:197], off
	s_mov_b32 m0, s70
	v_cndmask_b32_e64 v128, 0, 1, s[48:49]
	global_load_lds_dwordx4 v[226:227], off
	s_mov_b32 m0, s71
	v_cmp_ne_u32_e64 s[38:39], 1, v128
	global_load_lds_dwordx4 v[228:229], off
	s_waitcnt vmcnt(8)
	s_waitcnt lgkmcnt(0)
	s_andn2_b64 vcc, exec, s[48:49]
	s_barrier
	s_cbranch_vccnz .LBB0_1173
; #define PG8_STAGE(bufoff, gbase, voff) do { _Pragma("unroll") for (int _i = 0; _i < 2; ++_i) \
;         __builtin_amdgcn_global_load_lds((const unsigned*)((const char*)(gbase) + (voff)[_i]), (PG8_LAS unsigned*)(lds + (bufoff) + ldsw + _i * 8192), 16, 0, 0); } while (0)
; #define PG8_LDA(dst, b, h) do { _Pragma("unroll") for (int m = 0; m < 4; ++m) _Pragma("unroll") for (int k = 0; k < 2; ++k) dst[m][k] = *(const PG8_LAS bf16x8*)(lds + PG8_SA(b, h) + aoff + m * 2048 + k * 1024); } while (0)
; #define PG8_LDB(dst, b, h) do { _Pragma("unroll") for (int n = 0; n < 2; ++n) _Pragma("unroll") for (int k = 0; k < 2; ++k) dst[n][k] = *(const PG8_LAS bf16x8*)(lds + PG8_SB(b, h) + boff + n * 2048 + k * 1024); } while (0)
; #define PG8_MMA(ai, bj, At, Bt) do { __builtin_amdgcn_s_setprio(1); _Pragma("unroll") for (int m = 0; m < 4; ++m) _Pragma("unroll") for (int n = 0; n < 2; ++n) _Pragma("unroll") for (int k = 0; k < 2; ++k) \
;         acc[ai][bj][m][n] = __builtin_amdgcn_mfma_f32_16x16x32_bf16(Bt[n][k], At[m][k], acc[ai][bj][m][n], 0, 0, 0); __builtin_amdgcn_s_setprio(0); } while (0)
; #define PG8_WAIT_V(n) asm volatile("s_waitcnt vmcnt(" #n ")" ::: "memory")
; #define PG8_WAIT_L(n) asm volatile("s_waitcnt lgkmcnt(" #n ")" ::: "memory")
; #define PG8_BAR __builtin_amdgcn_s_barrier()
; #define PG8_SCHED __builtin_amdgcn_sched_barrier(0)
; template <class Epi, class Sched, bool ALIGN_EPI = false, bool SP2 = false>
; __device__ __forceinline__ void gemm_phase(PG8_LAS unsigned char* lds, const Gemm g, const Sched& S, const Epi& E) {
;     ...
;             PG8_WAIT_V(8); PG8_WAIT_L(0); PG8_BAR; if (full) { PG8_MMA(1, 0, At, B0); PG8_MMA(1, 1, At, B1); } PG8_BAR; PG8_SCHED;
;             PG8_LDB(B0, 1, 0); PG8_LDB(B1, 1, 1); PG8_SCHED; PG8_LDA(At, 1, 0); PG8_STAGE(PG8_SA(0, 1), a2 + hstep, voffA);
;             PG8_WAIT_V(8); PG8_WAIT_L(0); PG8_BAR; PG8_MMA(0, 0, At, B0); PG8_MMA(0, 1, At, B1); PG8_BAR; PG8_SCHED;
	s_setprio 1
	s_waitcnt lgkmcnt(0)
	v_mfma_f32_16x16x32_bf16 v[64:67], v[146:149], v[186:189], v[64:67]
	v_mfma_f32_16x16x32_bf16 v[60:63], v[154:157], v[186:189], v[60:63]
	v_mfma_f32_16x16x32_bf16 v[44:47], v[146:149], v[178:181], v[44:47]
	v_mfma_f32_16x16x32_bf16 v[40:43], v[154:157], v[178:181], v[40:43]
	v_mfma_f32_16x16x32_bf16 v[28:31], v[146:149], v[170:173], v[28:31]
	v_mfma_f32_16x16x32_bf16 v[24:27], v[154:157], v[170:173], v[24:27]
	v_mfma_f32_16x16x32_bf16 v[12:15], v[146:149], v[162:165], v[12:15]
	v_mfma_f32_16x16x32_bf16 v[8:11], v[154:157], v[162:165], v[8:11]
	v_mfma_f32_16x16x32_bf16 v[64:67], v[150:153], v[190:193], v[64:67]
	v_mfma_f32_16x16x32_bf16 v[60:63], v[158:161], v[190:193], v[60:63]
	v_mfma_f32_16x16x32_bf16 v[44:47], v[150:153], v[182:185], v[44:47]
	v_mfma_f32_16x16x32_bf16 v[40:43], v[158:161], v[182:185], v[40:43]
	v_mfma_f32_16x16x32_bf16 v[28:31], v[150:153], v[174:177], v[28:31]
	v_mfma_f32_16x16x32_bf16 v[24:27], v[158:161], v[174:177], v[24:27]
	v_mfma_f32_16x16x32_bf16 v[12:15], v[150:153], v[166:169], v[12:15]
	v_mfma_f32_16x16x32_bf16 v[8:11], v[158:161], v[166:169], v[8:11]
	s_setprio 0
	s_setprio 1
	v_mfma_f32_16x16x32_bf16 v[52:55], v[130:133], v[186:189], v[52:55]
	v_mfma_f32_16x16x32_bf16 v[48:51], v[138:141], v[186:189], v[48:51]
	v_mfma_f32_16x16x32_bf16 v[36:39], v[130:133], v[178:181], v[36:39]
	v_mfma_f32_16x16x32_bf16 v[32:35], v[138:141], v[178:181], v[32:35]
	v_mfma_f32_16x16x32_bf16 v[20:23], v[130:133], v[170:173], v[20:23]
	v_mfma_f32_16x16x32_bf16 v[16:19], v[138:141], v[170:173], v[16:19]
	v_mfma_f32_16x16x32_bf16 v[4:7], v[130:133], v[162:165], v[4:7]
	v_mfma_f32_16x16x32_bf16 v[0:3], v[138:141], v[162:165], v[0:3]
	v_mfma_f32_16x16x32_bf16 v[52:55], v[134:137], v[190:193], v[52:55]
	v_mfma_f32_16x16x32_bf16 v[48:51], v[142:145], v[190:193], v[48:51]
	v_mfma_f32_16x16x32_bf16 v[36:39], v[134:137], v[182:185], v[36:39]
	v_mfma_f32_16x16x32_bf16 v[32:35], v[142:145], v[182:185], v[32:35]
	v_mfma_f32_16x16x32_bf16 v[20:23], v[134:137], v[174:177], v[20:23]
	v_mfma_f32_16x16x32_bf16 v[16:19], v[142:145], v[174:177], v[16:19]
	v_mfma_f32_16x16x32_bf16 v[4:7], v[134:137], v[166:169], v[4:7]
	v_mfma_f32_16x16x32_bf16 v[0:3], v[142:145], v[166:169], v[0:3]
	s_setprio 0
.LBB0_1173:
	s_barrier
	s_add_i32 s4, 0, 0x18000
	v_add_u32_e32 v128, s4, v195
	s_add_i32 s5, 0, 0x1c000
	ds_read_b128 v[146:149], v128
	ds_read_b128 v[150:153], v128 offset:1024
	ds_read_b128 v[154:157], v128 offset:2048
	ds_read_b128 v[158:161], v128 offset:3072
	v_add_u32_e32 v128, s5, v195
	ds_read_b128 v[130:133], v128
	ds_read_b128 v[134:137], v128 offset:1024
	ds_read_b128 v[138:141], v128 offset:2048
	ds_read_b128 v[142:145], v128 offset:3072
	s_add_u32 s2, s34, 0xb0000
	s_addc_u32 s3, s35, 0
	s_mov_b32 m0, s73
	v_lshl_add_u64 v[196:197], s[2:3], 0, v[206:207]
	s_waitcnt lgkmcnt(7)
	ds_read_b128 v[162:165], v242 offset:32768
	ds_read_b128 v[166:169], v242 offset:33792
	ds_read_b128 v[170:173], v242 offset:34816
	ds_read_b128 v[174:177], v242 offset:35840
	ds_read_b128 v[178:181], v242 offset:36864
	ds_read_b128 v[182:185], v242 offset:37888
	ds_read_b128 v[186:189], v242 offset:38912
	ds_read_b128 v[190:193], v242 offset:39936
	global_load_lds_dwordx4 v[196:197], off
	v_lshl_add_u64 v[196:197], s[2:3], 0, v[210:211]
	s_mov_b32 m0, s82
	s_nop 0
	global_load_lds_dwordx4 v[196:197], off
	s_waitcnt vmcnt(8)
	s_waitcnt lgkmcnt(0)
	s_barrier
	s_setprio 1
	s_waitcnt lgkmcnt(0)
	v_mfma_f32_16x16x32_bf16 v[124:127], v[146:149], v[162:165], v[124:127]
	v_mfma_f32_16x16x32_bf16 v[120:123], v[154:157], v[162:165], v[120:123]
	v_mfma_f32_16x16x32_bf16 v[116:119], v[146:149], v[170:173], v[116:119]
	v_mfma_f32_16x16x32_bf16 v[112:115], v[154:157], v[170:173], v[112:115]
	v_mfma_f32_16x16x32_bf16 v[104:107], v[146:149], v[178:181], v[104:107]
	v_mfma_f32_16x16x32_bf16 v[96:99], v[154:157], v[178:181], v[96:99]
	v_mfma_f32_16x16x32_bf16 v[88:91], v[146:149], v[186:189], v[88:91]
	v_mfma_f32_16x16x32_bf16 v[80:83], v[154:157], v[186:189], v[80:83]
	v_mfma_f32_16x16x32_bf16 v[124:127], v[150:153], v[166:169], v[124:127]
	v_mfma_f32_16x16x32_bf16 v[120:123], v[158:161], v[166:169], v[120:123]
	v_mfma_f32_16x16x32_bf16 v[116:119], v[150:153], v[174:177], v[116:119]
	v_mfma_f32_16x16x32_bf16 v[112:115], v[158:161], v[174:177], v[112:115]
	v_mfma_f32_16x16x32_bf16 v[104:107], v[150:153], v[182:185], v[104:107]
	v_mfma_f32_16x16x32_bf16 v[96:99], v[158:161], v[182:185], v[96:99]
	v_mfma_f32_16x16x32_bf16 v[88:91], v[150:153], v[190:193], v[88:91]
	v_mfma_f32_16x16x32_bf16 v[80:83], v[158:161], v[190:193], v[80:83]
	s_setprio 0
	s_setprio 1
	v_mfma_f32_16x16x32_bf16 v[108:111], v[130:133], v[162:165], v[108:111]
	v_mfma_f32_16x16x32_bf16 v[100:103], v[138:141], v[162:165], v[100:103]
	v_mfma_f32_16x16x32_bf16 v[92:95], v[130:133], v[170:173], v[92:95]
	v_mfma_f32_16x16x32_bf16 v[84:87], v[138:141], v[170:173], v[84:87]
	v_mfma_f32_16x16x32_bf16 v[76:79], v[130:133], v[178:181], v[76:79]
	v_mfma_f32_16x16x32_bf16 v[72:75], v[138:141], v[178:181], v[72:75]
	v_mfma_f32_16x16x32_bf16 v[68:71], v[130:133], v[186:189], v[68:71]
	v_mfma_f32_16x16x32_bf16 v[56:59], v[138:141], v[186:189], v[56:59]
	v_mfma_f32_16x16x32_bf16 v[108:111], v[134:137], v[166:169], v[108:111]
	v_mfma_f32_16x16x32_bf16 v[100:103], v[142:145], v[166:169], v[100:103]
	v_mfma_f32_16x16x32_bf16 v[92:95], v[134:137], v[174:177], v[92:95]
	v_mfma_f32_16x16x32_bf16 v[84:87], v[142:145], v[174:177], v[84:87]
	v_mfma_f32_16x16x32_bf16 v[76:79], v[134:137], v[182:185], v[76:79]
	v_mfma_f32_16x16x32_bf16 v[72:75], v[142:145], v[182:185], v[72:75]
	v_mfma_f32_16x16x32_bf16 v[68:71], v[134:137], v[190:193], v[68:71]
	v_mfma_f32_16x16x32_bf16 v[56:59], v[142:145], v[190:193], v[56:59]
	s_setprio 0
	s_barrier
; #define PG8_STAGE(bufoff, gbase, voff) do { _Pragma("unroll") for (int _i = 0; _i < 2; ++_i) \
;         __builtin_amdgcn_global_load_lds((const unsigned*)((const char*)(gbase) + (voff)[_i]), (PG8_LAS unsigned*)(lds + (bufoff) + ldsw + _i * 8192), 16, 0, 0); } while (0)
; #define PG8_LDA(dst, b, h) do { _Pragma("unroll") for (int m = 0; m < 4; ++m) _Pragma("unroll") for (int k = 0; k < 2; ++k) dst[m][k] = *(const PG8_LAS bf16x8*)(lds + PG8_SA(b, h) + aoff + m * 2048 + k * 1024); } while (0)
; #define PG8_LDB(dst, b, h) do { _Pragma("unroll") for (int n = 0; n < 2; ++n) _Pragma("unroll") for (int k = 0; k < 2; ++k) dst[n][k] = *(const PG8_LAS bf16x8*)(lds + PG8_SB(b, h) + boff + n * 2048 + k * 1024); } while (0)
; #define PG8_WAIT_V(n) asm volatile("s_waitcnt vmcnt(" #n ")" ::: "memory")
; #define PG8_WAIT_L(n) asm volatile("s_waitcnt lgkmcnt(" #n ")" ::: "memory")
; #define PG8_BAR __builtin_amdgcn_s_barrier()
; #define PG8_SCHED __builtin_amdgcn_sched_barrier(0)
; template <class Epi, class Sched, bool ALIGN_EPI = false, bool SP2 = false>
; __device__ __forceinline__ void gemm_phase(PG8_LAS unsigned char* lds, const Gemm g, const Sched& S, const Epi& E) {
;     ...
;             const char* a3 = a2 + kstep; const char* b3 = b2 + kstep;
;             if (last && has_next) S.a_ready(nxt);
;             if constexpr (SP2) {
;             PG8_LDB(B0, 0, 0); PG8_LDB(B1, 0, 1); PG8_SCHED; PG8_LDA(At, 0, 0); PG8_STAGE(PG8_SA(1, 1), a1 + hstep, voffA);
;             PG8_WAIT_V(8); PG8_WAIT_L(0); PG8_BAR; PG8_MMA(0, 0, At, B0); PG8_MMA(0, 1, At, B1); PG8_BAR; PG8_SCHED;
;             PG8_LDA(At, 0, 1); PG8_STAGE(PG8_SB(0, 0), b2, voffB); PG8_STAGE(PG8_SB(0, 1), b2 + hstep, voffB); PG8_STAGE(PG8_SA(0, 0), a2, voffA);
;             PG8_WAIT_V(8); PG8_WAIT_L(0); PG8_BAR; if (full) { PG8_MMA(1, 0, At, B0); PG8_MMA(1, 1, At, B1); } PG8_BAR; PG8_SCHED;
;             PG8_LDB(B0, 1, 0); PG8_LDB(B1, 1, 1); PG8_SCHED; PG8_LDA(At, 1, 0); PG8_STAGE(PG8_SA(0, 1), a2 + hstep, voffA);
;             PG8_WAIT_V(8); PG8_WAIT_L(0); PG8_BAR; PG8_MMA(0, 0, At, B0); PG8_MMA(0, 1, At, B1); PG8_BAR; PG8_SCHED;
;             PG8_LDA(At, 1, 1); PG8_STAGE(PG8_SB(1, 0), b3, voffB); PG8_STAGE(PG8_SB(1, 1), b3 + hstep, voffB); PG8_STAGE(PG8_SA(1, 0), a3, voffA);
;             PG8_WAIT_V(8); PG8_WAIT_L(0); PG8_BAR; if (full) { PG8_MMA(1, 0, At, B0); PG8_MMA(1, 1, At, B1); } PG8_BAR; PG8_SCHED;
	s_add_i32 s2, s4, s65
	v_lshl_add_u64 v[196:197], v[222:223], 0, s[26:27]
	s_mov_b32 m0, s2
	ds_read_b128 v[186:189], v242 offset:49152
	ds_read_b128 v[190:193], v242 offset:50176
	ds_read_b128 v[178:181], v242 offset:51200
	ds_read_b128 v[182:185], v242 offset:52224
	ds_read_b128 v[170:173], v242 offset:53248
	ds_read_b128 v[174:177], v242 offset:54272
	ds_read_b128 v[162:165], v242 offset:55296
	ds_read_b128 v[166:169], v242 offset:56320
	global_load_lds_dwordx4 v[196:197], off
	s_add_i32 m0, s2, 0x2000
	s_add_u32 s2, s28, 0xb0080
	v_lshl_add_u64 v[196:197], v[224:225], 0, s[26:27]
	s_addc_u32 s3, s29, 0
	s_add_i32 s4, s5, s65
	global_load_lds_dwordx4 v[196:197], off
	v_lshl_add_u64 v[196:197], s[2:3], 0, v[208:209]
	s_mov_b32 m0, s4
	s_and_b64 vcc, exec, s[38:39]
	global_load_lds_dwordx4 v[196:197], off
	v_lshl_add_u64 v[196:197], s[2:3], 0, v[212:213]
	s_add_i32 m0, s4, 0x2000
	s_nop 0
	global_load_lds_dwordx4 v[196:197], off
	v_lshl_add_u64 v[196:197], v[226:227], 0, s[26:27]
	s_mov_b32 m0, s83
	s_nop 0
	global_load_lds_dwordx4 v[196:197], off
	v_lshl_add_u64 v[196:197], v[228:229], 0, s[26:27]
	s_mov_b32 m0, s84
	s_nop 0
	global_load_lds_dwordx4 v[196:197], off
	s_waitcnt vmcnt(8)
	s_waitcnt lgkmcnt(0)
	s_barrier
	s_cbranch_vccnz .LBB0_1170
	s_setprio 1
	s_waitcnt lgkmcnt(0)
	v_mfma_f32_16x16x32_bf16 v[64:67], v[146:149], v[186:189], v[64:67]
	v_mfma_f32_16x16x32_bf16 v[60:63], v[154:157], v[186:189], v[60:63]
	v_mfma_f32_16x16x32_bf16 v[44:47], v[146:149], v[178:181], v[44:47]
	v_mfma_f32_16x16x32_bf16 v[40:43], v[154:157], v[178:181], v[40:43]
	v_mfma_f32_16x16x32_bf16 v[28:31], v[146:149], v[170:173], v[28:31]
	v_mfma_f32_16x16x32_bf16 v[24:27], v[154:157], v[170:173], v[24:27]
	v_mfma_f32_16x16x32_bf16 v[12:15], v[146:149], v[162:165], v[12:15]
	v_mfma_f32_16x16x32_bf16 v[8:11], v[154:157], v[162:165], v[8:11]
	v_mfma_f32_16x16x32_bf16 v[64:67], v[150:153], v[190:193], v[64:67]
	v_mfma_f32_16x16x32_bf16 v[60:63], v[158:161], v[190:193], v[60:63]
	v_mfma_f32_16x16x32_bf16 v[44:47], v[150:153], v[182:185], v[44:47]
	v_mfma_f32_16x16x32_bf16 v[40:43], v[158:161], v[182:185], v[40:43]
	v_mfma_f32_16x16x32_bf16 v[28:31], v[150:153], v[174:177], v[28:31]
	v_mfma_f32_16x16x32_bf16 v[24:27], v[158:161], v[174:177], v[24:27]
	v_mfma_f32_16x16x32_bf16 v[12:15], v[150:153], v[166:169], v[12:15]
	v_mfma_f32_16x16x32_bf16 v[8:11], v[158:161], v[166:169], v[8:11]
	s_setprio 0
	s_setprio 1
	v_mfma_f32_16x16x32_bf16 v[52:55], v[130:133], v[186:189], v[52:55]
	v_mfma_f32_16x16x32_bf16 v[48:51], v[138:141], v[186:189], v[48:51]
	v_mfma_f32_16x16x32_bf16 v[36:39], v[130:133], v[178:181], v[36:39]
	v_mfma_f32_16x16x32_bf16 v[32:35], v[138:141], v[178:181], v[32:35]
	v_mfma_f32_16x16x32_bf16 v[20:23], v[130:133], v[170:173], v[20:23]
	v_mfma_f32_16x16x32_bf16 v[16:19], v[138:141], v[170:173], v[16:19]
	v_mfma_f32_16x16x32_bf16 v[4:7], v[130:133], v[162:165], v[4:7]
	v_mfma_f32_16x16x32_bf16 v[0:3], v[138:141], v[162:165], v[0:3]
	v_mfma_f32_16x16x32_bf16 v[52:55], v[134:137], v[190:193], v[52:55]
	v_mfma_f32_16x16x32_bf16 v[48:51], v[142:145], v[190:193], v[48:51]
	v_mfma_f32_16x16x32_bf16 v[36:39], v[134:137], v[182:185], v[36:39]
	v_mfma_f32_16x16x32_bf16 v[32:35], v[142:145], v[182:185], v[32:35]
	v_mfma_f32_16x16x32_bf16 v[20:23], v[134:137], v[174:177], v[20:23]
	v_mfma_f32_16x16x32_bf16 v[16:19], v[142:145], v[174:177], v[16:19]
	v_mfma_f32_16x16x32_bf16 v[4:7], v[134:137], v[166:169], v[4:7]
	v_mfma_f32_16x16x32_bf16 v[0:3], v[142:145], v[166:169], v[0:3]
	s_setprio 0
	s_branch .LBB0_1170
